# v83 + GEMM K-loops: loop-invariant LDS-offset scalars folded into literals at their uses (8 fewer SALU per K-iteration per wave in the read sections); M0 values and ds_read addresses verified symbolic
# speedup vs baseline: 1.0095x; 1.0071x over previous
; #define PG8_STAGE(bufoff, gbase, voff) do { _Pragma("unroll") for (int _i = 0; _i < 2; ++_i) \
;         __builtin_amdgcn_global_load_lds((const unsigned*)((const char*)(gbase) + (voff)[_i]), (LAS unsigned*)(lds + (bufoff) + ldsw + _i * 8192), 16, 0, 0); } while (0)
; #define PG8_LDA(dst, b, h) do { _Pragma("unroll") for (int m = 0; m < 4; ++m) _Pragma("unroll") for (int k = 0; k < 2; ++k) dst[m][k] = *(const LAS bf16x8*)(lds + PG8_SA(b, h) + aoff + m * 2048 + k * 1024); } while (0)
; #define PG8_LDB(dst, b, h) do { _Pragma("unroll") for (int n = 0; n < 2; ++n) _Pragma("unroll") for (int k = 0; k < 2; ++k) dst[n][k] = *(const LAS bf16x8*)(lds + PG8_SB(b, h) + boff + n * 2048 + k * 1024); } while (0)
; #define PG8_MMA(ai, bj, At, Bt) do { __builtin_amdgcn_s_setprio(1); _Pragma("unroll") for (int m = 0; m < 4; ++m) _Pragma("unroll") for (int n = 0; n < 2; ++n) _Pragma("unroll") for (int k = 0; k < 2; ++k) \
;         acc[ai][bj][m][n] = __builtin_amdgcn_mfma_f32_16x16x32_bf16(Bt[n][k], At[m][k], acc[ai][bj][m][n], 0, 0, 0); __builtin_amdgcn_s_setprio(0); } while (0)
; #define PG8_WAIT_V(n) asm volatile("s_waitcnt vmcnt(" #n ")" ::: "memory")
; #define PG8_WAIT_L(n) asm volatile("s_waitcnt lgkmcnt(" #n ")" ::: "memory")
; #define PG8_BAR __builtin_amdgcn_s_barrier()
; #define PG8_SCHED __builtin_amdgcn_sched_barrier(0)
; template <class Epi, bool ALIGN_EPI = PG8_ALIGN, bool SP2 = PG8_SP2>
; __device__ __forceinline__ void gemm_phase(LAS uchar* lds, const Gemm g, const StaticOrder& S, const Epi& E) {
;     ...
;             const bool last = (t == nt - 2);
;             const char* a1 = cA + (size_t)(t + 1) * kstep;
;             const char* a2 = last ? nA : cA + (size_t)(t + 2) * kstep; const char* b2 = last ? nB : cB + (size_t)(t + 2) * kstep;
;             const char* a3 = a2 + kstep; const char* b3 = b2 + kstep;
;             if constexpr (SP2) {
;             PG8_LDB(B0, 0, 0); PG8_LDB(B1, 0, 1); PG8_SCHED; PG8_LDA(At, 0, 0); PG8_STAGE(PG8_SA(1, 1), a1 + hstepA, voffA);
;             PG8_WAIT_V(8); PG8_WAIT_L(0); PG8_BAR; PG8_MMA(0, 0, At, B0); PG8_MMA(0, 1, At, B1); PG8_BAR; PG8_SCHED;
.Lxt_skip_344:
	s_add_u32 s38, s4, 0x100
	s_addc_u32 s39, s5, 0
	s_mov_b32 s40, -2
	s_add_u32 s18, s16, 0x100
	s_addc_u32 s19, s17, 0
	s_cmp_eq_u32 s40, 12
	s_cselect_b32 s21, s7, s19
	s_cselect_b32 s20, s6, s18
	v_add_u32_e32 v168, 0x10000, v139
	s_cselect_b32 s5, s15, s39
	s_cselect_b32 s4, s14, s38
	ds_read_b128 v[164:167], v168
	ds_read_b128 v[172:175], v168 offset:1024
	ds_read_b128 v[176:179], v168 offset:2048
	ds_read_b128 v[184:187], v168 offset:3072
	v_add_u32_e32 v168, 0x14000, v139
	ds_read_b128 v[188:191], v168
	ds_read_b128 v[192:195], v168 offset:1024
	ds_read_b128 v[196:199], v168 offset:2048
	ds_read_b128 v[200:203], v168 offset:3072
	v_lshl_add_u64 v[168:169], s[16:17], 0, v[160:161]
	s_add_i32 m0, s25, 0xc000
	ds_read_b128 v[204:207], v171
	ds_read_b128 v[208:211], v171 offset:1024
	ds_read_b128 v[212:215], v171 offset:2048
	ds_read_b128 v[216:219], v171 offset:3072
	ds_read_b128 v[220:223], v171 offset:4096
	ds_read_b128 v[224:227], v171 offset:5120
	ds_read_b128 v[228:231], v171 offset:6144
	ds_read_b128 v[232:235], v171 offset:7168
	global_load_lds_dwordx4 v[168:169], off
	s_add_i32 m0, s25, 0xe000
	v_lshl_add_u64 v[168:169], s[16:17], 0, v[162:163]
	global_load_lds_dwordx4 v[168:169], off
	s_cmp_eq_u32 s97, 1
	s_cbranch_scc0 .Lrw_std_345_0_pl
	s_waitcnt vmcnt(24)
	s_branch .Lrw_done_345_0_pl

; #define PG8_STAGE(bufoff, gbase, voff) do { _Pragma("unroll") for (int _i = 0; _i < 2; ++_i) \
;         __builtin_amdgcn_global_load_lds((const unsigned*)((const char*)(gbase) + (voff)[_i]), (LAS unsigned*)(lds + (bufoff) + ldsw + _i * 8192), 16, 0, 0); } while (0)
; #define PG8_LDA(dst, b, h) do { _Pragma("unroll") for (int m = 0; m < 4; ++m) _Pragma("unroll") for (int k = 0; k < 2; ++k) dst[m][k] = *(const LAS bf16x8*)(lds + PG8_SA(b, h) + aoff + m * 2048 + k * 1024); } while (0)
; #define PG8_MMA(ai, bj, At, Bt) do { __builtin_amdgcn_s_setprio(1); _Pragma("unroll") for (int m = 0; m < 4; ++m) _Pragma("unroll") for (int n = 0; n < 2; ++n) _Pragma("unroll") for (int k = 0; k < 2; ++k) \
;         acc[ai][bj][m][n] = __builtin_amdgcn_mfma_f32_16x16x32_bf16(Bt[n][k], At[m][k], acc[ai][bj][m][n], 0, 0, 0); __builtin_amdgcn_s_setprio(0); } while (0)
; #define PG8_WAIT_V(n) asm volatile("s_waitcnt vmcnt(" #n ")" ::: "memory")
; #define PG8_WAIT_L(n) asm volatile("s_waitcnt lgkmcnt(" #n ")" ::: "memory")
; #define PG8_BAR __builtin_amdgcn_s_barrier()
; #define PG8_SCHED __builtin_amdgcn_sched_barrier(0)
; template <class Epi, bool ALIGN_EPI = PG8_ALIGN, bool SP2 = PG8_SP2>
; __device__ __forceinline__ void gemm_phase(LAS uchar* lds, const Gemm g, const StaticOrder& S, const Epi& E) {
;     ...
;             PG8_WAIT_V(8); PG8_WAIT_L(0); PG8_BAR; PG8_MMA(0, 0, At, B0); PG8_MMA(0, 1, At, B1); PG8_BAR; PG8_SCHED;
;             PG8_LDA(At, 0, 1); PG8_STAGE(PG8_SB(0, 0), b2, voffB); PG8_STAGE(PG8_SB(0, 1), b2 + hstepB, voffB); PG8_STAGE(PG8_SA(0, 0), a2, voffA);
;             PG8_WAIT_V(8); PG8_WAIT_L(0); PG8_BAR; PG8_MMA(1, 0, At, B0); PG8_MMA(1, 1, At, B1); PG8_BAR; PG8_SCHED;
.Lrw_done_345_0_pl:
	s_waitcnt lgkmcnt(0)
	s_setprio 1
	s_barrier
	v_mfma_f32_16x16x32_bf16 v[126:129], v[164:167], v[204:207], 0
	v_mfma_f32_16x16x32_bf16 v[122:125], v[176:179], v[204:207], 0
	v_mfma_f32_16x16x32_bf16 v[118:121], v[164:167], v[212:215], 0
	v_mfma_f32_16x16x32_bf16 v[110:113], v[176:179], v[212:215], 0
	v_mfma_f32_16x16x32_bf16 v[102:105], v[164:167], v[220:223], 0
	v_mfma_f32_16x16x32_bf16 v[94:97], v[176:179], v[220:223], 0
	v_mfma_f32_16x16x32_bf16 v[86:89], v[164:167], v[228:231], 0
	v_mfma_f32_16x16x32_bf16 v[78:81], v[176:179], v[228:231], 0
	v_mfma_f32_16x16x32_bf16 v[126:129], v[172:175], v[208:211], v[126:129]
	v_mfma_f32_16x16x32_bf16 v[122:125], v[184:187], v[208:211], v[122:125]
	v_mfma_f32_16x16x32_bf16 v[118:121], v[172:175], v[216:219], v[118:121]
	v_mfma_f32_16x16x32_bf16 v[110:113], v[184:187], v[216:219], v[110:113]
	v_mfma_f32_16x16x32_bf16 v[102:105], v[172:175], v[224:227], v[102:105]
	v_mfma_f32_16x16x32_bf16 v[94:97], v[184:187], v[224:227], v[94:97]
	v_mfma_f32_16x16x32_bf16 v[86:89], v[172:175], v[232:235], v[86:89]
	v_mfma_f32_16x16x32_bf16 v[78:81], v[184:187], v[232:235], v[78:81]
	v_mfma_f32_16x16x32_bf16 v[114:117], v[188:191], v[204:207], 0
	v_mfma_f32_16x16x32_bf16 v[106:109], v[196:199], v[204:207], 0
	v_mfma_f32_16x16x32_bf16 v[98:101], v[188:191], v[212:215], 0
	v_mfma_f32_16x16x32_bf16 v[90:93], v[196:199], v[212:215], 0
	v_mfma_f32_16x16x32_bf16 v[82:85], v[188:191], v[220:223], 0
	v_mfma_f32_16x16x32_bf16 v[74:77], v[196:199], v[220:223], 0
	v_mfma_f32_16x16x32_bf16 v[70:73], v[188:191], v[228:231], 0
	v_mfma_f32_16x16x32_bf16 v[66:69], v[196:199], v[228:231], 0
	v_mfma_f32_16x16x32_bf16 v[114:117], v[192:195], v[208:211], v[114:117]
	v_mfma_f32_16x16x32_bf16 v[106:109], v[200:203], v[208:211], v[106:109]
	v_mfma_f32_16x16x32_bf16 v[98:101], v[192:195], v[216:219], v[98:101]
	v_mfma_f32_16x16x32_bf16 v[90:93], v[200:203], v[216:219], v[90:93]
	v_mfma_f32_16x16x32_bf16 v[82:85], v[192:195], v[224:227], v[82:85]
	v_mfma_f32_16x16x32_bf16 v[74:77], v[200:203], v[224:227], v[74:77]
	v_mfma_f32_16x16x32_bf16 v[70:73], v[192:195], v[232:235], v[70:73]
	v_mfma_f32_16x16x32_bf16 v[66:69], v[200:203], v[232:235], v[66:69]
	s_barrier
	s_setprio 0
	v_lshl_add_u64 v[168:169], s[4:5], 0, v[134:135]
	s_add_i32 m0, s23, 0x10000
	ds_read_b128 v[204:207], v171 offset:16384
	ds_read_b128 v[208:211], v171 offset:17408
	ds_read_b128 v[212:215], v171 offset:18432
	ds_read_b128 v[216:219], v171 offset:19456
	ds_read_b128 v[220:223], v171 offset:20480
	ds_read_b128 v[224:227], v171 offset:21504
	ds_read_b128 v[228:231], v171 offset:22528
	ds_read_b128 v[232:235], v171 offset:23552
	global_load_lds_dwordx4 v[168:169], off
	s_add_i32 m0, s23, 0x12000
	s_add_u32 s16, s4, 0x44000
	v_lshl_add_u64 v[180:181], s[4:5], 0, v[130:131]
	s_addc_u32 s17, s5, 0
	global_load_lds_dwordx4 v[180:181], off
	s_add_i32 m0, s23, 0x14000
	v_lshl_add_u64 v[236:237], s[16:17], 0, v[134:135]
	global_load_lds_dwordx4 v[236:237], off
	s_add_i32 m0, s23, 0x16000
	v_lshl_add_u64 v[236:237], s[16:17], 0, v[130:131]
	global_load_lds_dwordx4 v[236:237], off
	s_mov_b32 m0, s25
	v_lshl_add_u64 v[236:237], s[20:21], 0, v[156:157]
	global_load_lds_dwordx4 v[236:237], off
	s_mov_b32 m0, s26
	v_lshl_add_u64 v[238:239], s[20:21], 0, v[132:133]
	global_load_lds_dwordx4 v[238:239], off
	s_cmp_eq_u32 s97, 1
	s_cbranch_scc0 .Lrw_std_345_1_pl
	s_waitcnt vmcnt(24)
	s_branch .Lrw_done_345_1_pl

; #define PG8_STAGE(bufoff, gbase, voff) do { _Pragma("unroll") for (int _i = 0; _i < 2; ++_i) \
;         __builtin_amdgcn_global_load_lds((const unsigned*)((const char*)(gbase) + (voff)[_i]), (LAS unsigned*)(lds + (bufoff) + ldsw + _i * 8192), 16, 0, 0); } while (0)
; #define PG8_LDA(dst, b, h) do { _Pragma("unroll") for (int m = 0; m < 4; ++m) _Pragma("unroll") for (int k = 0; k < 2; ++k) dst[m][k] = *(const LAS bf16x8*)(lds + PG8_SA(b, h) + aoff + m * 2048 + k * 1024); } while (0)
; #define PG8_LDB(dst, b, h) do { _Pragma("unroll") for (int n = 0; n < 2; ++n) _Pragma("unroll") for (int k = 0; k < 2; ++k) dst[n][k] = *(const LAS bf16x8*)(lds + PG8_SB(b, h) + boff + n * 2048 + k * 1024); } while (0)
; #define PG8_MMA(ai, bj, At, Bt) do { __builtin_amdgcn_s_setprio(1); _Pragma("unroll") for (int m = 0; m < 4; ++m) _Pragma("unroll") for (int n = 0; n < 2; ++n) _Pragma("unroll") for (int k = 0; k < 2; ++k) \
;         acc[ai][bj][m][n] = __builtin_amdgcn_mfma_f32_16x16x32_bf16(Bt[n][k], At[m][k], acc[ai][bj][m][n], 0, 0, 0); __builtin_amdgcn_s_setprio(0); } while (0)
; #define PG8_WAIT_V(n) asm volatile("s_waitcnt vmcnt(" #n ")" ::: "memory")
; #define PG8_WAIT_L(n) asm volatile("s_waitcnt lgkmcnt(" #n ")" ::: "memory")
; #define PG8_BAR __builtin_amdgcn_s_barrier()
; #define PG8_SCHED __builtin_amdgcn_sched_barrier(0)
; template <class Epi, bool ALIGN_EPI = PG8_ALIGN, bool SP2 = PG8_SP2>
; __device__ __forceinline__ void gemm_phase(LAS uchar* lds, const Gemm g, const StaticOrder& S, const Epi& E) {
;     ...
;             PG8_WAIT_V(8); PG8_WAIT_L(0); PG8_BAR; PG8_MMA(1, 0, At, B0); PG8_MMA(1, 1, At, B1); PG8_BAR; PG8_SCHED;
;             PG8_LDB(B0, 1, 0); PG8_LDB(B1, 1, 1); PG8_SCHED; PG8_LDA(At, 1, 0); PG8_STAGE(PG8_SA(0, 1), a2 + hstepA, voffA);
;             PG8_WAIT_V(8); PG8_WAIT_L(0); PG8_BAR; PG8_MMA(0, 0, At, B0); PG8_MMA(0, 1, At, B1); PG8_BAR; PG8_SCHED;
.Lrw_done_345_1_pl:
	s_waitcnt lgkmcnt(0)
	s_setprio 1
	s_barrier
	v_mfma_f32_16x16x32_bf16 v[62:65], v[164:167], v[204:207], 0
	v_mfma_f32_16x16x32_bf16 v[58:61], v[176:179], v[204:207], 0
	v_mfma_f32_16x16x32_bf16 v[54:57], v[164:167], v[212:215], 0
	v_mfma_f32_16x16x32_bf16 v[46:49], v[176:179], v[212:215], 0
	v_mfma_f32_16x16x32_bf16 v[38:41], v[164:167], v[220:223], 0
	v_mfma_f32_16x16x32_bf16 v[30:33], v[176:179], v[220:223], 0
	v_mfma_f32_16x16x32_bf16 v[22:25], v[164:167], v[228:231], 0
	v_mfma_f32_16x16x32_bf16 v[14:17], v[176:179], v[228:231], 0
	v_mfma_f32_16x16x32_bf16 v[62:65], v[172:175], v[208:211], v[62:65]
	v_mfma_f32_16x16x32_bf16 v[58:61], v[184:187], v[208:211], v[58:61]
	v_mfma_f32_16x16x32_bf16 v[54:57], v[172:175], v[216:219], v[54:57]
	v_mfma_f32_16x16x32_bf16 v[46:49], v[184:187], v[216:219], v[46:49]
	v_mfma_f32_16x16x32_bf16 v[38:41], v[172:175], v[224:227], v[38:41]
	v_mfma_f32_16x16x32_bf16 v[30:33], v[184:187], v[224:227], v[30:33]
	v_mfma_f32_16x16x32_bf16 v[22:25], v[172:175], v[232:235], v[22:25]
	v_mfma_f32_16x16x32_bf16 v[14:17], v[184:187], v[232:235], v[14:17]
	v_mfma_f32_16x16x32_bf16 v[50:53], v[188:191], v[204:207], 0
	v_mfma_f32_16x16x32_bf16 v[42:45], v[196:199], v[204:207], 0
	v_mfma_f32_16x16x32_bf16 v[34:37], v[188:191], v[212:215], 0
	v_mfma_f32_16x16x32_bf16 v[26:29], v[196:199], v[212:215], 0
	v_mfma_f32_16x16x32_bf16 v[18:21], v[188:191], v[220:223], 0
	v_mfma_f32_16x16x32_bf16 v[10:13], v[196:199], v[220:223], 0
	v_mfma_f32_16x16x32_bf16 v[6:9], v[188:191], v[228:231], 0
	v_mfma_f32_16x16x32_bf16 v[2:5], v[196:199], v[228:231], 0
	v_mfma_f32_16x16x32_bf16 v[50:53], v[192:195], v[208:211], v[50:53]
	v_mfma_f32_16x16x32_bf16 v[42:45], v[200:203], v[208:211], v[42:45]
	v_mfma_f32_16x16x32_bf16 v[34:37], v[192:195], v[216:219], v[34:37]
	v_mfma_f32_16x16x32_bf16 v[26:29], v[200:203], v[216:219], v[26:29]
	v_mfma_f32_16x16x32_bf16 v[18:21], v[192:195], v[224:227], v[18:21]
	v_mfma_f32_16x16x32_bf16 v[10:13], v[200:203], v[224:227], v[10:13]
	v_mfma_f32_16x16x32_bf16 v[6:9], v[192:195], v[232:235], v[6:9]
	v_mfma_f32_16x16x32_bf16 v[2:5], v[200:203], v[232:235], v[2:5]
	s_barrier
	s_setprio 0
	v_add_u32_e32 v184, 0x18000, v139
	v_add_u32_e32 v200, 0x1c000, v139
	ds_read_b128 v[164:167], v184
	ds_read_b128 v[172:175], v184 offset:1024
	ds_read_b128 v[176:179], v184 offset:2048
	ds_read_b128 v[184:187], v184 offset:3072
	ds_read_b128 v[188:191], v200
	ds_read_b128 v[192:195], v200 offset:1024
	ds_read_b128 v[196:199], v200 offset:2048
	ds_read_b128 v[200:203], v200 offset:3072
	s_add_u32 s16, s20, 0x44000
	s_addc_u32 s17, s21, 0
	s_mov_b32 m0, s27
	v_lshl_add_u64 v[240:241], s[16:17], 0, v[156:157]
	ds_read_b128 v[204:207], v171 offset:32768
	ds_read_b128 v[208:211], v171 offset:33792
	ds_read_b128 v[212:215], v171 offset:34816
	ds_read_b128 v[216:219], v171 offset:35840
	ds_read_b128 v[220:223], v171 offset:36864
	ds_read_b128 v[224:227], v171 offset:37888
	ds_read_b128 v[228:231], v171 offset:38912
	ds_read_b128 v[232:235], v171 offset:39936
	global_load_lds_dwordx4 v[240:241], off
	s_mov_b32 m0, s28
	v_lshl_add_u64 v[240:241], s[16:17], 0, v[132:133]
	global_load_lds_dwordx4 v[240:241], off
	s_waitcnt vmcnt(8)
	s_waitcnt lgkmcnt(0)
	s_setprio 1
	s_barrier
	v_mfma_f32_16x16x32_bf16 v[126:129], v[164:167], v[204:207], v[126:129]
	v_mfma_f32_16x16x32_bf16 v[122:125], v[176:179], v[204:207], v[122:125]
	v_mfma_f32_16x16x32_bf16 v[118:121], v[164:167], v[212:215], v[118:121]
	v_mfma_f32_16x16x32_bf16 v[110:113], v[176:179], v[212:215], v[110:113]
	v_mfma_f32_16x16x32_bf16 v[102:105], v[164:167], v[220:223], v[102:105]
	v_mfma_f32_16x16x32_bf16 v[94:97], v[176:179], v[220:223], v[94:97]
	v_mfma_f32_16x16x32_bf16 v[86:89], v[164:167], v[228:231], v[86:89]
	v_mfma_f32_16x16x32_bf16 v[78:81], v[176:179], v[228:231], v[78:81]
	v_mfma_f32_16x16x32_bf16 v[126:129], v[172:175], v[208:211], v[126:129]
	v_mfma_f32_16x16x32_bf16 v[122:125], v[184:187], v[208:211], v[122:125]
	v_mfma_f32_16x16x32_bf16 v[118:121], v[172:175], v[216:219], v[118:121]
	v_mfma_f32_16x16x32_bf16 v[110:113], v[184:187], v[216:219], v[110:113]
	v_mfma_f32_16x16x32_bf16 v[102:105], v[172:175], v[224:227], v[102:105]
	v_mfma_f32_16x16x32_bf16 v[94:97], v[184:187], v[224:227], v[94:97]
	v_mfma_f32_16x16x32_bf16 v[86:89], v[172:175], v[232:235], v[86:89]
	v_mfma_f32_16x16x32_bf16 v[78:81], v[184:187], v[232:235], v[78:81]
	v_mfma_f32_16x16x32_bf16 v[114:117], v[188:191], v[204:207], v[114:117]
	v_mfma_f32_16x16x32_bf16 v[106:109], v[196:199], v[204:207], v[106:109]
	v_mfma_f32_16x16x32_bf16 v[98:101], v[188:191], v[212:215], v[98:101]
	v_mfma_f32_16x16x32_bf16 v[90:93], v[196:199], v[212:215], v[90:93]
	v_mfma_f32_16x16x32_bf16 v[82:85], v[188:191], v[220:223], v[82:85]
	v_mfma_f32_16x16x32_bf16 v[74:77], v[196:199], v[220:223], v[74:77]
	v_mfma_f32_16x16x32_bf16 v[70:73], v[188:191], v[228:231], v[70:73]
	v_mfma_f32_16x16x32_bf16 v[66:69], v[196:199], v[228:231], v[66:69]
	v_mfma_f32_16x16x32_bf16 v[114:117], v[192:195], v[208:211], v[114:117]
	v_mfma_f32_16x16x32_bf16 v[106:109], v[200:203], v[208:211], v[106:109]
	v_mfma_f32_16x16x32_bf16 v[98:101], v[192:195], v[216:219], v[98:101]
	v_mfma_f32_16x16x32_bf16 v[90:93], v[200:203], v[216:219], v[90:93]
	v_mfma_f32_16x16x32_bf16 v[82:85], v[192:195], v[224:227], v[82:85]
	v_mfma_f32_16x16x32_bf16 v[74:77], v[200:203], v[224:227], v[74:77]
	v_mfma_f32_16x16x32_bf16 v[70:73], v[192:195], v[232:235], v[70:73]
	v_mfma_f32_16x16x32_bf16 v[66:69], v[200:203], v[232:235], v[66:69]
	s_barrier
; #define PG8_STAGE(bufoff, gbase, voff) do { _Pragma("unroll") for (int _i = 0; _i < 2; ++_i) \
;         __builtin_amdgcn_global_load_lds((const unsigned*)((const char*)(gbase) + (voff)[_i]), (LAS unsigned*)(lds + (bufoff) + ldsw + _i * 8192), 16, 0, 0); } while (0)
; #define PG8_LDA(dst, b, h) do { _Pragma("unroll") for (int m = 0; m < 4; ++m) _Pragma("unroll") for (int k = 0; k < 2; ++k) dst[m][k] = *(const LAS bf16x8*)(lds + PG8_SA(b, h) + aoff + m * 2048 + k * 1024); } while (0)
; #define PG8_LDB(dst, b, h) do { _Pragma("unroll") for (int n = 0; n < 2; ++n) _Pragma("unroll") for (int k = 0; k < 2; ++k) dst[n][k] = *(const LAS bf16x8*)(lds + PG8_SB(b, h) + boff + n * 2048 + k * 1024); } while (0)
; #define PG8_MMA(ai, bj, At, Bt) do { __builtin_amdgcn_s_setprio(1); _Pragma("unroll") for (int m = 0; m < 4; ++m) _Pragma("unroll") for (int n = 0; n < 2; ++n) _Pragma("unroll") for (int k = 0; k < 2; ++k) \
;         acc[ai][bj][m][n] = __builtin_amdgcn_mfma_f32_16x16x32_bf16(Bt[n][k], At[m][k], acc[ai][bj][m][n], 0, 0, 0); __builtin_amdgcn_s_setprio(0); } while (0)
; #define PG8_WAIT_V(n) asm volatile("s_waitcnt vmcnt(" #n ")" ::: "memory")
; #define PG8_WAIT_L(n) asm volatile("s_waitcnt lgkmcnt(" #n ")" ::: "memory")
; #define PG8_BAR __builtin_amdgcn_s_barrier()
; #define PG8_SCHED __builtin_amdgcn_sched_barrier(0)
; template <class Epi, bool ALIGN_EPI = PG8_ALIGN, bool SP2 = PG8_SP2>
; __device__ __forceinline__ void gemm_phase(LAS uchar* lds, const Gemm g, const StaticOrder& S, const Epi& E) {
;     ...
;             const bool last = (t == nt - 2);
;             const char* a1 = cA + (size_t)(t + 1) * kstep;
;             const char* a2 = last ? nA : cA + (size_t)(t + 2) * kstep; const char* b2 = last ? nB : cB + (size_t)(t + 2) * kstep;
;             const char* a3 = a2 + kstep; const char* b3 = b2 + kstep;
;             if constexpr (SP2) {
;             PG8_LDB(B0, 0, 0); PG8_LDB(B1, 0, 1); PG8_SCHED; PG8_LDA(At, 0, 0); PG8_STAGE(PG8_SA(1, 1), a1 + hstepA, voffA);
;             PG8_WAIT_V(8); PG8_WAIT_L(0); PG8_BAR; PG8_MMA(0, 0, At, B0); PG8_MMA(0, 1, At, B1); PG8_BAR; PG8_SCHED;
;     ...
;             PG8_LDA(At, 1, 1); PG8_STAGE(PG8_SB(1, 0), b3, voffB); PG8_STAGE(PG8_SB(1, 1), b3 + hstepB, voffB); PG8_STAGE(PG8_SA(1, 0), a3, voffA);
;             PG8_WAIT_V(8); PG8_WAIT_L(0); PG8_BAR; PG8_MMA(1, 0, At, B0); PG8_MMA(1, 1, At, B1); PG8_BAR; PG8_SCHED;
	s_setprio 0
	v_lshl_add_u64 v[168:169], v[168:169], 0, s[84:85]
	s_add_i32 m0, s23, 0x18000
	ds_read_b128 v[204:207], v171 offset:49152
	ds_read_b128 v[208:211], v171 offset:50176
	ds_read_b128 v[212:215], v171 offset:51200
	ds_read_b128 v[216:219], v171 offset:52224
	ds_read_b128 v[220:223], v171 offset:53248
	ds_read_b128 v[224:227], v171 offset:54272
	ds_read_b128 v[228:231], v171 offset:55296
	ds_read_b128 v[232:235], v171 offset:56320
	global_load_lds_dwordx4 v[168:169], off
	s_add_i32 m0, s23, 0x1a000
	s_add_u32 s4, s4, 0x44080
	v_lshl_add_u64 v[168:169], v[180:181], 0, s[84:85]
	s_addc_u32 s5, s5, 0
	global_load_lds_dwordx4 v[168:169], off
	s_add_i32 m0, s23, 0x1c000
	v_lshl_add_u64 v[168:169], s[4:5], 0, v[134:135]
	global_load_lds_dwordx4 v[168:169], off
	s_add_i32 m0, s23, 0x1e000
	v_lshl_add_u64 v[168:169], s[4:5], 0, v[130:131]
	global_load_lds_dwordx4 v[168:169], off
	s_mov_b32 m0, s29
	v_lshl_add_u64 v[168:169], v[236:237], 0, s[84:85]
	global_load_lds_dwordx4 v[168:169], off
	s_mov_b32 m0, s30
	v_lshl_add_u64 v[168:169], v[238:239], 0, s[84:85]
	global_load_lds_dwordx4 v[168:169], off
	s_waitcnt vmcnt(8)
	s_waitcnt lgkmcnt(0)
	s_setprio 1
	s_barrier
	v_mfma_f32_16x16x32_bf16 v[62:65], v[164:167], v[204:207], v[62:65]
	v_mfma_f32_16x16x32_bf16 v[58:61], v[176:179], v[204:207], v[58:61]
	v_mfma_f32_16x16x32_bf16 v[54:57], v[164:167], v[212:215], v[54:57]
	v_mfma_f32_16x16x32_bf16 v[46:49], v[176:179], v[212:215], v[46:49]
	v_mfma_f32_16x16x32_bf16 v[38:41], v[164:167], v[220:223], v[38:41]
	v_mfma_f32_16x16x32_bf16 v[30:33], v[176:179], v[220:223], v[30:33]
	v_mfma_f32_16x16x32_bf16 v[22:25], v[164:167], v[228:231], v[22:25]
	v_mfma_f32_16x16x32_bf16 v[14:17], v[176:179], v[228:231], v[14:17]
	v_mfma_f32_16x16x32_bf16 v[62:65], v[172:175], v[208:211], v[62:65]
	v_mfma_f32_16x16x32_bf16 v[58:61], v[184:187], v[208:211], v[58:61]
	v_mfma_f32_16x16x32_bf16 v[54:57], v[172:175], v[216:219], v[54:57]
	v_mfma_f32_16x16x32_bf16 v[46:49], v[184:187], v[216:219], v[46:49]
	v_mfma_f32_16x16x32_bf16 v[38:41], v[172:175], v[224:227], v[38:41]
	v_mfma_f32_16x16x32_bf16 v[30:33], v[184:187], v[224:227], v[30:33]
	v_mfma_f32_16x16x32_bf16 v[22:25], v[172:175], v[232:235], v[22:25]
	v_mfma_f32_16x16x32_bf16 v[14:17], v[184:187], v[232:235], v[14:17]
	v_mfma_f32_16x16x32_bf16 v[50:53], v[188:191], v[204:207], v[50:53]
	v_mfma_f32_16x16x32_bf16 v[42:45], v[196:199], v[204:207], v[42:45]
	v_mfma_f32_16x16x32_bf16 v[34:37], v[188:191], v[212:215], v[34:37]
	v_mfma_f32_16x16x32_bf16 v[26:29], v[196:199], v[212:215], v[26:29]
	v_mfma_f32_16x16x32_bf16 v[18:21], v[188:191], v[220:223], v[18:21]
	v_mfma_f32_16x16x32_bf16 v[10:13], v[196:199], v[220:223], v[10:13]
	v_mfma_f32_16x16x32_bf16 v[6:9], v[188:191], v[228:231], v[6:9]
	v_mfma_f32_16x16x32_bf16 v[2:5], v[196:199], v[228:231], v[2:5]
	v_mfma_f32_16x16x32_bf16 v[50:53], v[192:195], v[208:211], v[50:53]
	v_mfma_f32_16x16x32_bf16 v[42:45], v[200:203], v[208:211], v[42:45]
	v_mfma_f32_16x16x32_bf16 v[34:37], v[192:195], v[216:219], v[34:37]
	v_mfma_f32_16x16x32_bf16 v[26:29], v[200:203], v[216:219], v[26:29]
	v_mfma_f32_16x16x32_bf16 v[18:21], v[192:195], v[224:227], v[18:21]
	v_mfma_f32_16x16x32_bf16 v[10:13], v[200:203], v[224:227], v[10:13]
	v_mfma_f32_16x16x32_bf16 v[6:9], v[192:195], v[232:235], v[6:9]
	v_mfma_f32_16x16x32_bf16 v[2:5], v[200:203], v[232:235], v[2:5]
	s_barrier
	s_setprio 0
	s_add_i32 s40, s40, 2
	s_add_u32 s38, s38, 0x100
	s_addc_u32 s39, s39, 0
	s_cmp_gt_u32 s40, 13
	s_mov_b64 s[16:17], s[18:19]
.LBB0_345:
	s_add_u32 s18, s16, 0x100
	s_addc_u32 s19, s17, 0
	s_cmp_eq_u32 s40, 12
	s_cselect_b32 s21, s7, s19
	s_cselect_b32 s20, s6, s18
	v_add_u32_e32 v168, 0x10000, v139
	s_cselect_b32 s5, s15, s39
	s_cselect_b32 s4, s14, s38
	ds_read_b128 v[164:167], v168
	ds_read_b128 v[172:175], v168 offset:1024
	ds_read_b128 v[176:179], v168 offset:2048
	ds_read_b128 v[184:187], v168 offset:3072
	v_add_u32_e32 v168, 0x14000, v139
	ds_read_b128 v[188:191], v168
	ds_read_b128 v[192:195], v168 offset:1024
	ds_read_b128 v[196:199], v168 offset:2048
	ds_read_b128 v[200:203], v168 offset:3072
	v_lshl_add_u64 v[168:169], s[16:17], 0, v[160:161]
	s_add_i32 m0, s25, 0xc000
	ds_read_b128 v[204:207], v171
	ds_read_b128 v[208:211], v171 offset:1024
	ds_read_b128 v[212:215], v171 offset:2048
	ds_read_b128 v[216:219], v171 offset:3072
	ds_read_b128 v[220:223], v171 offset:4096
	ds_read_b128 v[224:227], v171 offset:5120
	ds_read_b128 v[228:231], v171 offset:6144
	ds_read_b128 v[232:235], v171 offset:7168
	global_load_lds_dwordx4 v[168:169], off
	s_add_i32 m0, s25, 0xe000
	v_lshl_add_u64 v[168:169], s[16:17], 0, v[162:163]
	global_load_lds_dwordx4 v[168:169], off
	s_waitcnt vmcnt(8)
	s_waitcnt lgkmcnt(0)
	s_setprio 1
	s_barrier
; #define PG8_STAGE(bufoff, gbase, voff) do { _Pragma("unroll") for (int _i = 0; _i < 2; ++_i) \
;         __builtin_amdgcn_global_load_lds((const unsigned*)((const char*)(gbase) + (voff)[_i]), (LAS unsigned*)(lds + (bufoff) + ldsw + _i * 8192), 16, 0, 0); } while (0)
; #define PG8_LDA(dst, b, h) do { _Pragma("unroll") for (int m = 0; m < 4; ++m) _Pragma("unroll") for (int k = 0; k < 2; ++k) dst[m][k] = *(const LAS bf16x8*)(lds + PG8_SA(b, h) + aoff + m * 2048 + k * 1024); } while (0)
; #define PG8_MMA(ai, bj, At, Bt) do { __builtin_amdgcn_s_setprio(1); _Pragma("unroll") for (int m = 0; m < 4; ++m) _Pragma("unroll") for (int n = 0; n < 2; ++n) _Pragma("unroll") for (int k = 0; k < 2; ++k) \
;         acc[ai][bj][m][n] = __builtin_amdgcn_mfma_f32_16x16x32_bf16(Bt[n][k], At[m][k], acc[ai][bj][m][n], 0, 0, 0); __builtin_amdgcn_s_setprio(0); } while (0)
; #define PG8_WAIT_V(n) asm volatile("s_waitcnt vmcnt(" #n ")" ::: "memory")
; #define PG8_WAIT_L(n) asm volatile("s_waitcnt lgkmcnt(" #n ")" ::: "memory")
; #define PG8_BAR __builtin_amdgcn_s_barrier()
; #define PG8_SCHED __builtin_amdgcn_sched_barrier(0)
; template <class Epi, bool ALIGN_EPI = PG8_ALIGN, bool SP2 = PG8_SP2>
; __device__ __forceinline__ void gemm_phase(LAS uchar* lds, const Gemm g, const StaticOrder& S, const Epi& E) {
;     ...
;             PG8_WAIT_V(8); PG8_WAIT_L(0); PG8_BAR; PG8_MMA(0, 0, At, B0); PG8_MMA(0, 1, At, B1); PG8_BAR; PG8_SCHED;
;             PG8_LDA(At, 0, 1); PG8_STAGE(PG8_SB(0, 0), b2, voffB); PG8_STAGE(PG8_SB(0, 1), b2 + hstepB, voffB); PG8_STAGE(PG8_SA(0, 0), a2, voffA);
;             PG8_WAIT_V(8); PG8_WAIT_L(0); PG8_BAR; PG8_MMA(1, 0, At, B0); PG8_MMA(1, 1, At, B1); PG8_BAR; PG8_SCHED;
	v_mfma_f32_16x16x32_bf16 v[126:129], v[164:167], v[204:207], v[126:129]
	v_mfma_f32_16x16x32_bf16 v[122:125], v[176:179], v[204:207], v[122:125]
	v_mfma_f32_16x16x32_bf16 v[118:121], v[164:167], v[212:215], v[118:121]
	v_mfma_f32_16x16x32_bf16 v[110:113], v[176:179], v[212:215], v[110:113]
	v_mfma_f32_16x16x32_bf16 v[102:105], v[164:167], v[220:223], v[102:105]
	v_mfma_f32_16x16x32_bf16 v[94:97], v[176:179], v[220:223], v[94:97]
	v_mfma_f32_16x16x32_bf16 v[86:89], v[164:167], v[228:231], v[86:89]
	v_mfma_f32_16x16x32_bf16 v[78:81], v[176:179], v[228:231], v[78:81]
	v_mfma_f32_16x16x32_bf16 v[126:129], v[172:175], v[208:211], v[126:129]
	v_mfma_f32_16x16x32_bf16 v[122:125], v[184:187], v[208:211], v[122:125]
	v_mfma_f32_16x16x32_bf16 v[118:121], v[172:175], v[216:219], v[118:121]
	v_mfma_f32_16x16x32_bf16 v[110:113], v[184:187], v[216:219], v[110:113]
	v_mfma_f32_16x16x32_bf16 v[102:105], v[172:175], v[224:227], v[102:105]
	v_mfma_f32_16x16x32_bf16 v[94:97], v[184:187], v[224:227], v[94:97]
	v_mfma_f32_16x16x32_bf16 v[86:89], v[172:175], v[232:235], v[86:89]
	v_mfma_f32_16x16x32_bf16 v[78:81], v[184:187], v[232:235], v[78:81]
	v_mfma_f32_16x16x32_bf16 v[114:117], v[188:191], v[204:207], v[114:117]
	v_mfma_f32_16x16x32_bf16 v[106:109], v[196:199], v[204:207], v[106:109]
	v_mfma_f32_16x16x32_bf16 v[98:101], v[188:191], v[212:215], v[98:101]
	v_mfma_f32_16x16x32_bf16 v[90:93], v[196:199], v[212:215], v[90:93]
	v_mfma_f32_16x16x32_bf16 v[82:85], v[188:191], v[220:223], v[82:85]
	v_mfma_f32_16x16x32_bf16 v[74:77], v[196:199], v[220:223], v[74:77]
	v_mfma_f32_16x16x32_bf16 v[70:73], v[188:191], v[228:231], v[70:73]
	v_mfma_f32_16x16x32_bf16 v[66:69], v[196:199], v[228:231], v[66:69]
	v_mfma_f32_16x16x32_bf16 v[114:117], v[192:195], v[208:211], v[114:117]
	v_mfma_f32_16x16x32_bf16 v[106:109], v[200:203], v[208:211], v[106:109]
	v_mfma_f32_16x16x32_bf16 v[98:101], v[192:195], v[216:219], v[98:101]
	v_mfma_f32_16x16x32_bf16 v[90:93], v[200:203], v[216:219], v[90:93]
	v_mfma_f32_16x16x32_bf16 v[82:85], v[192:195], v[224:227], v[82:85]
	v_mfma_f32_16x16x32_bf16 v[74:77], v[200:203], v[224:227], v[74:77]
	v_mfma_f32_16x16x32_bf16 v[70:73], v[192:195], v[232:235], v[70:73]
	v_mfma_f32_16x16x32_bf16 v[66:69], v[200:203], v[232:235], v[66:69]
	s_barrier
	s_setprio 0
	v_lshl_add_u64 v[168:169], s[4:5], 0, v[134:135]
	s_add_i32 m0, s23, 0x10000
	ds_read_b128 v[204:207], v171 offset:16384
	ds_read_b128 v[208:211], v171 offset:17408
	ds_read_b128 v[212:215], v171 offset:18432
	ds_read_b128 v[216:219], v171 offset:19456
	ds_read_b128 v[220:223], v171 offset:20480
	ds_read_b128 v[224:227], v171 offset:21504
	ds_read_b128 v[228:231], v171 offset:22528
	ds_read_b128 v[232:235], v171 offset:23552
	global_load_lds_dwordx4 v[168:169], off
	s_add_i32 m0, s23, 0x12000
	s_add_u32 s16, s4, 0x44000
	v_lshl_add_u64 v[180:181], s[4:5], 0, v[130:131]
	s_addc_u32 s17, s5, 0
	global_load_lds_dwordx4 v[180:181], off
	s_add_i32 m0, s23, 0x14000
	v_lshl_add_u64 v[236:237], s[16:17], 0, v[134:135]
	global_load_lds_dwordx4 v[236:237], off
	s_add_i32 m0, s23, 0x16000
	v_lshl_add_u64 v[236:237], s[16:17], 0, v[130:131]
	global_load_lds_dwordx4 v[236:237], off
	s_mov_b32 m0, s25
	v_lshl_add_u64 v[236:237], s[20:21], 0, v[156:157]
	global_load_lds_dwordx4 v[236:237], off
	s_mov_b32 m0, s26
	v_lshl_add_u64 v[238:239], s[20:21], 0, v[132:133]
	global_load_lds_dwordx4 v[238:239], off
	s_waitcnt vmcnt(8)
	s_waitcnt lgkmcnt(0)
	s_setprio 1
	s_barrier
	v_mfma_f32_16x16x32_bf16 v[62:65], v[164:167], v[204:207], v[62:65]
	v_mfma_f32_16x16x32_bf16 v[58:61], v[176:179], v[204:207], v[58:61]
	v_mfma_f32_16x16x32_bf16 v[54:57], v[164:167], v[212:215], v[54:57]
	v_mfma_f32_16x16x32_bf16 v[46:49], v[176:179], v[212:215], v[46:49]
	v_mfma_f32_16x16x32_bf16 v[38:41], v[164:167], v[220:223], v[38:41]
	v_mfma_f32_16x16x32_bf16 v[30:33], v[176:179], v[220:223], v[30:33]
	v_mfma_f32_16x16x32_bf16 v[22:25], v[164:167], v[228:231], v[22:25]
	v_mfma_f32_16x16x32_bf16 v[14:17], v[176:179], v[228:231], v[14:17]
	v_mfma_f32_16x16x32_bf16 v[62:65], v[172:175], v[208:211], v[62:65]
	v_mfma_f32_16x16x32_bf16 v[58:61], v[184:187], v[208:211], v[58:61]
	v_mfma_f32_16x16x32_bf16 v[54:57], v[172:175], v[216:219], v[54:57]
	v_mfma_f32_16x16x32_bf16 v[46:49], v[184:187], v[216:219], v[46:49]
	v_mfma_f32_16x16x32_bf16 v[38:41], v[172:175], v[224:227], v[38:41]
	v_mfma_f32_16x16x32_bf16 v[30:33], v[184:187], v[224:227], v[30:33]
	v_mfma_f32_16x16x32_bf16 v[22:25], v[172:175], v[232:235], v[22:25]
	v_mfma_f32_16x16x32_bf16 v[14:17], v[184:187], v[232:235], v[14:17]
	v_mfma_f32_16x16x32_bf16 v[50:53], v[188:191], v[204:207], v[50:53]
	v_mfma_f32_16x16x32_bf16 v[42:45], v[196:199], v[204:207], v[42:45]
	v_mfma_f32_16x16x32_bf16 v[34:37], v[188:191], v[212:215], v[34:37]
	v_mfma_f32_16x16x32_bf16 v[26:29], v[196:199], v[212:215], v[26:29]
	v_mfma_f32_16x16x32_bf16 v[18:21], v[188:191], v[220:223], v[18:21]
	v_mfma_f32_16x16x32_bf16 v[10:13], v[196:199], v[220:223], v[10:13]
	v_mfma_f32_16x16x32_bf16 v[6:9], v[188:191], v[228:231], v[6:9]
	v_mfma_f32_16x16x32_bf16 v[2:5], v[196:199], v[228:231], v[2:5]
	v_mfma_f32_16x16x32_bf16 v[50:53], v[192:195], v[208:211], v[50:53]
	v_mfma_f32_16x16x32_bf16 v[42:45], v[200:203], v[208:211], v[42:45]
	v_mfma_f32_16x16x32_bf16 v[34:37], v[192:195], v[216:219], v[34:37]
	v_mfma_f32_16x16x32_bf16 v[26:29], v[200:203], v[216:219], v[26:29]
	v_mfma_f32_16x16x32_bf16 v[18:21], v[192:195], v[224:227], v[18:21]
	v_mfma_f32_16x16x32_bf16 v[10:13], v[200:203], v[224:227], v[10:13]
	v_mfma_f32_16x16x32_bf16 v[6:9], v[192:195], v[232:235], v[6:9]
	v_mfma_f32_16x16x32_bf16 v[2:5], v[200:203], v[232:235], v[2:5]
	s_barrier
; #define PG8_STAGE(bufoff, gbase, voff) do { _Pragma("unroll") for (int _i = 0; _i < 2; ++_i) \
;         __builtin_amdgcn_global_load_lds((const unsigned*)((const char*)(gbase) + (voff)[_i]), (LAS unsigned*)(lds + (bufoff) + ldsw + _i * 8192), 16, 0, 0); } while (0)
; #define PG8_LDA(dst, b, h) do { _Pragma("unroll") for (int m = 0; m < 4; ++m) _Pragma("unroll") for (int k = 0; k < 2; ++k) dst[m][k] = *(const LAS bf16x8*)(lds + PG8_SA(b, h) + aoff + m * 2048 + k * 1024); } while (0)
; #define PG8_LDB(dst, b, h) do { _Pragma("unroll") for (int n = 0; n < 2; ++n) _Pragma("unroll") for (int k = 0; k < 2; ++k) dst[n][k] = *(const LAS bf16x8*)(lds + PG8_SB(b, h) + boff + n * 2048 + k * 1024); } while (0)
; #define PG8_MMA(ai, bj, At, Bt) do { __builtin_amdgcn_s_setprio(1); _Pragma("unroll") for (int m = 0; m < 4; ++m) _Pragma("unroll") for (int n = 0; n < 2; ++n) _Pragma("unroll") for (int k = 0; k < 2; ++k) \
;         acc[ai][bj][m][n] = __builtin_amdgcn_mfma_f32_16x16x32_bf16(Bt[n][k], At[m][k], acc[ai][bj][m][n], 0, 0, 0); __builtin_amdgcn_s_setprio(0); } while (0)
; #define PG8_WAIT_V(n) asm volatile("s_waitcnt vmcnt(" #n ")" ::: "memory")
; #define PG8_WAIT_L(n) asm volatile("s_waitcnt lgkmcnt(" #n ")" ::: "memory")
; #define PG8_BAR __builtin_amdgcn_s_barrier()
; #define PG8_SCHED __builtin_amdgcn_sched_barrier(0)
; template <class Epi, bool ALIGN_EPI = PG8_ALIGN, bool SP2 = PG8_SP2>
; __device__ __forceinline__ void gemm_phase(LAS uchar* lds, const Gemm g, const StaticOrder& S, const Epi& E) {
;     ...
;             PG8_LDB(B0, 1, 0); PG8_LDB(B1, 1, 1); PG8_SCHED; PG8_LDA(At, 1, 0); PG8_STAGE(PG8_SA(0, 1), a2 + hstepA, voffA);
;             PG8_WAIT_V(8); PG8_WAIT_L(0); PG8_BAR; PG8_MMA(0, 0, At, B0); PG8_MMA(0, 1, At, B1); PG8_BAR; PG8_SCHED;
	s_setprio 0
	v_add_u32_e32 v184, 0x18000, v139
	v_add_u32_e32 v200, 0x1c000, v139
	ds_read_b128 v[164:167], v184
	ds_read_b128 v[172:175], v184 offset:1024
	ds_read_b128 v[176:179], v184 offset:2048
	ds_read_b128 v[184:187], v184 offset:3072
	ds_read_b128 v[188:191], v200
	ds_read_b128 v[192:195], v200 offset:1024
	ds_read_b128 v[196:199], v200 offset:2048
	ds_read_b128 v[200:203], v200 offset:3072
	s_add_u32 s16, s20, 0x44000
	s_addc_u32 s17, s21, 0
	s_mov_b32 m0, s27
	v_lshl_add_u64 v[240:241], s[16:17], 0, v[156:157]
	ds_read_b128 v[204:207], v171 offset:32768
	ds_read_b128 v[208:211], v171 offset:33792
	ds_read_b128 v[212:215], v171 offset:34816
	ds_read_b128 v[216:219], v171 offset:35840
	ds_read_b128 v[220:223], v171 offset:36864
	ds_read_b128 v[224:227], v171 offset:37888
	ds_read_b128 v[228:231], v171 offset:38912
	ds_read_b128 v[232:235], v171 offset:39936
	global_load_lds_dwordx4 v[240:241], off
	s_mov_b32 m0, s28
	v_lshl_add_u64 v[240:241], s[16:17], 0, v[132:133]
	global_load_lds_dwordx4 v[240:241], off
	s_waitcnt vmcnt(8)
	s_waitcnt lgkmcnt(0)
	s_setprio 1
	s_barrier
	v_mfma_f32_16x16x32_bf16 v[126:129], v[164:167], v[204:207], v[126:129]
	v_mfma_f32_16x16x32_bf16 v[122:125], v[176:179], v[204:207], v[122:125]
	v_mfma_f32_16x16x32_bf16 v[118:121], v[164:167], v[212:215], v[118:121]
	v_mfma_f32_16x16x32_bf16 v[110:113], v[176:179], v[212:215], v[110:113]
	v_mfma_f32_16x16x32_bf16 v[102:105], v[164:167], v[220:223], v[102:105]
	v_mfma_f32_16x16x32_bf16 v[94:97], v[176:179], v[220:223], v[94:97]
	v_mfma_f32_16x16x32_bf16 v[86:89], v[164:167], v[228:231], v[86:89]
	v_mfma_f32_16x16x32_bf16 v[78:81], v[176:179], v[228:231], v[78:81]
	v_mfma_f32_16x16x32_bf16 v[126:129], v[172:175], v[208:211], v[126:129]
	v_mfma_f32_16x16x32_bf16 v[122:125], v[184:187], v[208:211], v[122:125]
	v_mfma_f32_16x16x32_bf16 v[118:121], v[172:175], v[216:219], v[118:121]
	v_mfma_f32_16x16x32_bf16 v[110:113], v[184:187], v[216:219], v[110:113]
	v_mfma_f32_16x16x32_bf16 v[102:105], v[172:175], v[224:227], v[102:105]
	v_mfma_f32_16x16x32_bf16 v[94:97], v[184:187], v[224:227], v[94:97]
	v_mfma_f32_16x16x32_bf16 v[86:89], v[172:175], v[232:235], v[86:89]
	v_mfma_f32_16x16x32_bf16 v[78:81], v[184:187], v[232:235], v[78:81]
	v_mfma_f32_16x16x32_bf16 v[114:117], v[188:191], v[204:207], v[114:117]
	v_mfma_f32_16x16x32_bf16 v[106:109], v[196:199], v[204:207], v[106:109]
	v_mfma_f32_16x16x32_bf16 v[98:101], v[188:191], v[212:215], v[98:101]
	v_mfma_f32_16x16x32_bf16 v[90:93], v[196:199], v[212:215], v[90:93]
	v_mfma_f32_16x16x32_bf16 v[82:85], v[188:191], v[220:223], v[82:85]
	v_mfma_f32_16x16x32_bf16 v[74:77], v[196:199], v[220:223], v[74:77]
	v_mfma_f32_16x16x32_bf16 v[70:73], v[188:191], v[228:231], v[70:73]
	v_mfma_f32_16x16x32_bf16 v[66:69], v[196:199], v[228:231], v[66:69]
	v_mfma_f32_16x16x32_bf16 v[114:117], v[192:195], v[208:211], v[114:117]
	v_mfma_f32_16x16x32_bf16 v[106:109], v[200:203], v[208:211], v[106:109]
	v_mfma_f32_16x16x32_bf16 v[98:101], v[192:195], v[216:219], v[98:101]
	v_mfma_f32_16x16x32_bf16 v[90:93], v[200:203], v[216:219], v[90:93]
	v_mfma_f32_16x16x32_bf16 v[82:85], v[192:195], v[224:227], v[82:85]
	v_mfma_f32_16x16x32_bf16 v[74:77], v[200:203], v[224:227], v[74:77]
	v_mfma_f32_16x16x32_bf16 v[70:73], v[192:195], v[232:235], v[70:73]
	v_mfma_f32_16x16x32_bf16 v[66:69], v[200:203], v[232:235], v[66:69]
	s_barrier
; #define PG8_STAGE(bufoff, gbase, voff) do { _Pragma("unroll") for (int _i = 0; _i < 2; ++_i) \
;         __builtin_amdgcn_global_load_lds((const unsigned*)((const char*)(gbase) + (voff)[_i]), (LAS unsigned*)(lds + (bufoff) + ldsw + _i * 8192), 16, 0, 0); } while (0)
; #define PG8_LDA(dst, b, h) do { _Pragma("unroll") for (int m = 0; m < 4; ++m) _Pragma("unroll") for (int k = 0; k < 2; ++k) dst[m][k] = *(const LAS bf16x8*)(lds + PG8_SA(b, h) + aoff + m * 2048 + k * 1024); } while (0)
; #define PG8_MMA(ai, bj, At, Bt) do { __builtin_amdgcn_s_setprio(1); _Pragma("unroll") for (int m = 0; m < 4; ++m) _Pragma("unroll") for (int n = 0; n < 2; ++n) _Pragma("unroll") for (int k = 0; k < 2; ++k) \
;         acc[ai][bj][m][n] = __builtin_amdgcn_mfma_f32_16x16x32_bf16(Bt[n][k], At[m][k], acc[ai][bj][m][n], 0, 0, 0); __builtin_amdgcn_s_setprio(0); } while (0)
; #define PG8_WAIT_V(n) asm volatile("s_waitcnt vmcnt(" #n ")" ::: "memory")
; #define PG8_WAIT_L(n) asm volatile("s_waitcnt lgkmcnt(" #n ")" ::: "memory")
; #define PG8_BAR __builtin_amdgcn_s_barrier()
; #define PG8_SCHED __builtin_amdgcn_sched_barrier(0)
; template <class Epi, bool ALIGN_EPI = PG8_ALIGN, bool SP2 = PG8_SP2>
; __device__ __forceinline__ void gemm_phase(LAS uchar* lds, const Gemm g, const StaticOrder& S, const Epi& E) {
;     ...
;             PG8_LDA(At, 1, 1); PG8_STAGE(PG8_SB(1, 0), b3, voffB); PG8_STAGE(PG8_SB(1, 1), b3 + hstepB, voffB); PG8_STAGE(PG8_SA(1, 0), a3, voffA);
;             PG8_WAIT_V(8); PG8_WAIT_L(0); PG8_BAR; PG8_MMA(1, 0, At, B0); PG8_MMA(1, 1, At, B1); PG8_BAR; PG8_SCHED;
;     __device__ __forceinline__ void operator()(const f32x4 (&acc)[2][2][4][2], const pg8::Unit& u, int wr, int wc, int fr, int fq, int) const {
;         const int row0 = u.pm * 256 + wr * 64 + fr;
;         if (u.pn < 24) {
	s_setprio 0
	v_lshl_add_u64 v[168:169], v[168:169], 0, s[84:85]
	s_add_i32 m0, s23, 0x18000
	ds_read_b128 v[204:207], v171 offset:49152
	ds_read_b128 v[208:211], v171 offset:50176
	ds_read_b128 v[212:215], v171 offset:51200
	ds_read_b128 v[216:219], v171 offset:52224
	ds_read_b128 v[220:223], v171 offset:53248
	ds_read_b128 v[224:227], v171 offset:54272
	ds_read_b128 v[228:231], v171 offset:55296
	ds_read_b128 v[232:235], v171 offset:56320
	global_load_lds_dwordx4 v[168:169], off
	s_add_i32 m0, s23, 0x1a000
	s_add_u32 s4, s4, 0x44080
	v_lshl_add_u64 v[168:169], v[180:181], 0, s[84:85]
	s_addc_u32 s5, s5, 0
	global_load_lds_dwordx4 v[168:169], off
	s_add_i32 m0, s23, 0x1c000
	v_lshl_add_u64 v[168:169], s[4:5], 0, v[134:135]
	global_load_lds_dwordx4 v[168:169], off
	s_add_i32 m0, s23, 0x1e000
	v_lshl_add_u64 v[168:169], s[4:5], 0, v[130:131]
	global_load_lds_dwordx4 v[168:169], off
	s_mov_b32 m0, s29
	v_lshl_add_u64 v[168:169], v[236:237], 0, s[84:85]
	global_load_lds_dwordx4 v[168:169], off
	s_mov_b32 m0, s30
	v_lshl_add_u64 v[168:169], v[238:239], 0, s[84:85]
	global_load_lds_dwordx4 v[168:169], off
	s_waitcnt vmcnt(8)
	s_waitcnt lgkmcnt(0)
	s_setprio 1
	s_barrier
	v_mfma_f32_16x16x32_bf16 v[62:65], v[164:167], v[204:207], v[62:65]
	v_mfma_f32_16x16x32_bf16 v[58:61], v[176:179], v[204:207], v[58:61]
	v_mfma_f32_16x16x32_bf16 v[54:57], v[164:167], v[212:215], v[54:57]
	v_mfma_f32_16x16x32_bf16 v[46:49], v[176:179], v[212:215], v[46:49]
	v_mfma_f32_16x16x32_bf16 v[38:41], v[164:167], v[220:223], v[38:41]
	v_mfma_f32_16x16x32_bf16 v[30:33], v[176:179], v[220:223], v[30:33]
	v_mfma_f32_16x16x32_bf16 v[22:25], v[164:167], v[228:231], v[22:25]
	v_mfma_f32_16x16x32_bf16 v[14:17], v[176:179], v[228:231], v[14:17]
	v_mfma_f32_16x16x32_bf16 v[62:65], v[172:175], v[208:211], v[62:65]
	v_mfma_f32_16x16x32_bf16 v[58:61], v[184:187], v[208:211], v[58:61]
	v_mfma_f32_16x16x32_bf16 v[54:57], v[172:175], v[216:219], v[54:57]
	v_mfma_f32_16x16x32_bf16 v[46:49], v[184:187], v[216:219], v[46:49]
	v_mfma_f32_16x16x32_bf16 v[38:41], v[172:175], v[224:227], v[38:41]
	v_mfma_f32_16x16x32_bf16 v[30:33], v[184:187], v[224:227], v[30:33]
	v_mfma_f32_16x16x32_bf16 v[22:25], v[172:175], v[232:235], v[22:25]
	v_mfma_f32_16x16x32_bf16 v[14:17], v[184:187], v[232:235], v[14:17]
	v_mfma_f32_16x16x32_bf16 v[50:53], v[188:191], v[204:207], v[50:53]
	v_mfma_f32_16x16x32_bf16 v[42:45], v[196:199], v[204:207], v[42:45]
	v_mfma_f32_16x16x32_bf16 v[34:37], v[188:191], v[212:215], v[34:37]
	v_mfma_f32_16x16x32_bf16 v[26:29], v[196:199], v[212:215], v[26:29]
	v_mfma_f32_16x16x32_bf16 v[18:21], v[188:191], v[220:223], v[18:21]
	v_mfma_f32_16x16x32_bf16 v[10:13], v[196:199], v[220:223], v[10:13]
	v_mfma_f32_16x16x32_bf16 v[6:9], v[188:191], v[228:231], v[6:9]
	v_mfma_f32_16x16x32_bf16 v[2:5], v[196:199], v[228:231], v[2:5]
	v_mfma_f32_16x16x32_bf16 v[50:53], v[192:195], v[208:211], v[50:53]
	v_mfma_f32_16x16x32_bf16 v[42:45], v[200:203], v[208:211], v[42:45]
	v_mfma_f32_16x16x32_bf16 v[34:37], v[192:195], v[216:219], v[34:37]
	v_mfma_f32_16x16x32_bf16 v[26:29], v[200:203], v[216:219], v[26:29]
	v_mfma_f32_16x16x32_bf16 v[18:21], v[192:195], v[224:227], v[18:21]
	v_mfma_f32_16x16x32_bf16 v[10:13], v[200:203], v[224:227], v[10:13]
	v_mfma_f32_16x16x32_bf16 v[6:9], v[192:195], v[232:235], v[6:9]
	v_mfma_f32_16x16x32_bf16 v[2:5], v[200:203], v[232:235], v[2:5]
	s_barrier
	s_setprio 0
	s_add_i32 s40, s40, 2
	s_add_u32 s38, s38, 0x100
	s_addc_u32 s39, s39, 0
	s_cmp_gt_u32 s40, 13
	s_mov_b64 s[16:17], s[18:19]
	s_cbranch_scc0 .LBB0_345
	s_mov_b32 s97, 0
	s_and_b64 vcc, exec, s[10:11]
	s_cbranch_vccnz .LBB0_350
	v_lshl_add_u32 v164, s37, 8, v1
	s_cmp_gt_i32 s36, 23
	s_mov_b64 s[4:5], -1
	s_cbranch_scc1 .LBB0_351

; #define PG8_STAGE(bufoff, gbase, voff) do { _Pragma("unroll") for (int _i = 0; _i < 2; ++_i) \
;         __builtin_amdgcn_global_load_lds((const unsigned*)((const char*)(gbase) + (voff)[_i]), (LAS unsigned*)(lds + (bufoff) + ldsw + _i * 8192), 16, 0, 0); } while (0)
; #define PG8_LDA(dst, b, h) do { _Pragma("unroll") for (int m = 0; m < 4; ++m) _Pragma("unroll") for (int k = 0; k < 2; ++k) dst[m][k] = *(const LAS bf16x8*)(lds + PG8_SA(b, h) + aoff + m * 2048 + k * 1024); } while (0)
; #define PG8_LDB(dst, b, h) do { _Pragma("unroll") for (int n = 0; n < 2; ++n) _Pragma("unroll") for (int k = 0; k < 2; ++k) dst[n][k] = *(const LAS bf16x8*)(lds + PG8_SB(b, h) + boff + n * 2048 + k * 1024); } while (0)
; #define PG8_MMA(ai, bj, At, Bt) do { __builtin_amdgcn_s_setprio(1); _Pragma("unroll") for (int m = 0; m < 4; ++m) _Pragma("unroll") for (int n = 0; n < 2; ++n) _Pragma("unroll") for (int k = 0; k < 2; ++k) \
;         acc[ai][bj][m][n] = __builtin_amdgcn_mfma_f32_16x16x32_bf16(Bt[n][k], At[m][k], acc[ai][bj][m][n], 0, 0, 0); __builtin_amdgcn_s_setprio(0); } while (0)
; #define PG8_WAIT_V(n) asm volatile("s_waitcnt vmcnt(" #n ")" ::: "memory")
; #define PG8_WAIT_L(n) asm volatile("s_waitcnt lgkmcnt(" #n ")" ::: "memory")
; #define PG8_BAR __builtin_amdgcn_s_barrier()
; #define PG8_SCHED __builtin_amdgcn_sched_barrier(0)
; template <class Epi, bool ALIGN_EPI = PG8_ALIGN, bool SP2 = PG8_SP2>
; __device__ __forceinline__ void gemm_phase(LAS uchar* lds, const Gemm g, const StaticOrder& S, const Epi& E) {
;     ...
;             const bool last = (t == nt - 2);
;             const char* a1 = cA + (size_t)(t + 1) * kstep;
;             const char* a2 = last ? nA : cA + (size_t)(t + 2) * kstep; const char* b2 = last ? nB : cB + (size_t)(t + 2) * kstep;
;             const char* a3 = a2 + kstep; const char* b3 = b2 + kstep;
;             if constexpr (SP2) {
;             PG8_LDB(B0, 0, 0); PG8_LDB(B1, 0, 1); PG8_SCHED; PG8_LDA(At, 0, 0); PG8_STAGE(PG8_SA(1, 1), a1 + hstepA, voffA);
;             PG8_WAIT_V(8); PG8_WAIT_L(0); PG8_BAR; PG8_MMA(0, 0, At, B0); PG8_MMA(0, 1, At, B1); PG8_BAR; PG8_SCHED;
;             PG8_LDA(At, 0, 1); PG8_STAGE(PG8_SB(0, 0), b2, voffB); PG8_STAGE(PG8_SB(0, 1), b2 + hstepB, voffB); PG8_STAGE(PG8_SA(0, 0), a2, voffA);
;             PG8_WAIT_V(8); PG8_WAIT_L(0); PG8_BAR; PG8_MMA(1, 0, At, B0); PG8_MMA(1, 1, At, B1); PG8_BAR; PG8_SCHED;
.LBB0_668:
	s_add_u32 s36, s14, 0x100
	s_addc_u32 s37, s15, 0
	s_mov_b32 s38, -2
	s_add_u32 s14, s12, 0x100
	s_addc_u32 s15, s13, 0
	s_cmp_eq_u32 s38, 12
	s_cselect_b32 s19, s5, s15
	s_cselect_b32 s18, s4, s14
	s_cselect_b32 s17, s11, s37
	s_cselect_b32 s16, s10, s36
	v_add_u32_e32 v174, 0x10000, v139
	v_add_u32_e32 v192, 0x14000, v139
	ds_read_b128 v[160:163], v174
	ds_read_b128 v[164:167], v174 offset:1024
	ds_read_b128 v[168:171], v174 offset:2048
	ds_read_b128 v[174:177], v174 offset:3072
	ds_read_b128 v[178:181], v192
	ds_read_b128 v[184:187], v192 offset:1024
	ds_read_b128 v[188:191], v192 offset:2048
	ds_read_b128 v[192:195], v192 offset:3072
	v_lshl_add_u64 v[228:229], s[12:13], 0, v[156:157]
	s_add_i32 m0, s23, 0xc000
	ds_read_b128 v[196:199], v173
	ds_read_b128 v[200:203], v173 offset:1024
	ds_read_b128 v[204:207], v173 offset:2048
	ds_read_b128 v[208:211], v173 offset:3072
	ds_read_b128 v[212:215], v173 offset:4096
	ds_read_b128 v[216:219], v173 offset:5120
	ds_read_b128 v[220:223], v173 offset:6144
	ds_read_b128 v[224:227], v173 offset:7168
	global_load_lds_dwordx4 v[228:229], off
	s_add_i32 m0, s23, 0xe000
	v_lshl_add_u64 v[228:229], s[12:13], 0, v[158:159]
	global_load_lds_dwordx4 v[228:229], off
	s_waitcnt vmcnt(8)
	s_waitcnt lgkmcnt(0)
	s_setprio 1
	s_barrier
	v_mfma_f32_16x16x32_bf16 v[126:129], v[160:163], v[196:199], 0
	v_mfma_f32_16x16x32_bf16 v[122:125], v[168:171], v[196:199], 0
	v_mfma_f32_16x16x32_bf16 v[118:121], v[160:163], v[204:207], 0
	v_mfma_f32_16x16x32_bf16 v[110:113], v[168:171], v[204:207], 0
	v_mfma_f32_16x16x32_bf16 v[102:105], v[160:163], v[212:215], 0
	v_mfma_f32_16x16x32_bf16 v[94:97], v[168:171], v[212:215], 0
	v_mfma_f32_16x16x32_bf16 v[86:89], v[160:163], v[220:223], 0
	v_mfma_f32_16x16x32_bf16 v[78:81], v[168:171], v[220:223], 0
	v_mfma_f32_16x16x32_bf16 v[126:129], v[164:167], v[200:203], v[126:129]
	v_mfma_f32_16x16x32_bf16 v[122:125], v[174:177], v[200:203], v[122:125]
	v_mfma_f32_16x16x32_bf16 v[118:121], v[164:167], v[208:211], v[118:121]
	v_mfma_f32_16x16x32_bf16 v[110:113], v[174:177], v[208:211], v[110:113]
	v_mfma_f32_16x16x32_bf16 v[102:105], v[164:167], v[216:219], v[102:105]
	v_mfma_f32_16x16x32_bf16 v[94:97], v[174:177], v[216:219], v[94:97]
	v_mfma_f32_16x16x32_bf16 v[86:89], v[164:167], v[224:227], v[86:89]
	v_mfma_f32_16x16x32_bf16 v[78:81], v[174:177], v[224:227], v[78:81]
	v_mfma_f32_16x16x32_bf16 v[114:117], v[178:181], v[196:199], 0
	v_mfma_f32_16x16x32_bf16 v[106:109], v[188:191], v[196:199], 0
	v_mfma_f32_16x16x32_bf16 v[98:101], v[178:181], v[204:207], 0
	v_mfma_f32_16x16x32_bf16 v[90:93], v[188:191], v[204:207], 0
	v_mfma_f32_16x16x32_bf16 v[82:85], v[178:181], v[212:215], 0
	v_mfma_f32_16x16x32_bf16 v[74:77], v[188:191], v[212:215], 0
	v_mfma_f32_16x16x32_bf16 v[70:73], v[178:181], v[220:223], 0
	v_mfma_f32_16x16x32_bf16 v[66:69], v[188:191], v[220:223], 0
	v_mfma_f32_16x16x32_bf16 v[114:117], v[184:187], v[200:203], v[114:117]
	v_mfma_f32_16x16x32_bf16 v[106:109], v[192:195], v[200:203], v[106:109]
	v_mfma_f32_16x16x32_bf16 v[98:101], v[184:187], v[208:211], v[98:101]
	v_mfma_f32_16x16x32_bf16 v[90:93], v[192:195], v[208:211], v[90:93]
	v_mfma_f32_16x16x32_bf16 v[82:85], v[184:187], v[216:219], v[82:85]
	v_mfma_f32_16x16x32_bf16 v[74:77], v[192:195], v[216:219], v[74:77]
	v_mfma_f32_16x16x32_bf16 v[70:73], v[184:187], v[224:227], v[70:73]
	v_mfma_f32_16x16x32_bf16 v[66:69], v[192:195], v[224:227], v[66:69]
	s_barrier
	s_setprio 0
	v_lshl_add_u64 v[228:229], s[16:17], 0, v[134:135]
	s_add_i32 m0, s21, 0x10000
	ds_read_b128 v[196:199], v173 offset:16384
	ds_read_b128 v[200:203], v173 offset:17408
	ds_read_b128 v[204:207], v173 offset:18432
	ds_read_b128 v[208:211], v173 offset:19456
	ds_read_b128 v[212:215], v173 offset:20480
	ds_read_b128 v[216:219], v173 offset:21504
	ds_read_b128 v[220:223], v173 offset:22528
	ds_read_b128 v[224:227], v173 offset:23552
	global_load_lds_dwordx4 v[228:229], off
	s_add_i32 m0, s21, 0x12000
	s_add_u32 s12, s16, 0x44000
	v_lshl_add_u64 v[230:231], s[16:17], 0, v[130:131]
	s_addc_u32 s13, s17, 0
	global_load_lds_dwordx4 v[230:231], off
	s_add_i32 m0, s21, 0x14000
	v_lshl_add_u64 v[232:233], s[12:13], 0, v[134:135]
	global_load_lds_dwordx4 v[232:233], off
	s_add_i32 m0, s21, 0x16000
	v_lshl_add_u64 v[232:233], s[12:13], 0, v[130:131]
	global_load_lds_dwordx4 v[232:233], off
	s_mov_b32 m0, s23
	v_lshl_add_u64 v[232:233], s[18:19], 0, v[152:153]
	global_load_lds_dwordx4 v[232:233], off
	s_mov_b32 m0, s24
	v_lshl_add_u64 v[234:235], s[18:19], 0, v[132:133]
	global_load_lds_dwordx4 v[234:235], off
	s_waitcnt vmcnt(8)
	s_waitcnt lgkmcnt(0)
	s_setprio 1
	s_barrier
; #define PG8_STAGE(bufoff, gbase, voff) do { _Pragma("unroll") for (int _i = 0; _i < 2; ++_i) \
;         __builtin_amdgcn_global_load_lds((const unsigned*)((const char*)(gbase) + (voff)[_i]), (LAS unsigned*)(lds + (bufoff) + ldsw + _i * 8192), 16, 0, 0); } while (0)
; #define PG8_LDA(dst, b, h) do { _Pragma("unroll") for (int m = 0; m < 4; ++m) _Pragma("unroll") for (int k = 0; k < 2; ++k) dst[m][k] = *(const LAS bf16x8*)(lds + PG8_SA(b, h) + aoff + m * 2048 + k * 1024); } while (0)
; #define PG8_LDB(dst, b, h) do { _Pragma("unroll") for (int n = 0; n < 2; ++n) _Pragma("unroll") for (int k = 0; k < 2; ++k) dst[n][k] = *(const LAS bf16x8*)(lds + PG8_SB(b, h) + boff + n * 2048 + k * 1024); } while (0)
; #define PG8_MMA(ai, bj, At, Bt) do { __builtin_amdgcn_s_setprio(1); _Pragma("unroll") for (int m = 0; m < 4; ++m) _Pragma("unroll") for (int n = 0; n < 2; ++n) _Pragma("unroll") for (int k = 0; k < 2; ++k) \
;         acc[ai][bj][m][n] = __builtin_amdgcn_mfma_f32_16x16x32_bf16(Bt[n][k], At[m][k], acc[ai][bj][m][n], 0, 0, 0); __builtin_amdgcn_s_setprio(0); } while (0)
; #define PG8_WAIT_V(n) asm volatile("s_waitcnt vmcnt(" #n ")" ::: "memory")
; #define PG8_WAIT_L(n) asm volatile("s_waitcnt lgkmcnt(" #n ")" ::: "memory")
; #define PG8_BAR __builtin_amdgcn_s_barrier()
; #define PG8_SCHED __builtin_amdgcn_sched_barrier(0)
; template <class Epi, bool ALIGN_EPI = PG8_ALIGN, bool SP2 = PG8_SP2>
; __device__ __forceinline__ void gemm_phase(LAS uchar* lds, const Gemm g, const StaticOrder& S, const Epi& E) {
;     ...
;             PG8_WAIT_V(8); PG8_WAIT_L(0); PG8_BAR; PG8_MMA(1, 0, At, B0); PG8_MMA(1, 1, At, B1); PG8_BAR; PG8_SCHED;
;             PG8_LDB(B0, 1, 0); PG8_LDB(B1, 1, 1); PG8_SCHED; PG8_LDA(At, 1, 0); PG8_STAGE(PG8_SA(0, 1), a2 + hstepA, voffA);
;             PG8_WAIT_V(8); PG8_WAIT_L(0); PG8_BAR; PG8_MMA(0, 0, At, B0); PG8_MMA(0, 1, At, B1); PG8_BAR; PG8_SCHED;
	v_mfma_f32_16x16x32_bf16 v[62:65], v[160:163], v[196:199], 0
	v_mfma_f32_16x16x32_bf16 v[58:61], v[168:171], v[196:199], 0
	v_mfma_f32_16x16x32_bf16 v[54:57], v[160:163], v[204:207], 0
	v_mfma_f32_16x16x32_bf16 v[46:49], v[168:171], v[204:207], 0
	v_mfma_f32_16x16x32_bf16 v[38:41], v[160:163], v[212:215], 0
	v_mfma_f32_16x16x32_bf16 v[30:33], v[168:171], v[212:215], 0
	v_mfma_f32_16x16x32_bf16 v[22:25], v[160:163], v[220:223], 0
	v_mfma_f32_16x16x32_bf16 v[14:17], v[168:171], v[220:223], 0
	v_mfma_f32_16x16x32_bf16 v[62:65], v[164:167], v[200:203], v[62:65]
	v_mfma_f32_16x16x32_bf16 v[58:61], v[174:177], v[200:203], v[58:61]
	v_mfma_f32_16x16x32_bf16 v[54:57], v[164:167], v[208:211], v[54:57]
	v_mfma_f32_16x16x32_bf16 v[46:49], v[174:177], v[208:211], v[46:49]
	v_mfma_f32_16x16x32_bf16 v[38:41], v[164:167], v[216:219], v[38:41]
	v_mfma_f32_16x16x32_bf16 v[30:33], v[174:177], v[216:219], v[30:33]
	v_mfma_f32_16x16x32_bf16 v[22:25], v[164:167], v[224:227], v[22:25]
	v_mfma_f32_16x16x32_bf16 v[14:17], v[174:177], v[224:227], v[14:17]
	v_mfma_f32_16x16x32_bf16 v[50:53], v[178:181], v[196:199], 0
	v_mfma_f32_16x16x32_bf16 v[42:45], v[188:191], v[196:199], 0
	v_mfma_f32_16x16x32_bf16 v[34:37], v[178:181], v[204:207], 0
	v_mfma_f32_16x16x32_bf16 v[26:29], v[188:191], v[204:207], 0
	v_mfma_f32_16x16x32_bf16 v[18:21], v[178:181], v[212:215], 0
	v_mfma_f32_16x16x32_bf16 v[10:13], v[188:191], v[212:215], 0
	v_mfma_f32_16x16x32_bf16 v[6:9], v[178:181], v[220:223], 0
	v_mfma_f32_16x16x32_bf16 v[2:5], v[188:191], v[220:223], 0
	v_mfma_f32_16x16x32_bf16 v[50:53], v[184:187], v[200:203], v[50:53]
	v_mfma_f32_16x16x32_bf16 v[42:45], v[192:195], v[200:203], v[42:45]
	v_mfma_f32_16x16x32_bf16 v[34:37], v[184:187], v[208:211], v[34:37]
	v_mfma_f32_16x16x32_bf16 v[26:29], v[192:195], v[208:211], v[26:29]
	v_mfma_f32_16x16x32_bf16 v[18:21], v[184:187], v[216:219], v[18:21]
	v_mfma_f32_16x16x32_bf16 v[10:13], v[192:195], v[216:219], v[10:13]
	v_mfma_f32_16x16x32_bf16 v[6:9], v[184:187], v[224:227], v[6:9]
	v_mfma_f32_16x16x32_bf16 v[2:5], v[192:195], v[224:227], v[2:5]
	s_barrier
	s_setprio 0
	v_add_u32_e32 v174, 0x18000, v139
	v_add_u32_e32 v192, 0x1c000, v139
	ds_read_b128 v[160:163], v174
	ds_read_b128 v[164:167], v174 offset:1024
	ds_read_b128 v[168:171], v174 offset:2048
	ds_read_b128 v[174:177], v174 offset:3072
	ds_read_b128 v[178:181], v192
	ds_read_b128 v[184:187], v192 offset:1024
	ds_read_b128 v[188:191], v192 offset:2048
	ds_read_b128 v[192:195], v192 offset:3072
	s_add_u32 s12, s18, 0x44000
	s_addc_u32 s13, s19, 0
	s_mov_b32 m0, s25
	v_lshl_add_u64 v[236:237], s[12:13], 0, v[152:153]
	ds_read_b128 v[196:199], v173 offset:32768
	ds_read_b128 v[200:203], v173 offset:33792
	ds_read_b128 v[204:207], v173 offset:34816
	ds_read_b128 v[208:211], v173 offset:35840
	ds_read_b128 v[212:215], v173 offset:36864
	ds_read_b128 v[216:219], v173 offset:37888
	ds_read_b128 v[220:223], v173 offset:38912
	ds_read_b128 v[224:227], v173 offset:39936
	global_load_lds_dwordx4 v[236:237], off
	s_mov_b32 m0, s26
	v_lshl_add_u64 v[236:237], s[12:13], 0, v[132:133]
	global_load_lds_dwordx4 v[236:237], off
	s_waitcnt vmcnt(8)
	s_waitcnt lgkmcnt(0)
	s_setprio 1
	s_barrier
	v_mfma_f32_16x16x32_bf16 v[126:129], v[160:163], v[196:199], v[126:129]
	v_mfma_f32_16x16x32_bf16 v[122:125], v[168:171], v[196:199], v[122:125]
	v_mfma_f32_16x16x32_bf16 v[118:121], v[160:163], v[204:207], v[118:121]
	v_mfma_f32_16x16x32_bf16 v[110:113], v[168:171], v[204:207], v[110:113]
	v_mfma_f32_16x16x32_bf16 v[102:105], v[160:163], v[212:215], v[102:105]
	v_mfma_f32_16x16x32_bf16 v[94:97], v[168:171], v[212:215], v[94:97]
	v_mfma_f32_16x16x32_bf16 v[86:89], v[160:163], v[220:223], v[86:89]
	v_mfma_f32_16x16x32_bf16 v[78:81], v[168:171], v[220:223], v[78:81]
	v_mfma_f32_16x16x32_bf16 v[126:129], v[164:167], v[200:203], v[126:129]
	v_mfma_f32_16x16x32_bf16 v[122:125], v[174:177], v[200:203], v[122:125]
	v_mfma_f32_16x16x32_bf16 v[118:121], v[164:167], v[208:211], v[118:121]
	v_mfma_f32_16x16x32_bf16 v[110:113], v[174:177], v[208:211], v[110:113]
	v_mfma_f32_16x16x32_bf16 v[102:105], v[164:167], v[216:219], v[102:105]
	v_mfma_f32_16x16x32_bf16 v[94:97], v[174:177], v[216:219], v[94:97]
	v_mfma_f32_16x16x32_bf16 v[86:89], v[164:167], v[224:227], v[86:89]
	v_mfma_f32_16x16x32_bf16 v[78:81], v[174:177], v[224:227], v[78:81]
	v_mfma_f32_16x16x32_bf16 v[114:117], v[178:181], v[196:199], v[114:117]
	v_mfma_f32_16x16x32_bf16 v[106:109], v[188:191], v[196:199], v[106:109]
	v_mfma_f32_16x16x32_bf16 v[98:101], v[178:181], v[204:207], v[98:101]
	v_mfma_f32_16x16x32_bf16 v[90:93], v[188:191], v[204:207], v[90:93]
	v_mfma_f32_16x16x32_bf16 v[82:85], v[178:181], v[212:215], v[82:85]
	v_mfma_f32_16x16x32_bf16 v[74:77], v[188:191], v[212:215], v[74:77]
	v_mfma_f32_16x16x32_bf16 v[70:73], v[178:181], v[220:223], v[70:73]
	v_mfma_f32_16x16x32_bf16 v[66:69], v[188:191], v[220:223], v[66:69]
	v_mfma_f32_16x16x32_bf16 v[114:117], v[184:187], v[200:203], v[114:117]
	v_mfma_f32_16x16x32_bf16 v[106:109], v[192:195], v[200:203], v[106:109]
	v_mfma_f32_16x16x32_bf16 v[98:101], v[184:187], v[208:211], v[98:101]
	v_mfma_f32_16x16x32_bf16 v[90:93], v[192:195], v[208:211], v[90:93]
	v_mfma_f32_16x16x32_bf16 v[82:85], v[184:187], v[216:219], v[82:85]
	v_mfma_f32_16x16x32_bf16 v[74:77], v[192:195], v[216:219], v[74:77]
	v_mfma_f32_16x16x32_bf16 v[70:73], v[184:187], v[224:227], v[70:73]
	v_mfma_f32_16x16x32_bf16 v[66:69], v[192:195], v[224:227], v[66:69]
	s_barrier
; #define PG8_STAGE(bufoff, gbase, voff) do { _Pragma("unroll") for (int _i = 0; _i < 2; ++_i) \
;         __builtin_amdgcn_global_load_lds((const unsigned*)((const char*)(gbase) + (voff)[_i]), (LAS unsigned*)(lds + (bufoff) + ldsw + _i * 8192), 16, 0, 0); } while (0)
; #define PG8_LDA(dst, b, h) do { _Pragma("unroll") for (int m = 0; m < 4; ++m) _Pragma("unroll") for (int k = 0; k < 2; ++k) dst[m][k] = *(const LAS bf16x8*)(lds + PG8_SA(b, h) + aoff + m * 2048 + k * 1024); } while (0)
; #define PG8_LDB(dst, b, h) do { _Pragma("unroll") for (int n = 0; n < 2; ++n) _Pragma("unroll") for (int k = 0; k < 2; ++k) dst[n][k] = *(const LAS bf16x8*)(lds + PG8_SB(b, h) + boff + n * 2048 + k * 1024); } while (0)
; #define PG8_MMA(ai, bj, At, Bt) do { __builtin_amdgcn_s_setprio(1); _Pragma("unroll") for (int m = 0; m < 4; ++m) _Pragma("unroll") for (int n = 0; n < 2; ++n) _Pragma("unroll") for (int k = 0; k < 2; ++k) \
;         acc[ai][bj][m][n] = __builtin_amdgcn_mfma_f32_16x16x32_bf16(Bt[n][k], At[m][k], acc[ai][bj][m][n], 0, 0, 0); __builtin_amdgcn_s_setprio(0); } while (0)
; #define PG8_WAIT_V(n) asm volatile("s_waitcnt vmcnt(" #n ")" ::: "memory")
; #define PG8_WAIT_L(n) asm volatile("s_waitcnt lgkmcnt(" #n ")" ::: "memory")
; #define PG8_BAR __builtin_amdgcn_s_barrier()
; #define PG8_SCHED __builtin_amdgcn_sched_barrier(0)
; template <class Epi, bool ALIGN_EPI = PG8_ALIGN, bool SP2 = PG8_SP2>
; __device__ __forceinline__ void gemm_phase(LAS uchar* lds, const Gemm g, const StaticOrder& S, const Epi& E) {
;     ...
;             const bool last = (t == nt - 2);
;             const char* a1 = cA + (size_t)(t + 1) * kstep;
;             const char* a2 = last ? nA : cA + (size_t)(t + 2) * kstep; const char* b2 = last ? nB : cB + (size_t)(t + 2) * kstep;
;             const char* a3 = a2 + kstep; const char* b3 = b2 + kstep;
;             if constexpr (SP2) {
;             PG8_LDB(B0, 0, 0); PG8_LDB(B1, 0, 1); PG8_SCHED; PG8_LDA(At, 0, 0); PG8_STAGE(PG8_SA(1, 1), a1 + hstepA, voffA);
;             PG8_WAIT_V(8); PG8_WAIT_L(0); PG8_BAR; PG8_MMA(0, 0, At, B0); PG8_MMA(0, 1, At, B1); PG8_BAR; PG8_SCHED;
;     ...
;             PG8_LDA(At, 1, 1); PG8_STAGE(PG8_SB(1, 0), b3, voffB); PG8_STAGE(PG8_SB(1, 1), b3 + hstepB, voffB); PG8_STAGE(PG8_SA(1, 0), a3, voffA);
;             PG8_WAIT_V(8); PG8_WAIT_L(0); PG8_BAR; PG8_MMA(1, 0, At, B0); PG8_MMA(1, 1, At, B1); PG8_BAR; PG8_SCHED;
	s_setprio 0
	v_lshl_add_u64 v[228:229], v[228:229], 0, s[84:85]
	s_add_i32 m0, s21, 0x18000
	ds_read_b128 v[196:199], v173 offset:49152
	ds_read_b128 v[200:203], v173 offset:50176
	ds_read_b128 v[204:207], v173 offset:51200
	ds_read_b128 v[208:211], v173 offset:52224
	ds_read_b128 v[212:215], v173 offset:53248
	ds_read_b128 v[216:219], v173 offset:54272
	ds_read_b128 v[220:223], v173 offset:55296
	ds_read_b128 v[224:227], v173 offset:56320
	global_load_lds_dwordx4 v[228:229], off
	s_add_i32 m0, s21, 0x1a000
	s_add_u32 s12, s16, 0x44080
	v_lshl_add_u64 v[228:229], v[230:231], 0, s[84:85]
	s_addc_u32 s13, s17, 0
	global_load_lds_dwordx4 v[228:229], off
	s_add_i32 m0, s21, 0x1c000
	v_lshl_add_u64 v[228:229], s[12:13], 0, v[134:135]
	global_load_lds_dwordx4 v[228:229], off
	s_add_i32 m0, s21, 0x1e000
	v_lshl_add_u64 v[228:229], s[12:13], 0, v[130:131]
	global_load_lds_dwordx4 v[228:229], off
	s_mov_b32 m0, s27
	v_lshl_add_u64 v[228:229], v[232:233], 0, s[84:85]
	global_load_lds_dwordx4 v[228:229], off
	s_mov_b32 m0, s28
	v_lshl_add_u64 v[228:229], v[234:235], 0, s[84:85]
	global_load_lds_dwordx4 v[228:229], off
	s_waitcnt vmcnt(8)
	s_waitcnt lgkmcnt(0)
	s_setprio 1
	s_barrier
	v_mfma_f32_16x16x32_bf16 v[62:65], v[160:163], v[196:199], v[62:65]
	v_mfma_f32_16x16x32_bf16 v[58:61], v[168:171], v[196:199], v[58:61]
	v_mfma_f32_16x16x32_bf16 v[54:57], v[160:163], v[204:207], v[54:57]
	v_mfma_f32_16x16x32_bf16 v[46:49], v[168:171], v[204:207], v[46:49]
	v_mfma_f32_16x16x32_bf16 v[38:41], v[160:163], v[212:215], v[38:41]
	v_mfma_f32_16x16x32_bf16 v[30:33], v[168:171], v[212:215], v[30:33]
	v_mfma_f32_16x16x32_bf16 v[22:25], v[160:163], v[220:223], v[22:25]
	v_mfma_f32_16x16x32_bf16 v[14:17], v[168:171], v[220:223], v[14:17]
	v_mfma_f32_16x16x32_bf16 v[62:65], v[164:167], v[200:203], v[62:65]
	v_mfma_f32_16x16x32_bf16 v[58:61], v[174:177], v[200:203], v[58:61]
	v_mfma_f32_16x16x32_bf16 v[54:57], v[164:167], v[208:211], v[54:57]
	v_mfma_f32_16x16x32_bf16 v[46:49], v[174:177], v[208:211], v[46:49]
	v_mfma_f32_16x16x32_bf16 v[38:41], v[164:167], v[216:219], v[38:41]
	v_mfma_f32_16x16x32_bf16 v[30:33], v[174:177], v[216:219], v[30:33]
	v_mfma_f32_16x16x32_bf16 v[22:25], v[164:167], v[224:227], v[22:25]
	v_mfma_f32_16x16x32_bf16 v[14:17], v[174:177], v[224:227], v[14:17]
	v_mfma_f32_16x16x32_bf16 v[50:53], v[178:181], v[196:199], v[50:53]
	v_mfma_f32_16x16x32_bf16 v[42:45], v[188:191], v[196:199], v[42:45]
	v_mfma_f32_16x16x32_bf16 v[34:37], v[178:181], v[204:207], v[34:37]
	v_mfma_f32_16x16x32_bf16 v[26:29], v[188:191], v[204:207], v[26:29]
	v_mfma_f32_16x16x32_bf16 v[18:21], v[178:181], v[212:215], v[18:21]
	v_mfma_f32_16x16x32_bf16 v[10:13], v[188:191], v[212:215], v[10:13]
	v_mfma_f32_16x16x32_bf16 v[6:9], v[178:181], v[220:223], v[6:9]
	v_mfma_f32_16x16x32_bf16 v[2:5], v[188:191], v[220:223], v[2:5]
	v_mfma_f32_16x16x32_bf16 v[50:53], v[184:187], v[200:203], v[50:53]
	v_mfma_f32_16x16x32_bf16 v[42:45], v[192:195], v[200:203], v[42:45]
	v_mfma_f32_16x16x32_bf16 v[34:37], v[184:187], v[208:211], v[34:37]
	v_mfma_f32_16x16x32_bf16 v[26:29], v[192:195], v[208:211], v[26:29]
	v_mfma_f32_16x16x32_bf16 v[18:21], v[184:187], v[216:219], v[18:21]
	v_mfma_f32_16x16x32_bf16 v[10:13], v[192:195], v[216:219], v[10:13]
	v_mfma_f32_16x16x32_bf16 v[6:9], v[184:187], v[224:227], v[6:9]
	v_mfma_f32_16x16x32_bf16 v[2:5], v[192:195], v[224:227], v[2:5]
	s_barrier
	s_setprio 0
	s_add_i32 s38, s38, 2
	s_add_u32 s36, s36, 0x100
	s_addc_u32 s37, s37, 0
	s_cmp_gt_u32 s38, 13
	s_mov_b64 s[12:13], s[14:15]
.LBB0_669:
	s_add_u32 s14, s12, 0x100
	s_addc_u32 s15, s13, 0
	s_cmp_eq_u32 s38, 12
	s_cselect_b32 s19, s5, s15
	s_cselect_b32 s18, s4, s14
	s_cselect_b32 s17, s11, s37
	s_cselect_b32 s16, s10, s36
	v_add_u32_e32 v174, 0x10000, v139
	v_add_u32_e32 v192, 0x14000, v139
	ds_read_b128 v[160:163], v174
	ds_read_b128 v[164:167], v174 offset:1024
	ds_read_b128 v[168:171], v174 offset:2048
	ds_read_b128 v[174:177], v174 offset:3072
	ds_read_b128 v[178:181], v192
	ds_read_b128 v[184:187], v192 offset:1024
	ds_read_b128 v[188:191], v192 offset:2048
	ds_read_b128 v[192:195], v192 offset:3072
	v_lshl_add_u64 v[228:229], s[12:13], 0, v[156:157]
	s_add_i32 m0, s23, 0xc000
	ds_read_b128 v[196:199], v173
	ds_read_b128 v[200:203], v173 offset:1024
	ds_read_b128 v[204:207], v173 offset:2048
	ds_read_b128 v[208:211], v173 offset:3072
	ds_read_b128 v[212:215], v173 offset:4096
	ds_read_b128 v[216:219], v173 offset:5120
	ds_read_b128 v[220:223], v173 offset:6144
	ds_read_b128 v[224:227], v173 offset:7168
	global_load_lds_dwordx4 v[228:229], off
	s_add_i32 m0, s23, 0xe000
	v_lshl_add_u64 v[228:229], s[12:13], 0, v[158:159]
	global_load_lds_dwordx4 v[228:229], off
	s_waitcnt vmcnt(8)
	s_waitcnt lgkmcnt(0)
	s_setprio 1
	s_barrier
; #define PG8_STAGE(bufoff, gbase, voff) do { _Pragma("unroll") for (int _i = 0; _i < 2; ++_i) \
;         __builtin_amdgcn_global_load_lds((const unsigned*)((const char*)(gbase) + (voff)[_i]), (LAS unsigned*)(lds + (bufoff) + ldsw + _i * 8192), 16, 0, 0); } while (0)
; #define PG8_LDA(dst, b, h) do { _Pragma("unroll") for (int m = 0; m < 4; ++m) _Pragma("unroll") for (int k = 0; k < 2; ++k) dst[m][k] = *(const LAS bf16x8*)(lds + PG8_SA(b, h) + aoff + m * 2048 + k * 1024); } while (0)
; #define PG8_MMA(ai, bj, At, Bt) do { __builtin_amdgcn_s_setprio(1); _Pragma("unroll") for (int m = 0; m < 4; ++m) _Pragma("unroll") for (int n = 0; n < 2; ++n) _Pragma("unroll") for (int k = 0; k < 2; ++k) \
;         acc[ai][bj][m][n] = __builtin_amdgcn_mfma_f32_16x16x32_bf16(Bt[n][k], At[m][k], acc[ai][bj][m][n], 0, 0, 0); __builtin_amdgcn_s_setprio(0); } while (0)
; #define PG8_WAIT_V(n) asm volatile("s_waitcnt vmcnt(" #n ")" ::: "memory")
; #define PG8_WAIT_L(n) asm volatile("s_waitcnt lgkmcnt(" #n ")" ::: "memory")
; #define PG8_BAR __builtin_amdgcn_s_barrier()
; #define PG8_SCHED __builtin_amdgcn_sched_barrier(0)
; template <class Epi, bool ALIGN_EPI = PG8_ALIGN, bool SP2 = PG8_SP2>
; __device__ __forceinline__ void gemm_phase(LAS uchar* lds, const Gemm g, const StaticOrder& S, const Epi& E) {
;     ...
;             PG8_WAIT_V(8); PG8_WAIT_L(0); PG8_BAR; PG8_MMA(0, 0, At, B0); PG8_MMA(0, 1, At, B1); PG8_BAR; PG8_SCHED;
;             PG8_LDA(At, 0, 1); PG8_STAGE(PG8_SB(0, 0), b2, voffB); PG8_STAGE(PG8_SB(0, 1), b2 + hstepB, voffB); PG8_STAGE(PG8_SA(0, 0), a2, voffA);
;             PG8_WAIT_V(8); PG8_WAIT_L(0); PG8_BAR; PG8_MMA(1, 0, At, B0); PG8_MMA(1, 1, At, B1); PG8_BAR; PG8_SCHED;
	v_mfma_f32_16x16x32_bf16 v[126:129], v[160:163], v[196:199], v[126:129]
	v_mfma_f32_16x16x32_bf16 v[122:125], v[168:171], v[196:199], v[122:125]
	v_mfma_f32_16x16x32_bf16 v[118:121], v[160:163], v[204:207], v[118:121]
	v_mfma_f32_16x16x32_bf16 v[110:113], v[168:171], v[204:207], v[110:113]
	v_mfma_f32_16x16x32_bf16 v[102:105], v[160:163], v[212:215], v[102:105]
	v_mfma_f32_16x16x32_bf16 v[94:97], v[168:171], v[212:215], v[94:97]
	v_mfma_f32_16x16x32_bf16 v[86:89], v[160:163], v[220:223], v[86:89]
	v_mfma_f32_16x16x32_bf16 v[78:81], v[168:171], v[220:223], v[78:81]
	v_mfma_f32_16x16x32_bf16 v[126:129], v[164:167], v[200:203], v[126:129]
	v_mfma_f32_16x16x32_bf16 v[122:125], v[174:177], v[200:203], v[122:125]
	v_mfma_f32_16x16x32_bf16 v[118:121], v[164:167], v[208:211], v[118:121]
	v_mfma_f32_16x16x32_bf16 v[110:113], v[174:177], v[208:211], v[110:113]
	v_mfma_f32_16x16x32_bf16 v[102:105], v[164:167], v[216:219], v[102:105]
	v_mfma_f32_16x16x32_bf16 v[94:97], v[174:177], v[216:219], v[94:97]
	v_mfma_f32_16x16x32_bf16 v[86:89], v[164:167], v[224:227], v[86:89]
	v_mfma_f32_16x16x32_bf16 v[78:81], v[174:177], v[224:227], v[78:81]
	v_mfma_f32_16x16x32_bf16 v[114:117], v[178:181], v[196:199], v[114:117]
	v_mfma_f32_16x16x32_bf16 v[106:109], v[188:191], v[196:199], v[106:109]
	v_mfma_f32_16x16x32_bf16 v[98:101], v[178:181], v[204:207], v[98:101]
	v_mfma_f32_16x16x32_bf16 v[90:93], v[188:191], v[204:207], v[90:93]
	v_mfma_f32_16x16x32_bf16 v[82:85], v[178:181], v[212:215], v[82:85]
	v_mfma_f32_16x16x32_bf16 v[74:77], v[188:191], v[212:215], v[74:77]
	v_mfma_f32_16x16x32_bf16 v[70:73], v[178:181], v[220:223], v[70:73]
	v_mfma_f32_16x16x32_bf16 v[66:69], v[188:191], v[220:223], v[66:69]
	v_mfma_f32_16x16x32_bf16 v[114:117], v[184:187], v[200:203], v[114:117]
	v_mfma_f32_16x16x32_bf16 v[106:109], v[192:195], v[200:203], v[106:109]
	v_mfma_f32_16x16x32_bf16 v[98:101], v[184:187], v[208:211], v[98:101]
	v_mfma_f32_16x16x32_bf16 v[90:93], v[192:195], v[208:211], v[90:93]
	v_mfma_f32_16x16x32_bf16 v[82:85], v[184:187], v[216:219], v[82:85]
	v_mfma_f32_16x16x32_bf16 v[74:77], v[192:195], v[216:219], v[74:77]
	v_mfma_f32_16x16x32_bf16 v[70:73], v[184:187], v[224:227], v[70:73]
	v_mfma_f32_16x16x32_bf16 v[66:69], v[192:195], v[224:227], v[66:69]
	s_barrier
	s_setprio 0
	v_lshl_add_u64 v[228:229], s[16:17], 0, v[134:135]
	s_add_i32 m0, s21, 0x10000
	ds_read_b128 v[196:199], v173 offset:16384
	ds_read_b128 v[200:203], v173 offset:17408
	ds_read_b128 v[204:207], v173 offset:18432
	ds_read_b128 v[208:211], v173 offset:19456
	ds_read_b128 v[212:215], v173 offset:20480
	ds_read_b128 v[216:219], v173 offset:21504
	ds_read_b128 v[220:223], v173 offset:22528
	ds_read_b128 v[224:227], v173 offset:23552
	global_load_lds_dwordx4 v[228:229], off
	s_add_i32 m0, s21, 0x12000
	s_add_u32 s12, s16, 0x44000
	v_lshl_add_u64 v[230:231], s[16:17], 0, v[130:131]
	s_addc_u32 s13, s17, 0
	global_load_lds_dwordx4 v[230:231], off
	s_add_i32 m0, s21, 0x14000
	v_lshl_add_u64 v[232:233], s[12:13], 0, v[134:135]
	global_load_lds_dwordx4 v[232:233], off
	s_add_i32 m0, s21, 0x16000
	v_lshl_add_u64 v[232:233], s[12:13], 0, v[130:131]
	global_load_lds_dwordx4 v[232:233], off
	s_mov_b32 m0, s23
	v_lshl_add_u64 v[232:233], s[18:19], 0, v[152:153]
	global_load_lds_dwordx4 v[232:233], off
	s_mov_b32 m0, s24
	v_lshl_add_u64 v[234:235], s[18:19], 0, v[132:133]
	global_load_lds_dwordx4 v[234:235], off
	s_waitcnt vmcnt(8)
	s_waitcnt lgkmcnt(0)
	s_setprio 1
	s_barrier
	v_mfma_f32_16x16x32_bf16 v[62:65], v[160:163], v[196:199], v[62:65]
	v_mfma_f32_16x16x32_bf16 v[58:61], v[168:171], v[196:199], v[58:61]
	v_mfma_f32_16x16x32_bf16 v[54:57], v[160:163], v[204:207], v[54:57]
	v_mfma_f32_16x16x32_bf16 v[46:49], v[168:171], v[204:207], v[46:49]
	v_mfma_f32_16x16x32_bf16 v[38:41], v[160:163], v[212:215], v[38:41]
	v_mfma_f32_16x16x32_bf16 v[30:33], v[168:171], v[212:215], v[30:33]
	v_mfma_f32_16x16x32_bf16 v[22:25], v[160:163], v[220:223], v[22:25]
	v_mfma_f32_16x16x32_bf16 v[14:17], v[168:171], v[220:223], v[14:17]
	v_mfma_f32_16x16x32_bf16 v[62:65], v[164:167], v[200:203], v[62:65]
	v_mfma_f32_16x16x32_bf16 v[58:61], v[174:177], v[200:203], v[58:61]
	v_mfma_f32_16x16x32_bf16 v[54:57], v[164:167], v[208:211], v[54:57]
	v_mfma_f32_16x16x32_bf16 v[46:49], v[174:177], v[208:211], v[46:49]
	v_mfma_f32_16x16x32_bf16 v[38:41], v[164:167], v[216:219], v[38:41]
	v_mfma_f32_16x16x32_bf16 v[30:33], v[174:177], v[216:219], v[30:33]
	v_mfma_f32_16x16x32_bf16 v[22:25], v[164:167], v[224:227], v[22:25]
	v_mfma_f32_16x16x32_bf16 v[14:17], v[174:177], v[224:227], v[14:17]
	v_mfma_f32_16x16x32_bf16 v[50:53], v[178:181], v[196:199], v[50:53]
	v_mfma_f32_16x16x32_bf16 v[42:45], v[188:191], v[196:199], v[42:45]
	v_mfma_f32_16x16x32_bf16 v[34:37], v[178:181], v[204:207], v[34:37]
	v_mfma_f32_16x16x32_bf16 v[26:29], v[188:191], v[204:207], v[26:29]
	v_mfma_f32_16x16x32_bf16 v[18:21], v[178:181], v[212:215], v[18:21]
	v_mfma_f32_16x16x32_bf16 v[10:13], v[188:191], v[212:215], v[10:13]
	v_mfma_f32_16x16x32_bf16 v[6:9], v[178:181], v[220:223], v[6:9]
	v_mfma_f32_16x16x32_bf16 v[2:5], v[188:191], v[220:223], v[2:5]
	v_mfma_f32_16x16x32_bf16 v[50:53], v[184:187], v[200:203], v[50:53]
	v_mfma_f32_16x16x32_bf16 v[42:45], v[192:195], v[200:203], v[42:45]
	v_mfma_f32_16x16x32_bf16 v[34:37], v[184:187], v[208:211], v[34:37]
	v_mfma_f32_16x16x32_bf16 v[26:29], v[192:195], v[208:211], v[26:29]
	v_mfma_f32_16x16x32_bf16 v[18:21], v[184:187], v[216:219], v[18:21]
	v_mfma_f32_16x16x32_bf16 v[10:13], v[192:195], v[216:219], v[10:13]
	v_mfma_f32_16x16x32_bf16 v[6:9], v[184:187], v[224:227], v[6:9]
	v_mfma_f32_16x16x32_bf16 v[2:5], v[192:195], v[224:227], v[2:5]
	s_barrier
; #define PG8_STAGE(bufoff, gbase, voff) do { _Pragma("unroll") for (int _i = 0; _i < 2; ++_i) \
;         __builtin_amdgcn_global_load_lds((const unsigned*)((const char*)(gbase) + (voff)[_i]), (LAS unsigned*)(lds + (bufoff) + ldsw + _i * 8192), 16, 0, 0); } while (0)
; #define PG8_LDA(dst, b, h) do { _Pragma("unroll") for (int m = 0; m < 4; ++m) _Pragma("unroll") for (int k = 0; k < 2; ++k) dst[m][k] = *(const LAS bf16x8*)(lds + PG8_SA(b, h) + aoff + m * 2048 + k * 1024); } while (0)
; #define PG8_LDB(dst, b, h) do { _Pragma("unroll") for (int n = 0; n < 2; ++n) _Pragma("unroll") for (int k = 0; k < 2; ++k) dst[n][k] = *(const LAS bf16x8*)(lds + PG8_SB(b, h) + boff + n * 2048 + k * 1024); } while (0)
; #define PG8_MMA(ai, bj, At, Bt) do { __builtin_amdgcn_s_setprio(1); _Pragma("unroll") for (int m = 0; m < 4; ++m) _Pragma("unroll") for (int n = 0; n < 2; ++n) _Pragma("unroll") for (int k = 0; k < 2; ++k) \
;         acc[ai][bj][m][n] = __builtin_amdgcn_mfma_f32_16x16x32_bf16(Bt[n][k], At[m][k], acc[ai][bj][m][n], 0, 0, 0); __builtin_amdgcn_s_setprio(0); } while (0)
; #define PG8_WAIT_V(n) asm volatile("s_waitcnt vmcnt(" #n ")" ::: "memory")
; #define PG8_WAIT_L(n) asm volatile("s_waitcnt lgkmcnt(" #n ")" ::: "memory")
; #define PG8_BAR __builtin_amdgcn_s_barrier()
; #define PG8_SCHED __builtin_amdgcn_sched_barrier(0)
; template <class Epi, bool ALIGN_EPI = PG8_ALIGN, bool SP2 = PG8_SP2>
; __device__ __forceinline__ void gemm_phase(LAS uchar* lds, const Gemm g, const StaticOrder& S, const Epi& E) {
;     ...
;             PG8_LDB(B0, 1, 0); PG8_LDB(B1, 1, 1); PG8_SCHED; PG8_LDA(At, 1, 0); PG8_STAGE(PG8_SA(0, 1), a2 + hstepA, voffA);
;             PG8_WAIT_V(8); PG8_WAIT_L(0); PG8_BAR; PG8_MMA(0, 0, At, B0); PG8_MMA(0, 1, At, B1); PG8_BAR; PG8_SCHED;
;             PG8_LDA(At, 1, 1); PG8_STAGE(PG8_SB(1, 0), b3, voffB); PG8_STAGE(PG8_SB(1, 1), b3 + hstepB, voffB); PG8_STAGE(PG8_SA(1, 0), a3, voffA);
;             PG8_WAIT_V(8); PG8_WAIT_L(0); PG8_BAR; PG8_MMA(1, 0, At, B0); PG8_MMA(1, 1, At, B1); PG8_BAR; PG8_SCHED;
;     ...
;         if constexpr (ALIGN_EPI) { if (wr == 0) PG8_BAR; }
	s_setprio 0
	v_add_u32_e32 v174, 0x18000, v139
	v_add_u32_e32 v192, 0x1c000, v139
	ds_read_b128 v[160:163], v174
	ds_read_b128 v[164:167], v174 offset:1024
	ds_read_b128 v[168:171], v174 offset:2048
	ds_read_b128 v[174:177], v174 offset:3072
	ds_read_b128 v[178:181], v192
	ds_read_b128 v[184:187], v192 offset:1024
	ds_read_b128 v[188:191], v192 offset:2048
	ds_read_b128 v[192:195], v192 offset:3072
	s_add_u32 s12, s18, 0x44000
	s_addc_u32 s13, s19, 0
	s_mov_b32 m0, s25
	v_lshl_add_u64 v[236:237], s[12:13], 0, v[152:153]
	ds_read_b128 v[196:199], v173 offset:32768
	ds_read_b128 v[200:203], v173 offset:33792
	ds_read_b128 v[204:207], v173 offset:34816
	ds_read_b128 v[208:211], v173 offset:35840
	ds_read_b128 v[212:215], v173 offset:36864
	ds_read_b128 v[216:219], v173 offset:37888
	ds_read_b128 v[220:223], v173 offset:38912
	ds_read_b128 v[224:227], v173 offset:39936
	global_load_lds_dwordx4 v[236:237], off
	s_mov_b32 m0, s26
	v_lshl_add_u64 v[236:237], s[12:13], 0, v[132:133]
	global_load_lds_dwordx4 v[236:237], off
	s_waitcnt vmcnt(8)
	s_waitcnt lgkmcnt(0)
	s_setprio 1
	s_barrier
	v_mfma_f32_16x16x32_bf16 v[126:129], v[160:163], v[196:199], v[126:129]
	v_mfma_f32_16x16x32_bf16 v[122:125], v[168:171], v[196:199], v[122:125]
	v_mfma_f32_16x16x32_bf16 v[118:121], v[160:163], v[204:207], v[118:121]
	v_mfma_f32_16x16x32_bf16 v[110:113], v[168:171], v[204:207], v[110:113]
	v_mfma_f32_16x16x32_bf16 v[102:105], v[160:163], v[212:215], v[102:105]
	v_mfma_f32_16x16x32_bf16 v[94:97], v[168:171], v[212:215], v[94:97]
	v_mfma_f32_16x16x32_bf16 v[86:89], v[160:163], v[220:223], v[86:89]
	v_mfma_f32_16x16x32_bf16 v[78:81], v[168:171], v[220:223], v[78:81]
	v_mfma_f32_16x16x32_bf16 v[126:129], v[164:167], v[200:203], v[126:129]
	v_mfma_f32_16x16x32_bf16 v[122:125], v[174:177], v[200:203], v[122:125]
	v_mfma_f32_16x16x32_bf16 v[118:121], v[164:167], v[208:211], v[118:121]
	v_mfma_f32_16x16x32_bf16 v[110:113], v[174:177], v[208:211], v[110:113]
	v_mfma_f32_16x16x32_bf16 v[102:105], v[164:167], v[216:219], v[102:105]
	v_mfma_f32_16x16x32_bf16 v[94:97], v[174:177], v[216:219], v[94:97]
	v_mfma_f32_16x16x32_bf16 v[86:89], v[164:167], v[224:227], v[86:89]
	v_mfma_f32_16x16x32_bf16 v[78:81], v[174:177], v[224:227], v[78:81]
	v_mfma_f32_16x16x32_bf16 v[114:117], v[178:181], v[196:199], v[114:117]
	v_mfma_f32_16x16x32_bf16 v[106:109], v[188:191], v[196:199], v[106:109]
	v_mfma_f32_16x16x32_bf16 v[98:101], v[178:181], v[204:207], v[98:101]
	v_mfma_f32_16x16x32_bf16 v[90:93], v[188:191], v[204:207], v[90:93]
	v_mfma_f32_16x16x32_bf16 v[82:85], v[178:181], v[212:215], v[82:85]
	v_mfma_f32_16x16x32_bf16 v[74:77], v[188:191], v[212:215], v[74:77]
	v_mfma_f32_16x16x32_bf16 v[70:73], v[178:181], v[220:223], v[70:73]
	v_mfma_f32_16x16x32_bf16 v[66:69], v[188:191], v[220:223], v[66:69]
	v_mfma_f32_16x16x32_bf16 v[114:117], v[184:187], v[200:203], v[114:117]
	v_mfma_f32_16x16x32_bf16 v[106:109], v[192:195], v[200:203], v[106:109]
	v_mfma_f32_16x16x32_bf16 v[98:101], v[184:187], v[208:211], v[98:101]
	v_mfma_f32_16x16x32_bf16 v[90:93], v[192:195], v[208:211], v[90:93]
	v_mfma_f32_16x16x32_bf16 v[82:85], v[184:187], v[216:219], v[82:85]
	v_mfma_f32_16x16x32_bf16 v[74:77], v[192:195], v[216:219], v[74:77]
	v_mfma_f32_16x16x32_bf16 v[70:73], v[184:187], v[224:227], v[70:73]
	v_mfma_f32_16x16x32_bf16 v[66:69], v[192:195], v[224:227], v[66:69]
	s_barrier
	s_setprio 0
	v_lshl_add_u64 v[228:229], v[228:229], 0, s[84:85]
	s_add_i32 m0, s21, 0x18000
	ds_read_b128 v[196:199], v173 offset:49152
	ds_read_b128 v[200:203], v173 offset:50176
	ds_read_b128 v[204:207], v173 offset:51200
	ds_read_b128 v[208:211], v173 offset:52224
	ds_read_b128 v[212:215], v173 offset:53248
	ds_read_b128 v[216:219], v173 offset:54272
	ds_read_b128 v[220:223], v173 offset:55296
	ds_read_b128 v[224:227], v173 offset:56320
	global_load_lds_dwordx4 v[228:229], off
	s_add_i32 m0, s21, 0x1a000
	s_add_u32 s12, s16, 0x44080
	v_lshl_add_u64 v[228:229], v[230:231], 0, s[84:85]
	s_addc_u32 s13, s17, 0
	global_load_lds_dwordx4 v[228:229], off
	s_add_i32 m0, s21, 0x1c000
	v_lshl_add_u64 v[228:229], s[12:13], 0, v[134:135]
	global_load_lds_dwordx4 v[228:229], off
	s_add_i32 m0, s21, 0x1e000
	v_lshl_add_u64 v[228:229], s[12:13], 0, v[130:131]
	global_load_lds_dwordx4 v[228:229], off
	s_mov_b32 m0, s27
	v_lshl_add_u64 v[228:229], v[232:233], 0, s[84:85]
	global_load_lds_dwordx4 v[228:229], off
	s_mov_b32 m0, s28
	v_lshl_add_u64 v[228:229], v[234:235], 0, s[84:85]
	global_load_lds_dwordx4 v[228:229], off
	s_waitcnt vmcnt(8)
	s_waitcnt lgkmcnt(0)
	s_setprio 1
	s_barrier
	v_mfma_f32_16x16x32_bf16 v[62:65], v[160:163], v[196:199], v[62:65]
	v_mfma_f32_16x16x32_bf16 v[58:61], v[168:171], v[196:199], v[58:61]
	v_mfma_f32_16x16x32_bf16 v[54:57], v[160:163], v[204:207], v[54:57]
	v_mfma_f32_16x16x32_bf16 v[46:49], v[168:171], v[204:207], v[46:49]
	v_mfma_f32_16x16x32_bf16 v[38:41], v[160:163], v[212:215], v[38:41]
	v_mfma_f32_16x16x32_bf16 v[30:33], v[168:171], v[212:215], v[30:33]
	v_mfma_f32_16x16x32_bf16 v[22:25], v[160:163], v[220:223], v[22:25]
	v_mfma_f32_16x16x32_bf16 v[14:17], v[168:171], v[220:223], v[14:17]
	v_mfma_f32_16x16x32_bf16 v[62:65], v[164:167], v[200:203], v[62:65]
	v_mfma_f32_16x16x32_bf16 v[58:61], v[174:177], v[200:203], v[58:61]
	v_mfma_f32_16x16x32_bf16 v[54:57], v[164:167], v[208:211], v[54:57]
	v_mfma_f32_16x16x32_bf16 v[46:49], v[174:177], v[208:211], v[46:49]
	v_mfma_f32_16x16x32_bf16 v[38:41], v[164:167], v[216:219], v[38:41]
	v_mfma_f32_16x16x32_bf16 v[30:33], v[174:177], v[216:219], v[30:33]
	v_mfma_f32_16x16x32_bf16 v[22:25], v[164:167], v[224:227], v[22:25]
	v_mfma_f32_16x16x32_bf16 v[14:17], v[174:177], v[224:227], v[14:17]
	v_mfma_f32_16x16x32_bf16 v[50:53], v[178:181], v[196:199], v[50:53]
	v_mfma_f32_16x16x32_bf16 v[42:45], v[188:191], v[196:199], v[42:45]
	v_mfma_f32_16x16x32_bf16 v[34:37], v[178:181], v[204:207], v[34:37]
	v_mfma_f32_16x16x32_bf16 v[26:29], v[188:191], v[204:207], v[26:29]
	v_mfma_f32_16x16x32_bf16 v[18:21], v[178:181], v[212:215], v[18:21]
	v_mfma_f32_16x16x32_bf16 v[10:13], v[188:191], v[212:215], v[10:13]
	v_mfma_f32_16x16x32_bf16 v[6:9], v[178:181], v[220:223], v[6:9]
	v_mfma_f32_16x16x32_bf16 v[2:5], v[188:191], v[220:223], v[2:5]
	v_mfma_f32_16x16x32_bf16 v[50:53], v[184:187], v[200:203], v[50:53]
	v_mfma_f32_16x16x32_bf16 v[42:45], v[192:195], v[200:203], v[42:45]
	v_mfma_f32_16x16x32_bf16 v[34:37], v[184:187], v[208:211], v[34:37]
	v_mfma_f32_16x16x32_bf16 v[26:29], v[192:195], v[208:211], v[26:29]
	v_mfma_f32_16x16x32_bf16 v[18:21], v[184:187], v[216:219], v[18:21]
	v_mfma_f32_16x16x32_bf16 v[10:13], v[192:195], v[216:219], v[10:13]
	v_mfma_f32_16x16x32_bf16 v[6:9], v[184:187], v[224:227], v[6:9]
	v_mfma_f32_16x16x32_bf16 v[2:5], v[192:195], v[224:227], v[2:5]
	s_barrier
	s_setprio 0
	s_add_i32 s38, s38, 2
	s_add_u32 s36, s36, 0x100
	s_addc_u32 s37, s37, 0
	s_cmp_gt_u32 s38, 13
	s_mov_b64 s[12:13], s[14:15]
	s_cbranch_scc0 .LBB0_669
	s_and_b64 vcc, exec, s[8:9]
	s_cbranch_vccz .LBB0_672
	s_barrier

; #define PG8_STAGE(bufoff, gbase, voff) do { _Pragma("unroll") for (int _i = 0; _i < 2; ++_i) \
;         __builtin_amdgcn_global_load_lds((const unsigned*)((const char*)(gbase) + (voff)[_i]), (LAS unsigned*)(lds + (bufoff) + ldsw + _i * 8192), 16, 0, 0); } while (0)
; #define PG8_LDA(dst, b, h) do { _Pragma("unroll") for (int m = 0; m < 4; ++m) _Pragma("unroll") for (int k = 0; k < 2; ++k) dst[m][k] = *(const LAS bf16x8*)(lds + PG8_SA(b, h) + aoff + m * 2048 + k * 1024); } while (0)
; #define PG8_LDB(dst, b, h) do { _Pragma("unroll") for (int n = 0; n < 2; ++n) _Pragma("unroll") for (int k = 0; k < 2; ++k) dst[n][k] = *(const LAS bf16x8*)(lds + PG8_SB(b, h) + boff + n * 2048 + k * 1024); } while (0)
; #define PG8_MMA(ai, bj, At, Bt) do { __builtin_amdgcn_s_setprio(1); _Pragma("unroll") for (int m = 0; m < 4; ++m) _Pragma("unroll") for (int n = 0; n < 2; ++n) _Pragma("unroll") for (int k = 0; k < 2; ++k) \
;         acc[ai][bj][m][n] = __builtin_amdgcn_mfma_f32_16x16x32_bf16(Bt[n][k], At[m][k], acc[ai][bj][m][n], 0, 0, 0); __builtin_amdgcn_s_setprio(0); } while (0)
; #define PG8_WAIT_V(n) asm volatile("s_waitcnt vmcnt(" #n ")" ::: "memory")
; #define PG8_WAIT_L(n) asm volatile("s_waitcnt lgkmcnt(" #n ")" ::: "memory")
; #define PG8_BAR __builtin_amdgcn_s_barrier()
; #define PG8_SCHED __builtin_amdgcn_sched_barrier(0)
; template <class Epi, bool ALIGN_EPI = PG8_ALIGN, bool SP2 = PG8_SP2>
; __device__ __forceinline__ void gemm_phase(LAS uchar* lds, const Gemm g, const StaticOrder& S, const Epi& E) {
;     ...
;             const bool last = (t == nt - 2);
;             const char* a1 = cA + (size_t)(t + 1) * kstep;
;             const char* a2 = last ? nA : cA + (size_t)(t + 2) * kstep; const char* b2 = last ? nB : cB + (size_t)(t + 2) * kstep;
;             const char* a3 = a2 + kstep; const char* b3 = b2 + kstep;
;             if constexpr (SP2) {
;             PG8_LDB(B0, 0, 0); PG8_LDB(B1, 0, 1); PG8_SCHED; PG8_LDA(At, 0, 0); PG8_STAGE(PG8_SA(1, 1), a1 + hstepA, voffA);
;             PG8_WAIT_V(8); PG8_WAIT_L(0); PG8_BAR; PG8_MMA(0, 0, At, B0); PG8_MMA(0, 1, At, B1); PG8_BAR; PG8_SCHED;
;             PG8_LDA(At, 0, 1); PG8_STAGE(PG8_SB(0, 0), b2, voffB); PG8_STAGE(PG8_SB(0, 1), b2 + hstepB, voffB); PG8_STAGE(PG8_SA(0, 0), a2, voffA);
;             PG8_WAIT_V(8); PG8_WAIT_L(0); PG8_BAR; PG8_MMA(1, 0, At, B0); PG8_MMA(1, 1, At, B1); PG8_BAR; PG8_SCHED;
.LBB0_836:
	s_add_u32 s36, s14, 0x100
	s_addc_u32 s37, s15, 0
	s_mov_b32 s38, -2
	s_add_u32 s14, s12, 0x100
	s_addc_u32 s15, s13, 0
	s_cmp_eq_u32 s38, 12
	s_cselect_b32 s19, s5, s15
	s_cselect_b32 s18, s4, s14
	s_cselect_b32 s17, s11, s37
	s_cselect_b32 s16, s10, s36
	v_add_u32_e32 v174, 0x10000, v139
	v_add_u32_e32 v192, 0x14000, v139
	ds_read_b128 v[160:163], v174
	ds_read_b128 v[166:169], v174 offset:1024
	ds_read_b128 v[170:173], v174 offset:2048
	ds_read_b128 v[174:177], v174 offset:3072
	ds_read_b128 v[178:181], v192
	ds_read_b128 v[184:187], v192 offset:1024
	ds_read_b128 v[188:191], v192 offset:2048
	ds_read_b128 v[192:195], v192 offset:3072
	v_lshl_add_u64 v[228:229], s[12:13], 0, v[156:157]
	s_add_i32 m0, s23, 0xc000
	ds_read_b128 v[196:199], v165
	ds_read_b128 v[200:203], v165 offset:1024
	ds_read_b128 v[204:207], v165 offset:2048
	ds_read_b128 v[208:211], v165 offset:3072
	ds_read_b128 v[212:215], v165 offset:4096
	ds_read_b128 v[216:219], v165 offset:5120
	ds_read_b128 v[220:223], v165 offset:6144
	ds_read_b128 v[224:227], v165 offset:7168
	global_load_lds_dwordx4 v[228:229], off
	s_add_i32 m0, s23, 0xe000
	v_lshl_add_u64 v[228:229], s[12:13], 0, v[158:159]
	global_load_lds_dwordx4 v[228:229], off
	s_waitcnt vmcnt(8)
	s_waitcnt lgkmcnt(0)
	s_setprio 1
	s_barrier
	v_mfma_f32_16x16x32_bf16 v[126:129], v[160:163], v[196:199], 0
	v_mfma_f32_16x16x32_bf16 v[122:125], v[170:173], v[196:199], 0
	v_mfma_f32_16x16x32_bf16 v[118:121], v[160:163], v[204:207], 0
	v_mfma_f32_16x16x32_bf16 v[110:113], v[170:173], v[204:207], 0
	v_mfma_f32_16x16x32_bf16 v[102:105], v[160:163], v[212:215], 0
	v_mfma_f32_16x16x32_bf16 v[94:97], v[170:173], v[212:215], 0
	v_mfma_f32_16x16x32_bf16 v[86:89], v[160:163], v[220:223], 0
	v_mfma_f32_16x16x32_bf16 v[78:81], v[170:173], v[220:223], 0
	v_mfma_f32_16x16x32_bf16 v[126:129], v[166:169], v[200:203], v[126:129]
	v_mfma_f32_16x16x32_bf16 v[122:125], v[174:177], v[200:203], v[122:125]
	v_mfma_f32_16x16x32_bf16 v[118:121], v[166:169], v[208:211], v[118:121]
	v_mfma_f32_16x16x32_bf16 v[110:113], v[174:177], v[208:211], v[110:113]
	v_mfma_f32_16x16x32_bf16 v[102:105], v[166:169], v[216:219], v[102:105]
	v_mfma_f32_16x16x32_bf16 v[94:97], v[174:177], v[216:219], v[94:97]
	v_mfma_f32_16x16x32_bf16 v[86:89], v[166:169], v[224:227], v[86:89]
	v_mfma_f32_16x16x32_bf16 v[78:81], v[174:177], v[224:227], v[78:81]
	v_mfma_f32_16x16x32_bf16 v[114:117], v[178:181], v[196:199], 0
	v_mfma_f32_16x16x32_bf16 v[106:109], v[188:191], v[196:199], 0
	v_mfma_f32_16x16x32_bf16 v[98:101], v[178:181], v[204:207], 0
	v_mfma_f32_16x16x32_bf16 v[90:93], v[188:191], v[204:207], 0
	v_mfma_f32_16x16x32_bf16 v[82:85], v[178:181], v[212:215], 0
	v_mfma_f32_16x16x32_bf16 v[74:77], v[188:191], v[212:215], 0
	v_mfma_f32_16x16x32_bf16 v[70:73], v[178:181], v[220:223], 0
	v_mfma_f32_16x16x32_bf16 v[66:69], v[188:191], v[220:223], 0
	v_mfma_f32_16x16x32_bf16 v[114:117], v[184:187], v[200:203], v[114:117]
	v_mfma_f32_16x16x32_bf16 v[106:109], v[192:195], v[200:203], v[106:109]
	v_mfma_f32_16x16x32_bf16 v[98:101], v[184:187], v[208:211], v[98:101]
	v_mfma_f32_16x16x32_bf16 v[90:93], v[192:195], v[208:211], v[90:93]
	v_mfma_f32_16x16x32_bf16 v[82:85], v[184:187], v[216:219], v[82:85]
	v_mfma_f32_16x16x32_bf16 v[74:77], v[192:195], v[216:219], v[74:77]
	v_mfma_f32_16x16x32_bf16 v[70:73], v[184:187], v[224:227], v[70:73]
	v_mfma_f32_16x16x32_bf16 v[66:69], v[192:195], v[224:227], v[66:69]
	s_barrier
	s_setprio 0
	v_lshl_add_u64 v[228:229], s[16:17], 0, v[132:133]
	s_add_i32 m0, s22, 0x10000
	ds_read_b128 v[196:199], v165 offset:16384
	ds_read_b128 v[200:203], v165 offset:17408
	ds_read_b128 v[204:207], v165 offset:18432
	ds_read_b128 v[208:211], v165 offset:19456
	ds_read_b128 v[212:215], v165 offset:20480
	ds_read_b128 v[216:219], v165 offset:21504
	ds_read_b128 v[220:223], v165 offset:22528
	ds_read_b128 v[224:227], v165 offset:23552
	global_load_lds_dwordx4 v[228:229], off
	s_add_i32 m0, s22, 0x12000
	s_add_u32 s12, s16, 0x44000
	v_lshl_add_u64 v[230:231], s[16:17], 0, v[152:153]
	s_addc_u32 s13, s17, 0
	global_load_lds_dwordx4 v[230:231], off
	s_add_i32 m0, s22, 0x14000
	v_lshl_add_u64 v[232:233], s[12:13], 0, v[132:133]
	global_load_lds_dwordx4 v[232:233], off
	s_add_i32 m0, s22, 0x16000
	v_lshl_add_u64 v[232:233], s[12:13], 0, v[152:153]
	global_load_lds_dwordx4 v[232:233], off
	s_mov_b32 m0, s23
	v_lshl_add_u64 v[232:233], s[18:19], 0, v[130:131]
	global_load_lds_dwordx4 v[232:233], off
	s_mov_b32 m0, s24
	v_lshl_add_u64 v[234:235], s[18:19], 0, v[134:135]
	global_load_lds_dwordx4 v[234:235], off
	s_waitcnt vmcnt(8)
	s_waitcnt lgkmcnt(0)
	s_setprio 1
	s_barrier
; #define PG8_STAGE(bufoff, gbase, voff) do { _Pragma("unroll") for (int _i = 0; _i < 2; ++_i) \
;         __builtin_amdgcn_global_load_lds((const unsigned*)((const char*)(gbase) + (voff)[_i]), (LAS unsigned*)(lds + (bufoff) + ldsw + _i * 8192), 16, 0, 0); } while (0)
; #define PG8_LDA(dst, b, h) do { _Pragma("unroll") for (int m = 0; m < 4; ++m) _Pragma("unroll") for (int k = 0; k < 2; ++k) dst[m][k] = *(const LAS bf16x8*)(lds + PG8_SA(b, h) + aoff + m * 2048 + k * 1024); } while (0)
; #define PG8_LDB(dst, b, h) do { _Pragma("unroll") for (int n = 0; n < 2; ++n) _Pragma("unroll") for (int k = 0; k < 2; ++k) dst[n][k] = *(const LAS bf16x8*)(lds + PG8_SB(b, h) + boff + n * 2048 + k * 1024); } while (0)
; #define PG8_MMA(ai, bj, At, Bt) do { __builtin_amdgcn_s_setprio(1); _Pragma("unroll") for (int m = 0; m < 4; ++m) _Pragma("unroll") for (int n = 0; n < 2; ++n) _Pragma("unroll") for (int k = 0; k < 2; ++k) \
;         acc[ai][bj][m][n] = __builtin_amdgcn_mfma_f32_16x16x32_bf16(Bt[n][k], At[m][k], acc[ai][bj][m][n], 0, 0, 0); __builtin_amdgcn_s_setprio(0); } while (0)
; #define PG8_WAIT_V(n) asm volatile("s_waitcnt vmcnt(" #n ")" ::: "memory")
; #define PG8_WAIT_L(n) asm volatile("s_waitcnt lgkmcnt(" #n ")" ::: "memory")
; #define PG8_BAR __builtin_amdgcn_s_barrier()
; #define PG8_SCHED __builtin_amdgcn_sched_barrier(0)
; template <class Epi, bool ALIGN_EPI = PG8_ALIGN, bool SP2 = PG8_SP2>
; __device__ __forceinline__ void gemm_phase(LAS uchar* lds, const Gemm g, const StaticOrder& S, const Epi& E) {
;     ...
;             PG8_WAIT_V(8); PG8_WAIT_L(0); PG8_BAR; PG8_MMA(1, 0, At, B0); PG8_MMA(1, 1, At, B1); PG8_BAR; PG8_SCHED;
;             PG8_LDB(B0, 1, 0); PG8_LDB(B1, 1, 1); PG8_SCHED; PG8_LDA(At, 1, 0); PG8_STAGE(PG8_SA(0, 1), a2 + hstepA, voffA);
;             PG8_WAIT_V(8); PG8_WAIT_L(0); PG8_BAR; PG8_MMA(0, 0, At, B0); PG8_MMA(0, 1, At, B1); PG8_BAR; PG8_SCHED;
	v_mfma_f32_16x16x32_bf16 v[62:65], v[160:163], v[196:199], 0
	v_mfma_f32_16x16x32_bf16 v[58:61], v[170:173], v[196:199], 0
	v_mfma_f32_16x16x32_bf16 v[54:57], v[160:163], v[204:207], 0
	v_mfma_f32_16x16x32_bf16 v[46:49], v[170:173], v[204:207], 0
	v_mfma_f32_16x16x32_bf16 v[38:41], v[160:163], v[212:215], 0
	v_mfma_f32_16x16x32_bf16 v[30:33], v[170:173], v[212:215], 0
	v_mfma_f32_16x16x32_bf16 v[22:25], v[160:163], v[220:223], 0
	v_mfma_f32_16x16x32_bf16 v[14:17], v[170:173], v[220:223], 0
	v_mfma_f32_16x16x32_bf16 v[62:65], v[166:169], v[200:203], v[62:65]
	v_mfma_f32_16x16x32_bf16 v[58:61], v[174:177], v[200:203], v[58:61]
	v_mfma_f32_16x16x32_bf16 v[54:57], v[166:169], v[208:211], v[54:57]
	v_mfma_f32_16x16x32_bf16 v[46:49], v[174:177], v[208:211], v[46:49]
	v_mfma_f32_16x16x32_bf16 v[38:41], v[166:169], v[216:219], v[38:41]
	v_mfma_f32_16x16x32_bf16 v[30:33], v[174:177], v[216:219], v[30:33]
	v_mfma_f32_16x16x32_bf16 v[22:25], v[166:169], v[224:227], v[22:25]
	v_mfma_f32_16x16x32_bf16 v[14:17], v[174:177], v[224:227], v[14:17]
	v_mfma_f32_16x16x32_bf16 v[50:53], v[178:181], v[196:199], 0
	v_mfma_f32_16x16x32_bf16 v[42:45], v[188:191], v[196:199], 0
	v_mfma_f32_16x16x32_bf16 v[34:37], v[178:181], v[204:207], 0
	v_mfma_f32_16x16x32_bf16 v[26:29], v[188:191], v[204:207], 0
	v_mfma_f32_16x16x32_bf16 v[18:21], v[178:181], v[212:215], 0
	v_mfma_f32_16x16x32_bf16 v[10:13], v[188:191], v[212:215], 0
	v_mfma_f32_16x16x32_bf16 v[6:9], v[178:181], v[220:223], 0
	v_mfma_f32_16x16x32_bf16 v[2:5], v[188:191], v[220:223], 0
	v_mfma_f32_16x16x32_bf16 v[50:53], v[184:187], v[200:203], v[50:53]
	v_mfma_f32_16x16x32_bf16 v[42:45], v[192:195], v[200:203], v[42:45]
	v_mfma_f32_16x16x32_bf16 v[34:37], v[184:187], v[208:211], v[34:37]
	v_mfma_f32_16x16x32_bf16 v[26:29], v[192:195], v[208:211], v[26:29]
	v_mfma_f32_16x16x32_bf16 v[18:21], v[184:187], v[216:219], v[18:21]
	v_mfma_f32_16x16x32_bf16 v[10:13], v[192:195], v[216:219], v[10:13]
	v_mfma_f32_16x16x32_bf16 v[6:9], v[184:187], v[224:227], v[6:9]
	v_mfma_f32_16x16x32_bf16 v[2:5], v[192:195], v[224:227], v[2:5]
	s_barrier
	s_setprio 0
	v_add_u32_e32 v174, 0x18000, v139
	v_add_u32_e32 v192, 0x1c000, v139
	ds_read_b128 v[160:163], v174
	ds_read_b128 v[166:169], v174 offset:1024
	ds_read_b128 v[170:173], v174 offset:2048
	ds_read_b128 v[174:177], v174 offset:3072
	ds_read_b128 v[178:181], v192
	ds_read_b128 v[184:187], v192 offset:1024
	ds_read_b128 v[188:191], v192 offset:2048
	ds_read_b128 v[192:195], v192 offset:3072
	s_add_u32 s12, s18, 0x44000
	s_addc_u32 s13, s19, 0
	s_mov_b32 m0, s25
	v_lshl_add_u64 v[236:237], s[12:13], 0, v[130:131]
	ds_read_b128 v[196:199], v165 offset:32768
	ds_read_b128 v[200:203], v165 offset:33792
	ds_read_b128 v[204:207], v165 offset:34816
	ds_read_b128 v[208:211], v165 offset:35840
	ds_read_b128 v[212:215], v165 offset:36864
	ds_read_b128 v[216:219], v165 offset:37888
	ds_read_b128 v[220:223], v165 offset:38912
	ds_read_b128 v[224:227], v165 offset:39936
	global_load_lds_dwordx4 v[236:237], off
	s_mov_b32 m0, s26
	v_lshl_add_u64 v[236:237], s[12:13], 0, v[134:135]
	global_load_lds_dwordx4 v[236:237], off
	s_waitcnt vmcnt(8)
	s_waitcnt lgkmcnt(0)
	s_setprio 1
	s_barrier
	v_mfma_f32_16x16x32_bf16 v[126:129], v[160:163], v[196:199], v[126:129]
	v_mfma_f32_16x16x32_bf16 v[122:125], v[170:173], v[196:199], v[122:125]
	v_mfma_f32_16x16x32_bf16 v[118:121], v[160:163], v[204:207], v[118:121]
	v_mfma_f32_16x16x32_bf16 v[110:113], v[170:173], v[204:207], v[110:113]
	v_mfma_f32_16x16x32_bf16 v[102:105], v[160:163], v[212:215], v[102:105]
	v_mfma_f32_16x16x32_bf16 v[94:97], v[170:173], v[212:215], v[94:97]
	v_mfma_f32_16x16x32_bf16 v[86:89], v[160:163], v[220:223], v[86:89]
	v_mfma_f32_16x16x32_bf16 v[78:81], v[170:173], v[220:223], v[78:81]
	v_mfma_f32_16x16x32_bf16 v[126:129], v[166:169], v[200:203], v[126:129]
	v_mfma_f32_16x16x32_bf16 v[122:125], v[174:177], v[200:203], v[122:125]
	v_mfma_f32_16x16x32_bf16 v[118:121], v[166:169], v[208:211], v[118:121]
	v_mfma_f32_16x16x32_bf16 v[110:113], v[174:177], v[208:211], v[110:113]
	v_mfma_f32_16x16x32_bf16 v[102:105], v[166:169], v[216:219], v[102:105]
	v_mfma_f32_16x16x32_bf16 v[94:97], v[174:177], v[216:219], v[94:97]
	v_mfma_f32_16x16x32_bf16 v[86:89], v[166:169], v[224:227], v[86:89]
	v_mfma_f32_16x16x32_bf16 v[78:81], v[174:177], v[224:227], v[78:81]
	v_mfma_f32_16x16x32_bf16 v[114:117], v[178:181], v[196:199], v[114:117]
	v_mfma_f32_16x16x32_bf16 v[106:109], v[188:191], v[196:199], v[106:109]
	v_mfma_f32_16x16x32_bf16 v[98:101], v[178:181], v[204:207], v[98:101]
	v_mfma_f32_16x16x32_bf16 v[90:93], v[188:191], v[204:207], v[90:93]
	v_mfma_f32_16x16x32_bf16 v[82:85], v[178:181], v[212:215], v[82:85]
	v_mfma_f32_16x16x32_bf16 v[74:77], v[188:191], v[212:215], v[74:77]
	v_mfma_f32_16x16x32_bf16 v[70:73], v[178:181], v[220:223], v[70:73]
	v_mfma_f32_16x16x32_bf16 v[66:69], v[188:191], v[220:223], v[66:69]
	v_mfma_f32_16x16x32_bf16 v[114:117], v[184:187], v[200:203], v[114:117]
	v_mfma_f32_16x16x32_bf16 v[106:109], v[192:195], v[200:203], v[106:109]
	v_mfma_f32_16x16x32_bf16 v[98:101], v[184:187], v[208:211], v[98:101]
	v_mfma_f32_16x16x32_bf16 v[90:93], v[192:195], v[208:211], v[90:93]
	v_mfma_f32_16x16x32_bf16 v[82:85], v[184:187], v[216:219], v[82:85]
	v_mfma_f32_16x16x32_bf16 v[74:77], v[192:195], v[216:219], v[74:77]
	v_mfma_f32_16x16x32_bf16 v[70:73], v[184:187], v[224:227], v[70:73]
	v_mfma_f32_16x16x32_bf16 v[66:69], v[192:195], v[224:227], v[66:69]
	s_barrier
; #define PG8_STAGE(bufoff, gbase, voff) do { _Pragma("unroll") for (int _i = 0; _i < 2; ++_i) \
;         __builtin_amdgcn_global_load_lds((const unsigned*)((const char*)(gbase) + (voff)[_i]), (LAS unsigned*)(lds + (bufoff) + ldsw + _i * 8192), 16, 0, 0); } while (0)
; #define PG8_LDA(dst, b, h) do { _Pragma("unroll") for (int m = 0; m < 4; ++m) _Pragma("unroll") for (int k = 0; k < 2; ++k) dst[m][k] = *(const LAS bf16x8*)(lds + PG8_SA(b, h) + aoff + m * 2048 + k * 1024); } while (0)
; #define PG8_LDB(dst, b, h) do { _Pragma("unroll") for (int n = 0; n < 2; ++n) _Pragma("unroll") for (int k = 0; k < 2; ++k) dst[n][k] = *(const LAS bf16x8*)(lds + PG8_SB(b, h) + boff + n * 2048 + k * 1024); } while (0)
; #define PG8_MMA(ai, bj, At, Bt) do { __builtin_amdgcn_s_setprio(1); _Pragma("unroll") for (int m = 0; m < 4; ++m) _Pragma("unroll") for (int n = 0; n < 2; ++n) _Pragma("unroll") for (int k = 0; k < 2; ++k) \
;         acc[ai][bj][m][n] = __builtin_amdgcn_mfma_f32_16x16x32_bf16(Bt[n][k], At[m][k], acc[ai][bj][m][n], 0, 0, 0); __builtin_amdgcn_s_setprio(0); } while (0)
; #define PG8_WAIT_V(n) asm volatile("s_waitcnt vmcnt(" #n ")" ::: "memory")
; #define PG8_WAIT_L(n) asm volatile("s_waitcnt lgkmcnt(" #n ")" ::: "memory")
; #define PG8_BAR __builtin_amdgcn_s_barrier()
; #define PG8_SCHED __builtin_amdgcn_sched_barrier(0)
; template <class Epi, bool ALIGN_EPI = PG8_ALIGN, bool SP2 = PG8_SP2>
; __device__ __forceinline__ void gemm_phase(LAS uchar* lds, const Gemm g, const StaticOrder& S, const Epi& E) {
;     ...
;             const bool last = (t == nt - 2);
;             const char* a1 = cA + (size_t)(t + 1) * kstep;
;             const char* a2 = last ? nA : cA + (size_t)(t + 2) * kstep; const char* b2 = last ? nB : cB + (size_t)(t + 2) * kstep;
;             const char* a3 = a2 + kstep; const char* b3 = b2 + kstep;
;             if constexpr (SP2) {
;             PG8_LDB(B0, 0, 0); PG8_LDB(B1, 0, 1); PG8_SCHED; PG8_LDA(At, 0, 0); PG8_STAGE(PG8_SA(1, 1), a1 + hstepA, voffA);
;             PG8_WAIT_V(8); PG8_WAIT_L(0); PG8_BAR; PG8_MMA(0, 0, At, B0); PG8_MMA(0, 1, At, B1); PG8_BAR; PG8_SCHED;
;     ...
;             PG8_LDA(At, 1, 1); PG8_STAGE(PG8_SB(1, 0), b3, voffB); PG8_STAGE(PG8_SB(1, 1), b3 + hstepB, voffB); PG8_STAGE(PG8_SA(1, 0), a3, voffA);
;             PG8_WAIT_V(8); PG8_WAIT_L(0); PG8_BAR; PG8_MMA(1, 0, At, B0); PG8_MMA(1, 1, At, B1); PG8_BAR; PG8_SCHED;
	s_setprio 0
	v_lshl_add_u64 v[228:229], v[228:229], 0, s[84:85]
	s_add_i32 m0, s22, 0x18000
	ds_read_b128 v[196:199], v165 offset:49152
	ds_read_b128 v[200:203], v165 offset:50176
	ds_read_b128 v[204:207], v165 offset:51200
	ds_read_b128 v[208:211], v165 offset:52224
	ds_read_b128 v[212:215], v165 offset:53248
	ds_read_b128 v[216:219], v165 offset:54272
	ds_read_b128 v[220:223], v165 offset:55296
	ds_read_b128 v[224:227], v165 offset:56320
	global_load_lds_dwordx4 v[228:229], off
	s_add_i32 m0, s22, 0x1a000
	s_add_u32 s12, s16, 0x44080
	v_lshl_add_u64 v[228:229], v[230:231], 0, s[84:85]
	s_addc_u32 s13, s17, 0
	global_load_lds_dwordx4 v[228:229], off
	s_add_i32 m0, s22, 0x1c000
	v_lshl_add_u64 v[228:229], s[12:13], 0, v[132:133]
	global_load_lds_dwordx4 v[228:229], off
	s_add_i32 m0, s22, 0x1e000
	v_lshl_add_u64 v[228:229], s[12:13], 0, v[152:153]
	global_load_lds_dwordx4 v[228:229], off
	s_mov_b32 m0, s27
	v_lshl_add_u64 v[228:229], v[232:233], 0, s[84:85]
	global_load_lds_dwordx4 v[228:229], off
	s_mov_b32 m0, s28
	v_lshl_add_u64 v[228:229], v[234:235], 0, s[84:85]
	global_load_lds_dwordx4 v[228:229], off
	s_waitcnt vmcnt(8)
	s_waitcnt lgkmcnt(0)
	s_setprio 1
	s_barrier
	v_mfma_f32_16x16x32_bf16 v[62:65], v[160:163], v[196:199], v[62:65]
	v_mfma_f32_16x16x32_bf16 v[58:61], v[170:173], v[196:199], v[58:61]
	v_mfma_f32_16x16x32_bf16 v[54:57], v[160:163], v[204:207], v[54:57]
	v_mfma_f32_16x16x32_bf16 v[46:49], v[170:173], v[204:207], v[46:49]
	v_mfma_f32_16x16x32_bf16 v[38:41], v[160:163], v[212:215], v[38:41]
	v_mfma_f32_16x16x32_bf16 v[30:33], v[170:173], v[212:215], v[30:33]
	v_mfma_f32_16x16x32_bf16 v[22:25], v[160:163], v[220:223], v[22:25]
	v_mfma_f32_16x16x32_bf16 v[14:17], v[170:173], v[220:223], v[14:17]
	v_mfma_f32_16x16x32_bf16 v[62:65], v[166:169], v[200:203], v[62:65]
	v_mfma_f32_16x16x32_bf16 v[58:61], v[174:177], v[200:203], v[58:61]
	v_mfma_f32_16x16x32_bf16 v[54:57], v[166:169], v[208:211], v[54:57]
	v_mfma_f32_16x16x32_bf16 v[46:49], v[174:177], v[208:211], v[46:49]
	v_mfma_f32_16x16x32_bf16 v[38:41], v[166:169], v[216:219], v[38:41]
	v_mfma_f32_16x16x32_bf16 v[30:33], v[174:177], v[216:219], v[30:33]
	v_mfma_f32_16x16x32_bf16 v[22:25], v[166:169], v[224:227], v[22:25]
	v_mfma_f32_16x16x32_bf16 v[14:17], v[174:177], v[224:227], v[14:17]
	v_mfma_f32_16x16x32_bf16 v[50:53], v[178:181], v[196:199], v[50:53]
	v_mfma_f32_16x16x32_bf16 v[42:45], v[188:191], v[196:199], v[42:45]
	v_mfma_f32_16x16x32_bf16 v[34:37], v[178:181], v[204:207], v[34:37]
	v_mfma_f32_16x16x32_bf16 v[26:29], v[188:191], v[204:207], v[26:29]
	v_mfma_f32_16x16x32_bf16 v[18:21], v[178:181], v[212:215], v[18:21]
	v_mfma_f32_16x16x32_bf16 v[10:13], v[188:191], v[212:215], v[10:13]
	v_mfma_f32_16x16x32_bf16 v[6:9], v[178:181], v[220:223], v[6:9]
	v_mfma_f32_16x16x32_bf16 v[2:5], v[188:191], v[220:223], v[2:5]
	v_mfma_f32_16x16x32_bf16 v[50:53], v[184:187], v[200:203], v[50:53]
	v_mfma_f32_16x16x32_bf16 v[42:45], v[192:195], v[200:203], v[42:45]
	v_mfma_f32_16x16x32_bf16 v[34:37], v[184:187], v[208:211], v[34:37]
	v_mfma_f32_16x16x32_bf16 v[26:29], v[192:195], v[208:211], v[26:29]
	v_mfma_f32_16x16x32_bf16 v[18:21], v[184:187], v[216:219], v[18:21]
	v_mfma_f32_16x16x32_bf16 v[10:13], v[192:195], v[216:219], v[10:13]
	v_mfma_f32_16x16x32_bf16 v[6:9], v[184:187], v[224:227], v[6:9]
	v_mfma_f32_16x16x32_bf16 v[2:5], v[192:195], v[224:227], v[2:5]
	s_barrier
	s_setprio 0
	s_add_i32 s38, s38, 2
	s_add_u32 s36, s36, 0x100
	s_addc_u32 s37, s37, 0
	s_cmp_gt_u32 s38, 13
	s_mov_b64 s[12:13], s[14:15]
.LBB0_837:
	s_add_u32 s14, s12, 0x100
	s_addc_u32 s15, s13, 0
	s_cmp_eq_u32 s38, 12
	s_cselect_b32 s19, s5, s15
	s_cselect_b32 s18, s4, s14
	s_cselect_b32 s17, s11, s37
	s_cselect_b32 s16, s10, s36
	v_add_u32_e32 v174, 0x10000, v139
	v_add_u32_e32 v192, 0x14000, v139
	ds_read_b128 v[160:163], v174
	ds_read_b128 v[166:169], v174 offset:1024
	ds_read_b128 v[170:173], v174 offset:2048
	ds_read_b128 v[174:177], v174 offset:3072
	ds_read_b128 v[178:181], v192
	ds_read_b128 v[184:187], v192 offset:1024
	ds_read_b128 v[188:191], v192 offset:2048
	ds_read_b128 v[192:195], v192 offset:3072
	v_lshl_add_u64 v[228:229], s[12:13], 0, v[156:157]
	s_add_i32 m0, s23, 0xc000
	ds_read_b128 v[196:199], v165
	ds_read_b128 v[200:203], v165 offset:1024
	ds_read_b128 v[204:207], v165 offset:2048
	ds_read_b128 v[208:211], v165 offset:3072
	ds_read_b128 v[212:215], v165 offset:4096
	ds_read_b128 v[216:219], v165 offset:5120
	ds_read_b128 v[220:223], v165 offset:6144
	ds_read_b128 v[224:227], v165 offset:7168
	global_load_lds_dwordx4 v[228:229], off
	s_add_i32 m0, s23, 0xe000
	v_lshl_add_u64 v[228:229], s[12:13], 0, v[158:159]
	global_load_lds_dwordx4 v[228:229], off
	s_waitcnt vmcnt(8)
	s_waitcnt lgkmcnt(0)
	s_setprio 1
	s_barrier
; #define PG8_STAGE(bufoff, gbase, voff) do { _Pragma("unroll") for (int _i = 0; _i < 2; ++_i) \
;         __builtin_amdgcn_global_load_lds((const unsigned*)((const char*)(gbase) + (voff)[_i]), (LAS unsigned*)(lds + (bufoff) + ldsw + _i * 8192), 16, 0, 0); } while (0)
; #define PG8_LDA(dst, b, h) do { _Pragma("unroll") for (int m = 0; m < 4; ++m) _Pragma("unroll") for (int k = 0; k < 2; ++k) dst[m][k] = *(const LAS bf16x8*)(lds + PG8_SA(b, h) + aoff + m * 2048 + k * 1024); } while (0)
; #define PG8_MMA(ai, bj, At, Bt) do { __builtin_amdgcn_s_setprio(1); _Pragma("unroll") for (int m = 0; m < 4; ++m) _Pragma("unroll") for (int n = 0; n < 2; ++n) _Pragma("unroll") for (int k = 0; k < 2; ++k) \
;         acc[ai][bj][m][n] = __builtin_amdgcn_mfma_f32_16x16x32_bf16(Bt[n][k], At[m][k], acc[ai][bj][m][n], 0, 0, 0); __builtin_amdgcn_s_setprio(0); } while (0)
; #define PG8_WAIT_V(n) asm volatile("s_waitcnt vmcnt(" #n ")" ::: "memory")
; #define PG8_WAIT_L(n) asm volatile("s_waitcnt lgkmcnt(" #n ")" ::: "memory")
; #define PG8_BAR __builtin_amdgcn_s_barrier()
; #define PG8_SCHED __builtin_amdgcn_sched_barrier(0)
; template <class Epi, bool ALIGN_EPI = PG8_ALIGN, bool SP2 = PG8_SP2>
; __device__ __forceinline__ void gemm_phase(LAS uchar* lds, const Gemm g, const StaticOrder& S, const Epi& E) {
;     ...
;             PG8_WAIT_V(8); PG8_WAIT_L(0); PG8_BAR; PG8_MMA(0, 0, At, B0); PG8_MMA(0, 1, At, B1); PG8_BAR; PG8_SCHED;
;             PG8_LDA(At, 0, 1); PG8_STAGE(PG8_SB(0, 0), b2, voffB); PG8_STAGE(PG8_SB(0, 1), b2 + hstepB, voffB); PG8_STAGE(PG8_SA(0, 0), a2, voffA);
;             PG8_WAIT_V(8); PG8_WAIT_L(0); PG8_BAR; PG8_MMA(1, 0, At, B0); PG8_MMA(1, 1, At, B1); PG8_BAR; PG8_SCHED;
	v_mfma_f32_16x16x32_bf16 v[126:129], v[160:163], v[196:199], v[126:129]
	v_mfma_f32_16x16x32_bf16 v[122:125], v[170:173], v[196:199], v[122:125]
	v_mfma_f32_16x16x32_bf16 v[118:121], v[160:163], v[204:207], v[118:121]
	v_mfma_f32_16x16x32_bf16 v[110:113], v[170:173], v[204:207], v[110:113]
	v_mfma_f32_16x16x32_bf16 v[102:105], v[160:163], v[212:215], v[102:105]
	v_mfma_f32_16x16x32_bf16 v[94:97], v[170:173], v[212:215], v[94:97]
	v_mfma_f32_16x16x32_bf16 v[86:89], v[160:163], v[220:223], v[86:89]
	v_mfma_f32_16x16x32_bf16 v[78:81], v[170:173], v[220:223], v[78:81]
	v_mfma_f32_16x16x32_bf16 v[126:129], v[166:169], v[200:203], v[126:129]
	v_mfma_f32_16x16x32_bf16 v[122:125], v[174:177], v[200:203], v[122:125]
	v_mfma_f32_16x16x32_bf16 v[118:121], v[166:169], v[208:211], v[118:121]
	v_mfma_f32_16x16x32_bf16 v[110:113], v[174:177], v[208:211], v[110:113]
	v_mfma_f32_16x16x32_bf16 v[102:105], v[166:169], v[216:219], v[102:105]
	v_mfma_f32_16x16x32_bf16 v[94:97], v[174:177], v[216:219], v[94:97]
	v_mfma_f32_16x16x32_bf16 v[86:89], v[166:169], v[224:227], v[86:89]
	v_mfma_f32_16x16x32_bf16 v[78:81], v[174:177], v[224:227], v[78:81]
	v_mfma_f32_16x16x32_bf16 v[114:117], v[178:181], v[196:199], v[114:117]
	v_mfma_f32_16x16x32_bf16 v[106:109], v[188:191], v[196:199], v[106:109]
	v_mfma_f32_16x16x32_bf16 v[98:101], v[178:181], v[204:207], v[98:101]
	v_mfma_f32_16x16x32_bf16 v[90:93], v[188:191], v[204:207], v[90:93]
	v_mfma_f32_16x16x32_bf16 v[82:85], v[178:181], v[212:215], v[82:85]
	v_mfma_f32_16x16x32_bf16 v[74:77], v[188:191], v[212:215], v[74:77]
	v_mfma_f32_16x16x32_bf16 v[70:73], v[178:181], v[220:223], v[70:73]
	v_mfma_f32_16x16x32_bf16 v[66:69], v[188:191], v[220:223], v[66:69]
	v_mfma_f32_16x16x32_bf16 v[114:117], v[184:187], v[200:203], v[114:117]
	v_mfma_f32_16x16x32_bf16 v[106:109], v[192:195], v[200:203], v[106:109]
	v_mfma_f32_16x16x32_bf16 v[98:101], v[184:187], v[208:211], v[98:101]
	v_mfma_f32_16x16x32_bf16 v[90:93], v[192:195], v[208:211], v[90:93]
	v_mfma_f32_16x16x32_bf16 v[82:85], v[184:187], v[216:219], v[82:85]
	v_mfma_f32_16x16x32_bf16 v[74:77], v[192:195], v[216:219], v[74:77]
	v_mfma_f32_16x16x32_bf16 v[70:73], v[184:187], v[224:227], v[70:73]
	v_mfma_f32_16x16x32_bf16 v[66:69], v[192:195], v[224:227], v[66:69]
	s_barrier
	s_setprio 0
	v_lshl_add_u64 v[228:229], s[16:17], 0, v[132:133]
	s_add_i32 m0, s22, 0x10000
	ds_read_b128 v[196:199], v165 offset:16384
	ds_read_b128 v[200:203], v165 offset:17408
	ds_read_b128 v[204:207], v165 offset:18432
	ds_read_b128 v[208:211], v165 offset:19456
	ds_read_b128 v[212:215], v165 offset:20480
	ds_read_b128 v[216:219], v165 offset:21504
	ds_read_b128 v[220:223], v165 offset:22528
	ds_read_b128 v[224:227], v165 offset:23552
	global_load_lds_dwordx4 v[228:229], off
	s_add_i32 m0, s22, 0x12000
	s_add_u32 s12, s16, 0x44000
	v_lshl_add_u64 v[230:231], s[16:17], 0, v[152:153]
	s_addc_u32 s13, s17, 0
	global_load_lds_dwordx4 v[230:231], off
	s_add_i32 m0, s22, 0x14000
	v_lshl_add_u64 v[232:233], s[12:13], 0, v[132:133]
	global_load_lds_dwordx4 v[232:233], off
	s_add_i32 m0, s22, 0x16000
	v_lshl_add_u64 v[232:233], s[12:13], 0, v[152:153]
	global_load_lds_dwordx4 v[232:233], off
	s_mov_b32 m0, s23
	v_lshl_add_u64 v[232:233], s[18:19], 0, v[130:131]
	global_load_lds_dwordx4 v[232:233], off
	s_mov_b32 m0, s24
	v_lshl_add_u64 v[234:235], s[18:19], 0, v[134:135]
	global_load_lds_dwordx4 v[234:235], off
	s_waitcnt vmcnt(8)
	s_waitcnt lgkmcnt(0)
	s_setprio 1
	s_barrier
	v_mfma_f32_16x16x32_bf16 v[62:65], v[160:163], v[196:199], v[62:65]
	v_mfma_f32_16x16x32_bf16 v[58:61], v[170:173], v[196:199], v[58:61]
	v_mfma_f32_16x16x32_bf16 v[54:57], v[160:163], v[204:207], v[54:57]
	v_mfma_f32_16x16x32_bf16 v[46:49], v[170:173], v[204:207], v[46:49]
	v_mfma_f32_16x16x32_bf16 v[38:41], v[160:163], v[212:215], v[38:41]
	v_mfma_f32_16x16x32_bf16 v[30:33], v[170:173], v[212:215], v[30:33]
	v_mfma_f32_16x16x32_bf16 v[22:25], v[160:163], v[220:223], v[22:25]
	v_mfma_f32_16x16x32_bf16 v[14:17], v[170:173], v[220:223], v[14:17]
	v_mfma_f32_16x16x32_bf16 v[62:65], v[166:169], v[200:203], v[62:65]
	v_mfma_f32_16x16x32_bf16 v[58:61], v[174:177], v[200:203], v[58:61]
	v_mfma_f32_16x16x32_bf16 v[54:57], v[166:169], v[208:211], v[54:57]
	v_mfma_f32_16x16x32_bf16 v[46:49], v[174:177], v[208:211], v[46:49]
	v_mfma_f32_16x16x32_bf16 v[38:41], v[166:169], v[216:219], v[38:41]
	v_mfma_f32_16x16x32_bf16 v[30:33], v[174:177], v[216:219], v[30:33]
	v_mfma_f32_16x16x32_bf16 v[22:25], v[166:169], v[224:227], v[22:25]
	v_mfma_f32_16x16x32_bf16 v[14:17], v[174:177], v[224:227], v[14:17]
	v_mfma_f32_16x16x32_bf16 v[50:53], v[178:181], v[196:199], v[50:53]
	v_mfma_f32_16x16x32_bf16 v[42:45], v[188:191], v[196:199], v[42:45]
	v_mfma_f32_16x16x32_bf16 v[34:37], v[178:181], v[204:207], v[34:37]
	v_mfma_f32_16x16x32_bf16 v[26:29], v[188:191], v[204:207], v[26:29]
	v_mfma_f32_16x16x32_bf16 v[18:21], v[178:181], v[212:215], v[18:21]
	v_mfma_f32_16x16x32_bf16 v[10:13], v[188:191], v[212:215], v[10:13]
	v_mfma_f32_16x16x32_bf16 v[6:9], v[178:181], v[220:223], v[6:9]
	v_mfma_f32_16x16x32_bf16 v[2:5], v[188:191], v[220:223], v[2:5]
	v_mfma_f32_16x16x32_bf16 v[50:53], v[184:187], v[200:203], v[50:53]
	v_mfma_f32_16x16x32_bf16 v[42:45], v[192:195], v[200:203], v[42:45]
	v_mfma_f32_16x16x32_bf16 v[34:37], v[184:187], v[208:211], v[34:37]
	v_mfma_f32_16x16x32_bf16 v[26:29], v[192:195], v[208:211], v[26:29]
	v_mfma_f32_16x16x32_bf16 v[18:21], v[184:187], v[216:219], v[18:21]
	v_mfma_f32_16x16x32_bf16 v[10:13], v[192:195], v[216:219], v[10:13]
	v_mfma_f32_16x16x32_bf16 v[6:9], v[184:187], v[224:227], v[6:9]
	v_mfma_f32_16x16x32_bf16 v[2:5], v[192:195], v[224:227], v[2:5]
	s_barrier
; #define PG8_STAGE(bufoff, gbase, voff) do { _Pragma("unroll") for (int _i = 0; _i < 2; ++_i) \
;         __builtin_amdgcn_global_load_lds((const unsigned*)((const char*)(gbase) + (voff)[_i]), (LAS unsigned*)(lds + (bufoff) + ldsw + _i * 8192), 16, 0, 0); } while (0)
; #define PG8_LDA(dst, b, h) do { _Pragma("unroll") for (int m = 0; m < 4; ++m) _Pragma("unroll") for (int k = 0; k < 2; ++k) dst[m][k] = *(const LAS bf16x8*)(lds + PG8_SA(b, h) + aoff + m * 2048 + k * 1024); } while (0)
; #define PG8_LDB(dst, b, h) do { _Pragma("unroll") for (int n = 0; n < 2; ++n) _Pragma("unroll") for (int k = 0; k < 2; ++k) dst[n][k] = *(const LAS bf16x8*)(lds + PG8_SB(b, h) + boff + n * 2048 + k * 1024); } while (0)
; #define PG8_MMA(ai, bj, At, Bt) do { __builtin_amdgcn_s_setprio(1); _Pragma("unroll") for (int m = 0; m < 4; ++m) _Pragma("unroll") for (int n = 0; n < 2; ++n) _Pragma("unroll") for (int k = 0; k < 2; ++k) \
;         acc[ai][bj][m][n] = __builtin_amdgcn_mfma_f32_16x16x32_bf16(Bt[n][k], At[m][k], acc[ai][bj][m][n], 0, 0, 0); __builtin_amdgcn_s_setprio(0); } while (0)
; #define PG8_WAIT_V(n) asm volatile("s_waitcnt vmcnt(" #n ")" ::: "memory")
; #define PG8_WAIT_L(n) asm volatile("s_waitcnt lgkmcnt(" #n ")" ::: "memory")
; #define PG8_BAR __builtin_amdgcn_s_barrier()
; #define PG8_SCHED __builtin_amdgcn_sched_barrier(0)
; template <class Epi, bool ALIGN_EPI = PG8_ALIGN, bool SP2 = PG8_SP2>
; __device__ __forceinline__ void gemm_phase(LAS uchar* lds, const Gemm g, const StaticOrder& S, const Epi& E) {
;     ...
;             PG8_LDB(B0, 1, 0); PG8_LDB(B1, 1, 1); PG8_SCHED; PG8_LDA(At, 1, 0); PG8_STAGE(PG8_SA(0, 1), a2 + hstepA, voffA);
;             PG8_WAIT_V(8); PG8_WAIT_L(0); PG8_BAR; PG8_MMA(0, 0, At, B0); PG8_MMA(0, 1, At, B1); PG8_BAR; PG8_SCHED;
;             PG8_LDA(At, 1, 1); PG8_STAGE(PG8_SB(1, 0), b3, voffB); PG8_STAGE(PG8_SB(1, 1), b3 + hstepB, voffB); PG8_STAGE(PG8_SA(1, 0), a3, voffA);
;             PG8_WAIT_V(8); PG8_WAIT_L(0); PG8_BAR; PG8_MMA(1, 0, At, B0); PG8_MMA(1, 1, At, B1); PG8_BAR; PG8_SCHED;
;     ...
;         if constexpr (ALIGN_EPI) { if (wr == 0) PG8_BAR; }
	s_setprio 0
	v_add_u32_e32 v174, 0x18000, v139
	v_add_u32_e32 v192, 0x1c000, v139
	ds_read_b128 v[160:163], v174
	ds_read_b128 v[166:169], v174 offset:1024
	ds_read_b128 v[170:173], v174 offset:2048
	ds_read_b128 v[174:177], v174 offset:3072
	ds_read_b128 v[178:181], v192
	ds_read_b128 v[184:187], v192 offset:1024
	ds_read_b128 v[188:191], v192 offset:2048
	ds_read_b128 v[192:195], v192 offset:3072
	s_add_u32 s12, s18, 0x44000
	s_addc_u32 s13, s19, 0
	s_mov_b32 m0, s25
	v_lshl_add_u64 v[236:237], s[12:13], 0, v[130:131]
	ds_read_b128 v[196:199], v165 offset:32768
	ds_read_b128 v[200:203], v165 offset:33792
	ds_read_b128 v[204:207], v165 offset:34816
	ds_read_b128 v[208:211], v165 offset:35840
	ds_read_b128 v[212:215], v165 offset:36864
	ds_read_b128 v[216:219], v165 offset:37888
	ds_read_b128 v[220:223], v165 offset:38912
	ds_read_b128 v[224:227], v165 offset:39936
	global_load_lds_dwordx4 v[236:237], off
	s_mov_b32 m0, s26
	v_lshl_add_u64 v[236:237], s[12:13], 0, v[134:135]
	global_load_lds_dwordx4 v[236:237], off
	s_waitcnt vmcnt(8)
	s_waitcnt lgkmcnt(0)
	s_setprio 1
	s_barrier
	v_mfma_f32_16x16x32_bf16 v[126:129], v[160:163], v[196:199], v[126:129]
	v_mfma_f32_16x16x32_bf16 v[122:125], v[170:173], v[196:199], v[122:125]
	v_mfma_f32_16x16x32_bf16 v[118:121], v[160:163], v[204:207], v[118:121]
	v_mfma_f32_16x16x32_bf16 v[110:113], v[170:173], v[204:207], v[110:113]
	v_mfma_f32_16x16x32_bf16 v[102:105], v[160:163], v[212:215], v[102:105]
	v_mfma_f32_16x16x32_bf16 v[94:97], v[170:173], v[212:215], v[94:97]
	v_mfma_f32_16x16x32_bf16 v[86:89], v[160:163], v[220:223], v[86:89]
	v_mfma_f32_16x16x32_bf16 v[78:81], v[170:173], v[220:223], v[78:81]
	v_mfma_f32_16x16x32_bf16 v[126:129], v[166:169], v[200:203], v[126:129]
	v_mfma_f32_16x16x32_bf16 v[122:125], v[174:177], v[200:203], v[122:125]
	v_mfma_f32_16x16x32_bf16 v[118:121], v[166:169], v[208:211], v[118:121]
	v_mfma_f32_16x16x32_bf16 v[110:113], v[174:177], v[208:211], v[110:113]
	v_mfma_f32_16x16x32_bf16 v[102:105], v[166:169], v[216:219], v[102:105]
	v_mfma_f32_16x16x32_bf16 v[94:97], v[174:177], v[216:219], v[94:97]
	v_mfma_f32_16x16x32_bf16 v[86:89], v[166:169], v[224:227], v[86:89]
	v_mfma_f32_16x16x32_bf16 v[78:81], v[174:177], v[224:227], v[78:81]
	v_mfma_f32_16x16x32_bf16 v[114:117], v[178:181], v[196:199], v[114:117]
	v_mfma_f32_16x16x32_bf16 v[106:109], v[188:191], v[196:199], v[106:109]
	v_mfma_f32_16x16x32_bf16 v[98:101], v[178:181], v[204:207], v[98:101]
	v_mfma_f32_16x16x32_bf16 v[90:93], v[188:191], v[204:207], v[90:93]
	v_mfma_f32_16x16x32_bf16 v[82:85], v[178:181], v[212:215], v[82:85]
	v_mfma_f32_16x16x32_bf16 v[74:77], v[188:191], v[212:215], v[74:77]
	v_mfma_f32_16x16x32_bf16 v[70:73], v[178:181], v[220:223], v[70:73]
	v_mfma_f32_16x16x32_bf16 v[66:69], v[188:191], v[220:223], v[66:69]
	v_mfma_f32_16x16x32_bf16 v[114:117], v[184:187], v[200:203], v[114:117]
	v_mfma_f32_16x16x32_bf16 v[106:109], v[192:195], v[200:203], v[106:109]
	v_mfma_f32_16x16x32_bf16 v[98:101], v[184:187], v[208:211], v[98:101]
	v_mfma_f32_16x16x32_bf16 v[90:93], v[192:195], v[208:211], v[90:93]
	v_mfma_f32_16x16x32_bf16 v[82:85], v[184:187], v[216:219], v[82:85]
	v_mfma_f32_16x16x32_bf16 v[74:77], v[192:195], v[216:219], v[74:77]
	v_mfma_f32_16x16x32_bf16 v[70:73], v[184:187], v[224:227], v[70:73]
	v_mfma_f32_16x16x32_bf16 v[66:69], v[192:195], v[224:227], v[66:69]
	s_barrier
	s_setprio 0
	v_lshl_add_u64 v[228:229], v[228:229], 0, s[84:85]
	s_add_i32 m0, s22, 0x18000
	ds_read_b128 v[196:199], v165 offset:49152
	ds_read_b128 v[200:203], v165 offset:50176
	ds_read_b128 v[204:207], v165 offset:51200
	ds_read_b128 v[208:211], v165 offset:52224
	ds_read_b128 v[212:215], v165 offset:53248
	ds_read_b128 v[216:219], v165 offset:54272
	ds_read_b128 v[220:223], v165 offset:55296
	ds_read_b128 v[224:227], v165 offset:56320
	global_load_lds_dwordx4 v[228:229], off
	s_add_i32 m0, s22, 0x1a000
	s_add_u32 s12, s16, 0x44080
	v_lshl_add_u64 v[228:229], v[230:231], 0, s[84:85]
	s_addc_u32 s13, s17, 0
	global_load_lds_dwordx4 v[228:229], off
	s_add_i32 m0, s22, 0x1c000
	v_lshl_add_u64 v[228:229], s[12:13], 0, v[132:133]
	global_load_lds_dwordx4 v[228:229], off
	s_add_i32 m0, s22, 0x1e000
	v_lshl_add_u64 v[228:229], s[12:13], 0, v[152:153]
	global_load_lds_dwordx4 v[228:229], off
	s_mov_b32 m0, s27
	v_lshl_add_u64 v[228:229], v[232:233], 0, s[84:85]
	global_load_lds_dwordx4 v[228:229], off
	s_mov_b32 m0, s28
	v_lshl_add_u64 v[228:229], v[234:235], 0, s[84:85]
	global_load_lds_dwordx4 v[228:229], off
	s_waitcnt vmcnt(8)
	s_waitcnt lgkmcnt(0)
	s_setprio 1
	s_barrier
	v_mfma_f32_16x16x32_bf16 v[62:65], v[160:163], v[196:199], v[62:65]
	v_mfma_f32_16x16x32_bf16 v[58:61], v[170:173], v[196:199], v[58:61]
	v_mfma_f32_16x16x32_bf16 v[54:57], v[160:163], v[204:207], v[54:57]
	v_mfma_f32_16x16x32_bf16 v[46:49], v[170:173], v[204:207], v[46:49]
	v_mfma_f32_16x16x32_bf16 v[38:41], v[160:163], v[212:215], v[38:41]
	v_mfma_f32_16x16x32_bf16 v[30:33], v[170:173], v[212:215], v[30:33]
	v_mfma_f32_16x16x32_bf16 v[22:25], v[160:163], v[220:223], v[22:25]
	v_mfma_f32_16x16x32_bf16 v[14:17], v[170:173], v[220:223], v[14:17]
	v_mfma_f32_16x16x32_bf16 v[62:65], v[166:169], v[200:203], v[62:65]
	v_mfma_f32_16x16x32_bf16 v[58:61], v[174:177], v[200:203], v[58:61]
	v_mfma_f32_16x16x32_bf16 v[54:57], v[166:169], v[208:211], v[54:57]
	v_mfma_f32_16x16x32_bf16 v[46:49], v[174:177], v[208:211], v[46:49]
	v_mfma_f32_16x16x32_bf16 v[38:41], v[166:169], v[216:219], v[38:41]
	v_mfma_f32_16x16x32_bf16 v[30:33], v[174:177], v[216:219], v[30:33]
	v_mfma_f32_16x16x32_bf16 v[22:25], v[166:169], v[224:227], v[22:25]
	v_mfma_f32_16x16x32_bf16 v[14:17], v[174:177], v[224:227], v[14:17]
	v_mfma_f32_16x16x32_bf16 v[50:53], v[178:181], v[196:199], v[50:53]
	v_mfma_f32_16x16x32_bf16 v[42:45], v[188:191], v[196:199], v[42:45]
	v_mfma_f32_16x16x32_bf16 v[34:37], v[178:181], v[204:207], v[34:37]
	v_mfma_f32_16x16x32_bf16 v[26:29], v[188:191], v[204:207], v[26:29]
	v_mfma_f32_16x16x32_bf16 v[18:21], v[178:181], v[212:215], v[18:21]
	v_mfma_f32_16x16x32_bf16 v[10:13], v[188:191], v[212:215], v[10:13]
	v_mfma_f32_16x16x32_bf16 v[6:9], v[178:181], v[220:223], v[6:9]
	v_mfma_f32_16x16x32_bf16 v[2:5], v[188:191], v[220:223], v[2:5]
	v_mfma_f32_16x16x32_bf16 v[50:53], v[184:187], v[200:203], v[50:53]
	v_mfma_f32_16x16x32_bf16 v[42:45], v[192:195], v[200:203], v[42:45]
	v_mfma_f32_16x16x32_bf16 v[34:37], v[184:187], v[208:211], v[34:37]
	v_mfma_f32_16x16x32_bf16 v[26:29], v[192:195], v[208:211], v[26:29]
	v_mfma_f32_16x16x32_bf16 v[18:21], v[184:187], v[216:219], v[18:21]
	v_mfma_f32_16x16x32_bf16 v[10:13], v[192:195], v[216:219], v[10:13]
	v_mfma_f32_16x16x32_bf16 v[6:9], v[184:187], v[224:227], v[6:9]
	v_mfma_f32_16x16x32_bf16 v[2:5], v[192:195], v[224:227], v[2:5]
	s_barrier
	s_setprio 0
	s_add_i32 s38, s38, 2
	s_add_u32 s36, s36, 0x100
	s_addc_u32 s37, s37, 0
	s_cmp_gt_u32 s38, 13
	s_mov_b64 s[12:13], s[14:15]
	s_cbranch_scc0 .LBB0_837
	s_and_b64 vcc, exec, s[8:9]
	s_cbranch_vccz .LBB0_840
	s_barrier

; #define PG8_STAGE(bufoff, gbase, voff) do { _Pragma("unroll") for (int _i = 0; _i < 2; ++_i) \
;         __builtin_amdgcn_global_load_lds((const unsigned*)((const char*)(gbase) + (voff)[_i]), (LAS unsigned*)(lds + (bufoff) + ldsw + _i * 8192), 16, 0, 0); } while (0)
; #define PG8_LDA(dst, b, h) do { _Pragma("unroll") for (int m = 0; m < 4; ++m) _Pragma("unroll") for (int k = 0; k < 2; ++k) dst[m][k] = *(const LAS bf16x8*)(lds + PG8_SA(b, h) + aoff + m * 2048 + k * 1024); } while (0)
; #define PG8_LDB(dst, b, h) do { _Pragma("unroll") for (int n = 0; n < 2; ++n) _Pragma("unroll") for (int k = 0; k < 2; ++k) dst[n][k] = *(const LAS bf16x8*)(lds + PG8_SB(b, h) + boff + n * 2048 + k * 1024); } while (0)
; #define PG8_SCHED __builtin_amdgcn_sched_barrier(0)
; template <class Epi, bool ALIGN_EPI = PG8_ALIGN, bool SP2 = PG8_SP2>
; __device__ __forceinline__ void gemm_phase(LAS uchar* lds, const Gemm g, const StaticOrder& S, const Epi& E) {
;     ...
;             const bool last = (t == nt - 2);
;             const char* a1 = cA + (size_t)(t + 1) * kstep;
;             const char* a2 = last ? nA : cA + (size_t)(t + 2) * kstep; const char* b2 = last ? nB : cB + (size_t)(t + 2) * kstep;
;             const char* a3 = a2 + kstep; const char* b3 = b2 + kstep;
;             if constexpr (SP2) {
;             PG8_LDB(B0, 0, 0); PG8_LDB(B1, 0, 1); PG8_SCHED; PG8_LDA(At, 0, 0); PG8_STAGE(PG8_SA(1, 1), a1 + hstepA, voffA);
.Lxt_skip_1049:
	s_add_u32 s36, s14, 0x100
	s_addc_u32 s37, s15, 0
	s_mov_b32 s38, -2
	s_add_u32 s14, s12, 0x100
	s_addc_u32 s15, s13, 0
	s_cmp_eq_u32 s38, 12
	s_cselect_b32 s19, s1, s15
	s_cselect_b32 s18, s0, s14
	v_add_u32_e32 v144, 0x10000, v139
	s_cselect_b32 s17, s11, s37
	s_cselect_b32 s16, s10, s36
	ds_read_b128 v[164:167], v144
	ds_read_b128 v[168:171], v144 offset:1024
	ds_read_b128 v[172:175], v144 offset:2048
	ds_read_b128 v[176:179], v144 offset:3072
	v_add_u32_e32 v144, 0x14000, v139
	ds_read_b128 v[184:187], v144
	ds_read_b128 v[188:191], v144 offset:1024
	ds_read_b128 v[192:195], v144 offset:2048
	ds_read_b128 v[196:199], v144 offset:3072
	v_lshl_add_u64 v[160:161], s[12:13], 0, v[156:157]
	s_add_i32 m0, s23, 0xc000
	ds_read_b128 v[200:203], v163
	ds_read_b128 v[204:207], v163 offset:1024
	ds_read_b128 v[208:211], v163 offset:2048
	ds_read_b128 v[212:215], v163 offset:3072
	ds_read_b128 v[216:219], v163 offset:4096
	ds_read_b128 v[220:223], v163 offset:5120
	ds_read_b128 v[224:227], v163 offset:6144
	ds_read_b128 v[228:231], v163 offset:7168
	global_load_lds_dwordx4 v[160:161], off
	s_add_i32 m0, s23, 0xe000
	v_lshl_add_u64 v[160:161], s[12:13], 0, v[158:159]
	global_load_lds_dwordx4 v[160:161], off
	s_cmp_lt_u32 s29, 2
	s_cbranch_scc1 .Lrw_std_1050_0_pl
	s_waitcnt vmcnt(16)
	s_branch .Lrw_done_1050_0_pl

; #define PG8_STAGE(bufoff, gbase, voff) do { _Pragma("unroll") for (int _i = 0; _i < 2; ++_i) \
;         __builtin_amdgcn_global_load_lds((const unsigned*)((const char*)(gbase) + (voff)[_i]), (LAS unsigned*)(lds + (bufoff) + ldsw + _i * 8192), 16, 0, 0); } while (0)
; #define PG8_LDA(dst, b, h) do { _Pragma("unroll") for (int m = 0; m < 4; ++m) _Pragma("unroll") for (int k = 0; k < 2; ++k) dst[m][k] = *(const LAS bf16x8*)(lds + PG8_SA(b, h) + aoff + m * 2048 + k * 1024); } while (0)
; #define PG8_MMA(ai, bj, At, Bt) do { __builtin_amdgcn_s_setprio(1); _Pragma("unroll") for (int m = 0; m < 4; ++m) _Pragma("unroll") for (int n = 0; n < 2; ++n) _Pragma("unroll") for (int k = 0; k < 2; ++k) \
;         acc[ai][bj][m][n] = __builtin_amdgcn_mfma_f32_16x16x32_bf16(Bt[n][k], At[m][k], acc[ai][bj][m][n], 0, 0, 0); __builtin_amdgcn_s_setprio(0); } while (0)
; #define PG8_WAIT_V(n) asm volatile("s_waitcnt vmcnt(" #n ")" ::: "memory")
; #define PG8_WAIT_L(n) asm volatile("s_waitcnt lgkmcnt(" #n ")" ::: "memory")
; #define PG8_BAR __builtin_amdgcn_s_barrier()
; #define PG8_SCHED __builtin_amdgcn_sched_barrier(0)
; template <class Epi, bool ALIGN_EPI = PG8_ALIGN, bool SP2 = PG8_SP2>
; __device__ __forceinline__ void gemm_phase(LAS uchar* lds, const Gemm g, const StaticOrder& S, const Epi& E) {
;     ...
;             PG8_WAIT_V(8); PG8_WAIT_L(0); PG8_BAR; PG8_MMA(0, 0, At, B0); PG8_MMA(0, 1, At, B1); PG8_BAR; PG8_SCHED;
;             PG8_LDA(At, 0, 1); PG8_STAGE(PG8_SB(0, 0), b2, voffB); PG8_STAGE(PG8_SB(0, 1), b2 + hstepB, voffB); PG8_STAGE(PG8_SA(0, 0), a2, voffA);
.Lrw_done_1050_0_pl:
	s_waitcnt lgkmcnt(0)
	s_setprio 1
	s_barrier
	v_mfma_f32_16x16x32_bf16 v[126:129], v[164:167], v[200:203], 0
	v_mfma_f32_16x16x32_bf16 v[118:121], v[172:175], v[200:203], 0
	v_mfma_f32_16x16x32_bf16 v[110:113], v[164:167], v[208:211], 0
	v_mfma_f32_16x16x32_bf16 v[102:105], v[172:175], v[208:211], 0
	v_mfma_f32_16x16x32_bf16 v[94:97], v[164:167], v[216:219], 0
	v_mfma_f32_16x16x32_bf16 v[86:89], v[172:175], v[216:219], 0
	v_mfma_f32_16x16x32_bf16 v[78:81], v[164:167], v[224:227], 0
	v_mfma_f32_16x16x32_bf16 v[70:73], v[172:175], v[224:227], 0
	v_mfma_f32_16x16x32_bf16 v[126:129], v[168:171], v[204:207], v[126:129]
	v_mfma_f32_16x16x32_bf16 v[118:121], v[176:179], v[204:207], v[118:121]
	v_mfma_f32_16x16x32_bf16 v[110:113], v[168:171], v[212:215], v[110:113]
	v_mfma_f32_16x16x32_bf16 v[102:105], v[176:179], v[212:215], v[102:105]
	v_mfma_f32_16x16x32_bf16 v[94:97], v[168:171], v[220:223], v[94:97]
	v_mfma_f32_16x16x32_bf16 v[86:89], v[176:179], v[220:223], v[86:89]
	v_mfma_f32_16x16x32_bf16 v[78:81], v[168:171], v[228:231], v[78:81]
	v_mfma_f32_16x16x32_bf16 v[70:73], v[176:179], v[228:231], v[70:73]
	v_mfma_f32_16x16x32_bf16 v[122:125], v[184:187], v[200:203], 0
	v_mfma_f32_16x16x32_bf16 v[114:117], v[192:195], v[200:203], 0
	v_mfma_f32_16x16x32_bf16 v[106:109], v[184:187], v[208:211], 0
	v_mfma_f32_16x16x32_bf16 v[98:101], v[192:195], v[208:211], 0
	v_mfma_f32_16x16x32_bf16 v[90:93], v[184:187], v[216:219], 0
	v_mfma_f32_16x16x32_bf16 v[82:85], v[192:195], v[216:219], 0
	v_mfma_f32_16x16x32_bf16 v[74:77], v[184:187], v[224:227], 0
	v_mfma_f32_16x16x32_bf16 v[66:69], v[192:195], v[224:227], 0
	v_mfma_f32_16x16x32_bf16 v[122:125], v[188:191], v[204:207], v[122:125]
	v_mfma_f32_16x16x32_bf16 v[114:117], v[196:199], v[204:207], v[114:117]
	v_mfma_f32_16x16x32_bf16 v[106:109], v[188:191], v[212:215], v[106:109]
	v_mfma_f32_16x16x32_bf16 v[98:101], v[196:199], v[212:215], v[98:101]
	v_mfma_f32_16x16x32_bf16 v[90:93], v[188:191], v[220:223], v[90:93]
	v_mfma_f32_16x16x32_bf16 v[82:85], v[196:199], v[220:223], v[82:85]
	v_mfma_f32_16x16x32_bf16 v[74:77], v[188:191], v[228:231], v[74:77]
	v_mfma_f32_16x16x32_bf16 v[66:69], v[196:199], v[228:231], v[66:69]
	s_barrier
	s_setprio 0
	v_lshl_add_u64 v[160:161], s[16:17], 0, v[134:135]
	s_add_i32 m0, s21, 0x10000
	ds_read_b128 v[200:203], v163 offset:16384
	ds_read_b128 v[204:207], v163 offset:17408
	ds_read_b128 v[208:211], v163 offset:18432
	ds_read_b128 v[212:215], v163 offset:19456
	ds_read_b128 v[216:219], v163 offset:20480
	ds_read_b128 v[220:223], v163 offset:21504
	ds_read_b128 v[224:227], v163 offset:22528
	ds_read_b128 v[228:231], v163 offset:23552
	global_load_lds_dwordx4 v[160:161], off
	s_add_i32 m0, s21, 0x12000
	s_add_u32 s12, s16, 0x44000
	v_lshl_add_u64 v[180:181], s[16:17], 0, v[130:131]
	s_addc_u32 s13, s17, 0
	global_load_lds_dwordx4 v[180:181], off
	s_add_i32 m0, s21, 0x14000
	v_lshl_add_u64 v[232:233], s[12:13], 0, v[134:135]
	global_load_lds_dwordx4 v[232:233], off
	s_add_i32 m0, s21, 0x16000
	v_lshl_add_u64 v[232:233], s[12:13], 0, v[130:131]
	global_load_lds_dwordx4 v[232:233], off
	s_mov_b32 m0, s23
	v_lshl_add_u64 v[232:233], s[18:19], 0, v[154:155]
	global_load_lds_dwordx4 v[232:233], off
	s_mov_b32 m0, s24
	v_lshl_add_u64 v[234:235], s[18:19], 0, v[132:133]
	global_load_lds_dwordx4 v[234:235], off
	s_cmp_lt_u32 s29, 2
	s_cbranch_scc1 .Lrw_std_1050_1_pl
	s_waitcnt vmcnt(16)
	s_branch .Lrw_done_1050_1_pl

; #define PG8_STAGE(bufoff, gbase, voff) do { _Pragma("unroll") for (int _i = 0; _i < 2; ++_i) \
;         __builtin_amdgcn_global_load_lds((const unsigned*)((const char*)(gbase) + (voff)[_i]), (LAS unsigned*)(lds + (bufoff) + ldsw + _i * 8192), 16, 0, 0); } while (0)
; #define PG8_LDA(dst, b, h) do { _Pragma("unroll") for (int m = 0; m < 4; ++m) _Pragma("unroll") for (int k = 0; k < 2; ++k) dst[m][k] = *(const LAS bf16x8*)(lds + PG8_SA(b, h) + aoff + m * 2048 + k * 1024); } while (0)
; #define PG8_LDB(dst, b, h) do { _Pragma("unroll") for (int n = 0; n < 2; ++n) _Pragma("unroll") for (int k = 0; k < 2; ++k) dst[n][k] = *(const LAS bf16x8*)(lds + PG8_SB(b, h) + boff + n * 2048 + k * 1024); } while (0)
; #define PG8_MMA(ai, bj, At, Bt) do { __builtin_amdgcn_s_setprio(1); _Pragma("unroll") for (int m = 0; m < 4; ++m) _Pragma("unroll") for (int n = 0; n < 2; ++n) _Pragma("unroll") for (int k = 0; k < 2; ++k) \
;         acc[ai][bj][m][n] = __builtin_amdgcn_mfma_f32_16x16x32_bf16(Bt[n][k], At[m][k], acc[ai][bj][m][n], 0, 0, 0); __builtin_amdgcn_s_setprio(0); } while (0)
; #define PG8_WAIT_V(n) asm volatile("s_waitcnt vmcnt(" #n ")" ::: "memory")
; #define PG8_WAIT_L(n) asm volatile("s_waitcnt lgkmcnt(" #n ")" ::: "memory")
; #define PG8_BAR __builtin_amdgcn_s_barrier()
; #define PG8_SCHED __builtin_amdgcn_sched_barrier(0)
; template <class Epi, bool ALIGN_EPI = PG8_ALIGN, bool SP2 = PG8_SP2>
; __device__ __forceinline__ void gemm_phase(LAS uchar* lds, const Gemm g, const StaticOrder& S, const Epi& E) {
;     ...
;             PG8_WAIT_V(8); PG8_WAIT_L(0); PG8_BAR; PG8_MMA(1, 0, At, B0); PG8_MMA(1, 1, At, B1); PG8_BAR; PG8_SCHED;
;             PG8_LDB(B0, 1, 0); PG8_LDB(B1, 1, 1); PG8_SCHED; PG8_LDA(At, 1, 0); PG8_STAGE(PG8_SA(0, 1), a2 + hstepA, voffA);
;             PG8_WAIT_V(8); PG8_WAIT_L(0); PG8_BAR; PG8_MMA(0, 0, At, B0); PG8_MMA(0, 1, At, B1); PG8_BAR; PG8_SCHED;
.Lrw_done_1050_1_pl:
	s_waitcnt lgkmcnt(0)
	s_setprio 1
	s_barrier
	v_mfma_f32_16x16x32_bf16 v[62:65], v[164:167], v[200:203], 0
	v_mfma_f32_16x16x32_bf16 v[54:57], v[172:175], v[200:203], 0
	v_mfma_f32_16x16x32_bf16 v[46:49], v[164:167], v[208:211], 0
	v_mfma_f32_16x16x32_bf16 v[38:41], v[172:175], v[208:211], 0
	v_mfma_f32_16x16x32_bf16 v[30:33], v[164:167], v[216:219], 0
	v_mfma_f32_16x16x32_bf16 v[22:25], v[172:175], v[216:219], 0
	v_mfma_f32_16x16x32_bf16 v[14:17], v[164:167], v[224:227], 0
	v_mfma_f32_16x16x32_bf16 v[6:9], v[172:175], v[224:227], 0
	v_mfma_f32_16x16x32_bf16 v[62:65], v[168:171], v[204:207], v[62:65]
	v_mfma_f32_16x16x32_bf16 v[54:57], v[176:179], v[204:207], v[54:57]
	v_mfma_f32_16x16x32_bf16 v[46:49], v[168:171], v[212:215], v[46:49]
	v_mfma_f32_16x16x32_bf16 v[38:41], v[176:179], v[212:215], v[38:41]
	v_mfma_f32_16x16x32_bf16 v[30:33], v[168:171], v[220:223], v[30:33]
	v_mfma_f32_16x16x32_bf16 v[22:25], v[176:179], v[220:223], v[22:25]
	v_mfma_f32_16x16x32_bf16 v[14:17], v[168:171], v[228:231], v[14:17]
	v_mfma_f32_16x16x32_bf16 v[6:9], v[176:179], v[228:231], v[6:9]
	v_mfma_f32_16x16x32_bf16 v[58:61], v[184:187], v[200:203], 0
	v_mfma_f32_16x16x32_bf16 v[50:53], v[192:195], v[200:203], 0
	v_mfma_f32_16x16x32_bf16 v[42:45], v[184:187], v[208:211], 0
	v_mfma_f32_16x16x32_bf16 v[34:37], v[192:195], v[208:211], 0
	v_mfma_f32_16x16x32_bf16 v[26:29], v[184:187], v[216:219], 0
	v_mfma_f32_16x16x32_bf16 v[18:21], v[192:195], v[216:219], 0
	v_mfma_f32_16x16x32_bf16 v[10:13], v[184:187], v[224:227], 0
	v_mfma_f32_16x16x32_bf16 v[2:5], v[192:195], v[224:227], 0
	v_mfma_f32_16x16x32_bf16 v[58:61], v[188:191], v[204:207], v[58:61]
	v_mfma_f32_16x16x32_bf16 v[50:53], v[196:199], v[204:207], v[50:53]
	v_mfma_f32_16x16x32_bf16 v[42:45], v[188:191], v[212:215], v[42:45]
	v_mfma_f32_16x16x32_bf16 v[34:37], v[196:199], v[212:215], v[34:37]
	v_mfma_f32_16x16x32_bf16 v[26:29], v[188:191], v[220:223], v[26:29]
	v_mfma_f32_16x16x32_bf16 v[18:21], v[196:199], v[220:223], v[18:21]
	v_mfma_f32_16x16x32_bf16 v[10:13], v[188:191], v[228:231], v[10:13]
	v_mfma_f32_16x16x32_bf16 v[2:5], v[196:199], v[228:231], v[2:5]
	s_barrier
	s_setprio 0
	v_add_u32_e32 v144, 0x18000, v139
	ds_read_b128 v[164:167], v144
	ds_read_b128 v[168:171], v144 offset:1024
	ds_read_b128 v[172:175], v144 offset:2048
	ds_read_b128 v[176:179], v144 offset:3072
	v_add_u32_e32 v144, 0x1c000, v139
	ds_read_b128 v[184:187], v144
	ds_read_b128 v[188:191], v144 offset:1024
	ds_read_b128 v[192:195], v144 offset:2048
	ds_read_b128 v[196:199], v144 offset:3072
	s_add_u32 s12, s18, 0x44000
	s_addc_u32 s13, s19, 0
	s_mov_b32 m0, s25
	v_lshl_add_u64 v[236:237], s[12:13], 0, v[154:155]
	ds_read_b128 v[200:203], v163 offset:32768
	ds_read_b128 v[204:207], v163 offset:33792
	ds_read_b128 v[208:211], v163 offset:34816
	ds_read_b128 v[212:215], v163 offset:35840
	ds_read_b128 v[216:219], v163 offset:36864
	ds_read_b128 v[220:223], v163 offset:37888
	ds_read_b128 v[224:227], v163 offset:38912
	ds_read_b128 v[228:231], v163 offset:39936
	global_load_lds_dwordx4 v[236:237], off
	s_mov_b32 m0, s26
	v_lshl_add_u64 v[236:237], s[12:13], 0, v[132:133]
	global_load_lds_dwordx4 v[236:237], off
	s_waitcnt vmcnt(8)
	s_waitcnt lgkmcnt(0)
	s_setprio 1
	s_barrier
	v_mfma_f32_16x16x32_bf16 v[126:129], v[164:167], v[200:203], v[126:129]
	v_mfma_f32_16x16x32_bf16 v[118:121], v[172:175], v[200:203], v[118:121]
	v_mfma_f32_16x16x32_bf16 v[110:113], v[164:167], v[208:211], v[110:113]
	v_mfma_f32_16x16x32_bf16 v[102:105], v[172:175], v[208:211], v[102:105]
	v_mfma_f32_16x16x32_bf16 v[94:97], v[164:167], v[216:219], v[94:97]
	v_mfma_f32_16x16x32_bf16 v[86:89], v[172:175], v[216:219], v[86:89]
	v_mfma_f32_16x16x32_bf16 v[78:81], v[164:167], v[224:227], v[78:81]
	v_mfma_f32_16x16x32_bf16 v[70:73], v[172:175], v[224:227], v[70:73]
	v_mfma_f32_16x16x32_bf16 v[126:129], v[168:171], v[204:207], v[126:129]
	v_mfma_f32_16x16x32_bf16 v[118:121], v[176:179], v[204:207], v[118:121]
	v_mfma_f32_16x16x32_bf16 v[110:113], v[168:171], v[212:215], v[110:113]
	v_mfma_f32_16x16x32_bf16 v[102:105], v[176:179], v[212:215], v[102:105]
	v_mfma_f32_16x16x32_bf16 v[94:97], v[168:171], v[220:223], v[94:97]
	v_mfma_f32_16x16x32_bf16 v[86:89], v[176:179], v[220:223], v[86:89]
	v_mfma_f32_16x16x32_bf16 v[78:81], v[168:171], v[228:231], v[78:81]
	v_mfma_f32_16x16x32_bf16 v[70:73], v[176:179], v[228:231], v[70:73]
	v_mfma_f32_16x16x32_bf16 v[122:125], v[184:187], v[200:203], v[122:125]
	v_mfma_f32_16x16x32_bf16 v[114:117], v[192:195], v[200:203], v[114:117]
	v_mfma_f32_16x16x32_bf16 v[106:109], v[184:187], v[208:211], v[106:109]
	v_mfma_f32_16x16x32_bf16 v[98:101], v[192:195], v[208:211], v[98:101]
	v_mfma_f32_16x16x32_bf16 v[90:93], v[184:187], v[216:219], v[90:93]
	v_mfma_f32_16x16x32_bf16 v[82:85], v[192:195], v[216:219], v[82:85]
	v_mfma_f32_16x16x32_bf16 v[74:77], v[184:187], v[224:227], v[74:77]
	v_mfma_f32_16x16x32_bf16 v[66:69], v[192:195], v[224:227], v[66:69]
	v_mfma_f32_16x16x32_bf16 v[122:125], v[188:191], v[204:207], v[122:125]
	v_mfma_f32_16x16x32_bf16 v[114:117], v[196:199], v[204:207], v[114:117]
	v_mfma_f32_16x16x32_bf16 v[106:109], v[188:191], v[212:215], v[106:109]
	v_mfma_f32_16x16x32_bf16 v[98:101], v[196:199], v[212:215], v[98:101]
	v_mfma_f32_16x16x32_bf16 v[90:93], v[188:191], v[220:223], v[90:93]
	v_mfma_f32_16x16x32_bf16 v[82:85], v[196:199], v[220:223], v[82:85]
	v_mfma_f32_16x16x32_bf16 v[74:77], v[188:191], v[228:231], v[74:77]
	v_mfma_f32_16x16x32_bf16 v[66:69], v[196:199], v[228:231], v[66:69]
	s_barrier
; #define PG8_STAGE(bufoff, gbase, voff) do { _Pragma("unroll") for (int _i = 0; _i < 2; ++_i) \
;         __builtin_amdgcn_global_load_lds((const unsigned*)((const char*)(gbase) + (voff)[_i]), (LAS unsigned*)(lds + (bufoff) + ldsw + _i * 8192), 16, 0, 0); } while (0)
; #define PG8_LDA(dst, b, h) do { _Pragma("unroll") for (int m = 0; m < 4; ++m) _Pragma("unroll") for (int k = 0; k < 2; ++k) dst[m][k] = *(const LAS bf16x8*)(lds + PG8_SA(b, h) + aoff + m * 2048 + k * 1024); } while (0)
; #define PG8_LDB(dst, b, h) do { _Pragma("unroll") for (int n = 0; n < 2; ++n) _Pragma("unroll") for (int k = 0; k < 2; ++k) dst[n][k] = *(const LAS bf16x8*)(lds + PG8_SB(b, h) + boff + n * 2048 + k * 1024); } while (0)
; #define PG8_WAIT_V(n) asm volatile("s_waitcnt vmcnt(" #n ")" ::: "memory")
; #define PG8_BAR __builtin_amdgcn_s_barrier()
; template <class Epi, bool ALIGN_EPI = PG8_ALIGN, bool SP2 = PG8_SP2>
; __device__ __forceinline__ void gemm_phase(LAS uchar* lds, const Gemm g, const StaticOrder& S, const Epi& E) {
;     ...
;             const bool last = (t == nt - 2);
;             const char* a1 = cA + (size_t)(t + 1) * kstep;
;             const char* a2 = last ? nA : cA + (size_t)(t + 2) * kstep; const char* b2 = last ? nB : cB + (size_t)(t + 2) * kstep;
;             const char* a3 = a2 + kstep; const char* b3 = b2 + kstep;
;             if constexpr (SP2) {
;             PG8_LDB(B0, 0, 0); PG8_LDB(B1, 0, 1); PG8_SCHED; PG8_LDA(At, 0, 0); PG8_STAGE(PG8_SA(1, 1), a1 + hstepA, voffA);
;             PG8_WAIT_V(8); PG8_WAIT_L(0); PG8_BAR; PG8_MMA(0, 0, At, B0); PG8_MMA(0, 1, At, B1); PG8_BAR; PG8_SCHED;
;             PG8_LDA(At, 0, 1); PG8_STAGE(PG8_SB(0, 0), b2, voffB); PG8_STAGE(PG8_SB(0, 1), b2 + hstepB, voffB); PG8_STAGE(PG8_SA(0, 0), a2, voffA);
;             PG8_WAIT_V(8); PG8_WAIT_L(0); PG8_BAR; PG8_MMA(1, 0, At, B0); PG8_MMA(1, 1, At, B1); PG8_BAR; PG8_SCHED;
;             PG8_LDB(B0, 1, 0); PG8_LDB(B1, 1, 1); PG8_SCHED; PG8_LDA(At, 1, 0); PG8_STAGE(PG8_SA(0, 1), a2 + hstepA, voffA);
;             PG8_WAIT_V(8); PG8_WAIT_L(0); PG8_BAR; PG8_MMA(0, 0, At, B0); PG8_MMA(0, 1, At, B1); PG8_BAR; PG8_SCHED;
;             PG8_LDA(At, 1, 1); PG8_STAGE(PG8_SB(1, 0), b3, voffB); PG8_STAGE(PG8_SB(1, 1), b3 + hstepB, voffB); PG8_STAGE(PG8_SA(1, 0), a3, voffA);
;             PG8_WAIT_V(8); PG8_WAIT_L(0); PG8_BAR; PG8_MMA(1, 0, At, B0); PG8_MMA(1, 1, At, B1); PG8_BAR; PG8_SCHED;
	s_setprio 0
	v_lshl_add_u64 v[160:161], v[160:161], 0, s[84:85]
	s_add_i32 m0, s21, 0x18000
	ds_read_b128 v[200:203], v163 offset:49152
	ds_read_b128 v[204:207], v163 offset:50176
	ds_read_b128 v[208:211], v163 offset:51200
	ds_read_b128 v[212:215], v163 offset:52224
	ds_read_b128 v[216:219], v163 offset:53248
	ds_read_b128 v[220:223], v163 offset:54272
	ds_read_b128 v[224:227], v163 offset:55296
	ds_read_b128 v[228:231], v163 offset:56320
	global_load_lds_dwordx4 v[160:161], off
	s_add_i32 m0, s21, 0x1a000
	s_add_u32 s12, s16, 0x44080
	v_lshl_add_u64 v[160:161], v[180:181], 0, s[84:85]
	s_addc_u32 s13, s17, 0
	global_load_lds_dwordx4 v[160:161], off
	s_add_i32 m0, s21, 0x1c000
	v_lshl_add_u64 v[160:161], s[12:13], 0, v[134:135]
	global_load_lds_dwordx4 v[160:161], off
	s_add_i32 m0, s21, 0x1e000
	v_lshl_add_u64 v[160:161], s[12:13], 0, v[130:131]
	global_load_lds_dwordx4 v[160:161], off
	s_mov_b32 m0, s27
	v_lshl_add_u64 v[160:161], v[232:233], 0, s[84:85]
	global_load_lds_dwordx4 v[160:161], off
	s_mov_b32 m0, s28
	v_lshl_add_u64 v[160:161], v[234:235], 0, s[84:85]
	global_load_lds_dwordx4 v[160:161], off
	s_waitcnt vmcnt(8)
	s_waitcnt lgkmcnt(0)
	s_setprio 1
	s_barrier
	v_mfma_f32_16x16x32_bf16 v[62:65], v[164:167], v[200:203], v[62:65]
	v_mfma_f32_16x16x32_bf16 v[54:57], v[172:175], v[200:203], v[54:57]
	v_mfma_f32_16x16x32_bf16 v[46:49], v[164:167], v[208:211], v[46:49]
	v_mfma_f32_16x16x32_bf16 v[38:41], v[172:175], v[208:211], v[38:41]
	v_mfma_f32_16x16x32_bf16 v[30:33], v[164:167], v[216:219], v[30:33]
	v_mfma_f32_16x16x32_bf16 v[22:25], v[172:175], v[216:219], v[22:25]
	v_mfma_f32_16x16x32_bf16 v[14:17], v[164:167], v[224:227], v[14:17]
	v_mfma_f32_16x16x32_bf16 v[6:9], v[172:175], v[224:227], v[6:9]
	v_mfma_f32_16x16x32_bf16 v[62:65], v[168:171], v[204:207], v[62:65]
	v_mfma_f32_16x16x32_bf16 v[54:57], v[176:179], v[204:207], v[54:57]
	v_mfma_f32_16x16x32_bf16 v[46:49], v[168:171], v[212:215], v[46:49]
	v_mfma_f32_16x16x32_bf16 v[38:41], v[176:179], v[212:215], v[38:41]
	v_mfma_f32_16x16x32_bf16 v[30:33], v[168:171], v[220:223], v[30:33]
	v_mfma_f32_16x16x32_bf16 v[22:25], v[176:179], v[220:223], v[22:25]
	v_mfma_f32_16x16x32_bf16 v[14:17], v[168:171], v[228:231], v[14:17]
	v_mfma_f32_16x16x32_bf16 v[6:9], v[176:179], v[228:231], v[6:9]
	v_mfma_f32_16x16x32_bf16 v[58:61], v[184:187], v[200:203], v[58:61]
	v_mfma_f32_16x16x32_bf16 v[50:53], v[192:195], v[200:203], v[50:53]
	v_mfma_f32_16x16x32_bf16 v[42:45], v[184:187], v[208:211], v[42:45]
	v_mfma_f32_16x16x32_bf16 v[34:37], v[192:195], v[208:211], v[34:37]
	v_mfma_f32_16x16x32_bf16 v[26:29], v[184:187], v[216:219], v[26:29]
	v_mfma_f32_16x16x32_bf16 v[18:21], v[192:195], v[216:219], v[18:21]
	v_mfma_f32_16x16x32_bf16 v[10:13], v[184:187], v[224:227], v[10:13]
	v_mfma_f32_16x16x32_bf16 v[2:5], v[192:195], v[224:227], v[2:5]
	v_mfma_f32_16x16x32_bf16 v[58:61], v[188:191], v[204:207], v[58:61]
	v_mfma_f32_16x16x32_bf16 v[50:53], v[196:199], v[204:207], v[50:53]
	v_mfma_f32_16x16x32_bf16 v[42:45], v[188:191], v[212:215], v[42:45]
	v_mfma_f32_16x16x32_bf16 v[34:37], v[196:199], v[212:215], v[34:37]
	v_mfma_f32_16x16x32_bf16 v[26:29], v[188:191], v[220:223], v[26:29]
	v_mfma_f32_16x16x32_bf16 v[18:21], v[196:199], v[220:223], v[18:21]
	v_mfma_f32_16x16x32_bf16 v[10:13], v[188:191], v[228:231], v[10:13]
	v_mfma_f32_16x16x32_bf16 v[2:5], v[196:199], v[228:231], v[2:5]
	s_barrier
	s_setprio 0
	s_add_i32 s38, s38, 2
	s_add_u32 s36, s36, 0x100
	s_addc_u32 s37, s37, 0
	s_cmp_gt_u32 s38, 13
	s_mov_b64 s[12:13], s[14:15]
.LBB0_1050:
	s_add_u32 s14, s12, 0x100
	s_addc_u32 s15, s13, 0
	s_cmp_eq_u32 s38, 12
	s_cselect_b32 s19, s1, s15
	s_cselect_b32 s18, s0, s14
	v_add_u32_e32 v144, 0x10000, v139
	s_cselect_b32 s17, s11, s37
	s_cselect_b32 s16, s10, s36
	ds_read_b128 v[164:167], v144
	ds_read_b128 v[168:171], v144 offset:1024
	ds_read_b128 v[172:175], v144 offset:2048
	ds_read_b128 v[176:179], v144 offset:3072
	v_add_u32_e32 v144, 0x14000, v139
	ds_read_b128 v[184:187], v144
	ds_read_b128 v[188:191], v144 offset:1024
	ds_read_b128 v[192:195], v144 offset:2048
	ds_read_b128 v[196:199], v144 offset:3072
	v_lshl_add_u64 v[160:161], s[12:13], 0, v[156:157]
	s_add_i32 m0, s23, 0xc000
	ds_read_b128 v[200:203], v163
	ds_read_b128 v[204:207], v163 offset:1024
	ds_read_b128 v[208:211], v163 offset:2048
	ds_read_b128 v[212:215], v163 offset:3072
	ds_read_b128 v[216:219], v163 offset:4096
	ds_read_b128 v[220:223], v163 offset:5120
	ds_read_b128 v[224:227], v163 offset:6144
	ds_read_b128 v[228:231], v163 offset:7168
	global_load_lds_dwordx4 v[160:161], off
	s_add_i32 m0, s23, 0xe000
	v_lshl_add_u64 v[160:161], s[12:13], 0, v[158:159]
	global_load_lds_dwordx4 v[160:161], off
	s_waitcnt vmcnt(8)
	s_waitcnt lgkmcnt(0)
	s_setprio 1
	s_barrier
; #define PG8_STAGE(bufoff, gbase, voff) do { _Pragma("unroll") for (int _i = 0; _i < 2; ++_i) \
;         __builtin_amdgcn_global_load_lds((const unsigned*)((const char*)(gbase) + (voff)[_i]), (LAS unsigned*)(lds + (bufoff) + ldsw + _i * 8192), 16, 0, 0); } while (0)
; #define PG8_LDA(dst, b, h) do { _Pragma("unroll") for (int m = 0; m < 4; ++m) _Pragma("unroll") for (int k = 0; k < 2; ++k) dst[m][k] = *(const LAS bf16x8*)(lds + PG8_SA(b, h) + aoff + m * 2048 + k * 1024); } while (0)
; #define PG8_MMA(ai, bj, At, Bt) do { __builtin_amdgcn_s_setprio(1); _Pragma("unroll") for (int m = 0; m < 4; ++m) _Pragma("unroll") for (int n = 0; n < 2; ++n) _Pragma("unroll") for (int k = 0; k < 2; ++k) \
;         acc[ai][bj][m][n] = __builtin_amdgcn_mfma_f32_16x16x32_bf16(Bt[n][k], At[m][k], acc[ai][bj][m][n], 0, 0, 0); __builtin_amdgcn_s_setprio(0); } while (0)
; #define PG8_WAIT_V(n) asm volatile("s_waitcnt vmcnt(" #n ")" ::: "memory")
; #define PG8_WAIT_L(n) asm volatile("s_waitcnt lgkmcnt(" #n ")" ::: "memory")
; #define PG8_BAR __builtin_amdgcn_s_barrier()
; #define PG8_SCHED __builtin_amdgcn_sched_barrier(0)
; template <class Epi, bool ALIGN_EPI = PG8_ALIGN, bool SP2 = PG8_SP2>
; __device__ __forceinline__ void gemm_phase(LAS uchar* lds, const Gemm g, const StaticOrder& S, const Epi& E) {
;     ...
;             PG8_WAIT_V(8); PG8_WAIT_L(0); PG8_BAR; PG8_MMA(0, 0, At, B0); PG8_MMA(0, 1, At, B1); PG8_BAR; PG8_SCHED;
;             PG8_LDA(At, 0, 1); PG8_STAGE(PG8_SB(0, 0), b2, voffB); PG8_STAGE(PG8_SB(0, 1), b2 + hstepB, voffB); PG8_STAGE(PG8_SA(0, 0), a2, voffA);
;             PG8_WAIT_V(8); PG8_WAIT_L(0); PG8_BAR; PG8_MMA(1, 0, At, B0); PG8_MMA(1, 1, At, B1); PG8_BAR; PG8_SCHED;
	v_mfma_f32_16x16x32_bf16 v[126:129], v[164:167], v[200:203], v[126:129]
	v_mfma_f32_16x16x32_bf16 v[118:121], v[172:175], v[200:203], v[118:121]
	v_mfma_f32_16x16x32_bf16 v[110:113], v[164:167], v[208:211], v[110:113]
	v_mfma_f32_16x16x32_bf16 v[102:105], v[172:175], v[208:211], v[102:105]
	v_mfma_f32_16x16x32_bf16 v[94:97], v[164:167], v[216:219], v[94:97]
	v_mfma_f32_16x16x32_bf16 v[86:89], v[172:175], v[216:219], v[86:89]
	v_mfma_f32_16x16x32_bf16 v[78:81], v[164:167], v[224:227], v[78:81]
	v_mfma_f32_16x16x32_bf16 v[70:73], v[172:175], v[224:227], v[70:73]
	v_mfma_f32_16x16x32_bf16 v[126:129], v[168:171], v[204:207], v[126:129]
	v_mfma_f32_16x16x32_bf16 v[118:121], v[176:179], v[204:207], v[118:121]
	v_mfma_f32_16x16x32_bf16 v[110:113], v[168:171], v[212:215], v[110:113]
	v_mfma_f32_16x16x32_bf16 v[102:105], v[176:179], v[212:215], v[102:105]
	v_mfma_f32_16x16x32_bf16 v[94:97], v[168:171], v[220:223], v[94:97]
	v_mfma_f32_16x16x32_bf16 v[86:89], v[176:179], v[220:223], v[86:89]
	v_mfma_f32_16x16x32_bf16 v[78:81], v[168:171], v[228:231], v[78:81]
	v_mfma_f32_16x16x32_bf16 v[70:73], v[176:179], v[228:231], v[70:73]
	v_mfma_f32_16x16x32_bf16 v[122:125], v[184:187], v[200:203], v[122:125]
	v_mfma_f32_16x16x32_bf16 v[114:117], v[192:195], v[200:203], v[114:117]
	v_mfma_f32_16x16x32_bf16 v[106:109], v[184:187], v[208:211], v[106:109]
	v_mfma_f32_16x16x32_bf16 v[98:101], v[192:195], v[208:211], v[98:101]
	v_mfma_f32_16x16x32_bf16 v[90:93], v[184:187], v[216:219], v[90:93]
	v_mfma_f32_16x16x32_bf16 v[82:85], v[192:195], v[216:219], v[82:85]
	v_mfma_f32_16x16x32_bf16 v[74:77], v[184:187], v[224:227], v[74:77]
	v_mfma_f32_16x16x32_bf16 v[66:69], v[192:195], v[224:227], v[66:69]
	v_mfma_f32_16x16x32_bf16 v[122:125], v[188:191], v[204:207], v[122:125]
	v_mfma_f32_16x16x32_bf16 v[114:117], v[196:199], v[204:207], v[114:117]
	v_mfma_f32_16x16x32_bf16 v[106:109], v[188:191], v[212:215], v[106:109]
	v_mfma_f32_16x16x32_bf16 v[98:101], v[196:199], v[212:215], v[98:101]
	v_mfma_f32_16x16x32_bf16 v[90:93], v[188:191], v[220:223], v[90:93]
	v_mfma_f32_16x16x32_bf16 v[82:85], v[196:199], v[220:223], v[82:85]
	v_mfma_f32_16x16x32_bf16 v[74:77], v[188:191], v[228:231], v[74:77]
	v_mfma_f32_16x16x32_bf16 v[66:69], v[196:199], v[228:231], v[66:69]
	s_barrier
	s_setprio 0
	v_lshl_add_u64 v[160:161], s[16:17], 0, v[134:135]
	s_add_i32 m0, s21, 0x10000
	ds_read_b128 v[200:203], v163 offset:16384
	ds_read_b128 v[204:207], v163 offset:17408
	ds_read_b128 v[208:211], v163 offset:18432
	ds_read_b128 v[212:215], v163 offset:19456
	ds_read_b128 v[216:219], v163 offset:20480
	ds_read_b128 v[220:223], v163 offset:21504
	ds_read_b128 v[224:227], v163 offset:22528
	ds_read_b128 v[228:231], v163 offset:23552
	global_load_lds_dwordx4 v[160:161], off
	s_add_i32 m0, s21, 0x12000
	s_add_u32 s12, s16, 0x44000
	v_lshl_add_u64 v[180:181], s[16:17], 0, v[130:131]
	s_addc_u32 s13, s17, 0
	global_load_lds_dwordx4 v[180:181], off
	s_add_i32 m0, s21, 0x14000
	v_lshl_add_u64 v[232:233], s[12:13], 0, v[134:135]
	global_load_lds_dwordx4 v[232:233], off
	s_add_i32 m0, s21, 0x16000
	v_lshl_add_u64 v[232:233], s[12:13], 0, v[130:131]
	global_load_lds_dwordx4 v[232:233], off
	s_mov_b32 m0, s23
	v_lshl_add_u64 v[232:233], s[18:19], 0, v[154:155]
	global_load_lds_dwordx4 v[232:233], off
	s_mov_b32 m0, s24
	v_lshl_add_u64 v[234:235], s[18:19], 0, v[132:133]
	global_load_lds_dwordx4 v[234:235], off
	s_waitcnt vmcnt(8)
	s_waitcnt lgkmcnt(0)
	s_setprio 1
	s_barrier
	v_mfma_f32_16x16x32_bf16 v[62:65], v[164:167], v[200:203], v[62:65]
	v_mfma_f32_16x16x32_bf16 v[54:57], v[172:175], v[200:203], v[54:57]
	v_mfma_f32_16x16x32_bf16 v[46:49], v[164:167], v[208:211], v[46:49]
	v_mfma_f32_16x16x32_bf16 v[38:41], v[172:175], v[208:211], v[38:41]
	v_mfma_f32_16x16x32_bf16 v[30:33], v[164:167], v[216:219], v[30:33]
	v_mfma_f32_16x16x32_bf16 v[22:25], v[172:175], v[216:219], v[22:25]
	v_mfma_f32_16x16x32_bf16 v[14:17], v[164:167], v[224:227], v[14:17]
	v_mfma_f32_16x16x32_bf16 v[6:9], v[172:175], v[224:227], v[6:9]
	v_mfma_f32_16x16x32_bf16 v[62:65], v[168:171], v[204:207], v[62:65]
	v_mfma_f32_16x16x32_bf16 v[54:57], v[176:179], v[204:207], v[54:57]
	v_mfma_f32_16x16x32_bf16 v[46:49], v[168:171], v[212:215], v[46:49]
	v_mfma_f32_16x16x32_bf16 v[38:41], v[176:179], v[212:215], v[38:41]
	v_mfma_f32_16x16x32_bf16 v[30:33], v[168:171], v[220:223], v[30:33]
	v_mfma_f32_16x16x32_bf16 v[22:25], v[176:179], v[220:223], v[22:25]
	v_mfma_f32_16x16x32_bf16 v[14:17], v[168:171], v[228:231], v[14:17]
	v_mfma_f32_16x16x32_bf16 v[6:9], v[176:179], v[228:231], v[6:9]
	v_mfma_f32_16x16x32_bf16 v[58:61], v[184:187], v[200:203], v[58:61]
	v_mfma_f32_16x16x32_bf16 v[50:53], v[192:195], v[200:203], v[50:53]
	v_mfma_f32_16x16x32_bf16 v[42:45], v[184:187], v[208:211], v[42:45]
	v_mfma_f32_16x16x32_bf16 v[34:37], v[192:195], v[208:211], v[34:37]
	v_mfma_f32_16x16x32_bf16 v[26:29], v[184:187], v[216:219], v[26:29]
	v_mfma_f32_16x16x32_bf16 v[18:21], v[192:195], v[216:219], v[18:21]
	v_mfma_f32_16x16x32_bf16 v[10:13], v[184:187], v[224:227], v[10:13]
	v_mfma_f32_16x16x32_bf16 v[2:5], v[192:195], v[224:227], v[2:5]
	v_mfma_f32_16x16x32_bf16 v[58:61], v[188:191], v[204:207], v[58:61]
	v_mfma_f32_16x16x32_bf16 v[50:53], v[196:199], v[204:207], v[50:53]
	v_mfma_f32_16x16x32_bf16 v[42:45], v[188:191], v[212:215], v[42:45]
	v_mfma_f32_16x16x32_bf16 v[34:37], v[196:199], v[212:215], v[34:37]
	v_mfma_f32_16x16x32_bf16 v[26:29], v[188:191], v[220:223], v[26:29]
	v_mfma_f32_16x16x32_bf16 v[18:21], v[196:199], v[220:223], v[18:21]
	v_mfma_f32_16x16x32_bf16 v[10:13], v[188:191], v[228:231], v[10:13]
	v_mfma_f32_16x16x32_bf16 v[2:5], v[196:199], v[228:231], v[2:5]
	s_barrier
; #define PG8_STAGE(bufoff, gbase, voff) do { _Pragma("unroll") for (int _i = 0; _i < 2; ++_i) \
;         __builtin_amdgcn_global_load_lds((const unsigned*)((const char*)(gbase) + (voff)[_i]), (LAS unsigned*)(lds + (bufoff) + ldsw + _i * 8192), 16, 0, 0); } while (0)
; #define PG8_LDA(dst, b, h) do { _Pragma("unroll") for (int m = 0; m < 4; ++m) _Pragma("unroll") for (int k = 0; k < 2; ++k) dst[m][k] = *(const LAS bf16x8*)(lds + PG8_SA(b, h) + aoff + m * 2048 + k * 1024); } while (0)
; #define PG8_LDB(dst, b, h) do { _Pragma("unroll") for (int n = 0; n < 2; ++n) _Pragma("unroll") for (int k = 0; k < 2; ++k) dst[n][k] = *(const LAS bf16x8*)(lds + PG8_SB(b, h) + boff + n * 2048 + k * 1024); } while (0)
; #define PG8_MMA(ai, bj, At, Bt) do { __builtin_amdgcn_s_setprio(1); _Pragma("unroll") for (int m = 0; m < 4; ++m) _Pragma("unroll") for (int n = 0; n < 2; ++n) _Pragma("unroll") for (int k = 0; k < 2; ++k) \
;         acc[ai][bj][m][n] = __builtin_amdgcn_mfma_f32_16x16x32_bf16(Bt[n][k], At[m][k], acc[ai][bj][m][n], 0, 0, 0); __builtin_amdgcn_s_setprio(0); } while (0)
; #define PG8_WAIT_V(n) asm volatile("s_waitcnt vmcnt(" #n ")" ::: "memory")
; #define PG8_WAIT_L(n) asm volatile("s_waitcnt lgkmcnt(" #n ")" ::: "memory")
; #define PG8_BAR __builtin_amdgcn_s_barrier()
; #define PG8_SCHED __builtin_amdgcn_sched_barrier(0)
; template <class Epi, bool ALIGN_EPI = PG8_ALIGN, bool SP2 = PG8_SP2>
; __device__ __forceinline__ void gemm_phase(LAS uchar* lds, const Gemm g, const StaticOrder& S, const Epi& E) {
;     ...
;             PG8_LDB(B0, 1, 0); PG8_LDB(B1, 1, 1); PG8_SCHED; PG8_LDA(At, 1, 0); PG8_STAGE(PG8_SA(0, 1), a2 + hstepA, voffA);
;             PG8_WAIT_V(8); PG8_WAIT_L(0); PG8_BAR; PG8_MMA(0, 0, At, B0); PG8_MMA(0, 1, At, B1); PG8_BAR; PG8_SCHED;
;             PG8_LDA(At, 1, 1); PG8_STAGE(PG8_SB(1, 0), b3, voffB); PG8_STAGE(PG8_SB(1, 1), b3 + hstepB, voffB); PG8_STAGE(PG8_SA(1, 0), a3, voffA);
;             PG8_WAIT_V(8); PG8_WAIT_L(0); PG8_BAR; PG8_MMA(1, 0, At, B0); PG8_MMA(1, 1, At, B1); PG8_BAR; PG8_SCHED;
	s_setprio 0
	v_add_u32_e32 v144, 0x18000, v139
	ds_read_b128 v[164:167], v144
	ds_read_b128 v[168:171], v144 offset:1024
	ds_read_b128 v[172:175], v144 offset:2048
	ds_read_b128 v[176:179], v144 offset:3072
	v_add_u32_e32 v144, 0x1c000, v139
	ds_read_b128 v[184:187], v144
	ds_read_b128 v[188:191], v144 offset:1024
	ds_read_b128 v[192:195], v144 offset:2048
	ds_read_b128 v[196:199], v144 offset:3072
	s_add_u32 s12, s18, 0x44000
	s_addc_u32 s13, s19, 0
	s_mov_b32 m0, s25
	v_lshl_add_u64 v[236:237], s[12:13], 0, v[154:155]
	ds_read_b128 v[200:203], v163 offset:32768
	ds_read_b128 v[204:207], v163 offset:33792
	ds_read_b128 v[208:211], v163 offset:34816
	ds_read_b128 v[212:215], v163 offset:35840
	ds_read_b128 v[216:219], v163 offset:36864
	ds_read_b128 v[220:223], v163 offset:37888
	ds_read_b128 v[224:227], v163 offset:38912
	ds_read_b128 v[228:231], v163 offset:39936
	global_load_lds_dwordx4 v[236:237], off
	s_mov_b32 m0, s26
	v_lshl_add_u64 v[236:237], s[12:13], 0, v[132:133]
	global_load_lds_dwordx4 v[236:237], off
	s_waitcnt vmcnt(8)
	s_waitcnt lgkmcnt(0)
	s_setprio 1
	s_barrier
	v_mfma_f32_16x16x32_bf16 v[126:129], v[164:167], v[200:203], v[126:129]
	v_mfma_f32_16x16x32_bf16 v[118:121], v[172:175], v[200:203], v[118:121]
	v_mfma_f32_16x16x32_bf16 v[110:113], v[164:167], v[208:211], v[110:113]
	v_mfma_f32_16x16x32_bf16 v[102:105], v[172:175], v[208:211], v[102:105]
	v_mfma_f32_16x16x32_bf16 v[94:97], v[164:167], v[216:219], v[94:97]
	v_mfma_f32_16x16x32_bf16 v[86:89], v[172:175], v[216:219], v[86:89]
	v_mfma_f32_16x16x32_bf16 v[78:81], v[164:167], v[224:227], v[78:81]
	v_mfma_f32_16x16x32_bf16 v[70:73], v[172:175], v[224:227], v[70:73]
	v_mfma_f32_16x16x32_bf16 v[126:129], v[168:171], v[204:207], v[126:129]
	v_mfma_f32_16x16x32_bf16 v[118:121], v[176:179], v[204:207], v[118:121]
	v_mfma_f32_16x16x32_bf16 v[110:113], v[168:171], v[212:215], v[110:113]
	v_mfma_f32_16x16x32_bf16 v[102:105], v[176:179], v[212:215], v[102:105]
	v_mfma_f32_16x16x32_bf16 v[94:97], v[168:171], v[220:223], v[94:97]
	v_mfma_f32_16x16x32_bf16 v[86:89], v[176:179], v[220:223], v[86:89]
	v_mfma_f32_16x16x32_bf16 v[78:81], v[168:171], v[228:231], v[78:81]
	v_mfma_f32_16x16x32_bf16 v[70:73], v[176:179], v[228:231], v[70:73]
	v_mfma_f32_16x16x32_bf16 v[122:125], v[184:187], v[200:203], v[122:125]
	v_mfma_f32_16x16x32_bf16 v[114:117], v[192:195], v[200:203], v[114:117]
	v_mfma_f32_16x16x32_bf16 v[106:109], v[184:187], v[208:211], v[106:109]
	v_mfma_f32_16x16x32_bf16 v[98:101], v[192:195], v[208:211], v[98:101]
	v_mfma_f32_16x16x32_bf16 v[90:93], v[184:187], v[216:219], v[90:93]
	v_mfma_f32_16x16x32_bf16 v[82:85], v[192:195], v[216:219], v[82:85]
	v_mfma_f32_16x16x32_bf16 v[74:77], v[184:187], v[224:227], v[74:77]
	v_mfma_f32_16x16x32_bf16 v[66:69], v[192:195], v[224:227], v[66:69]
	v_mfma_f32_16x16x32_bf16 v[122:125], v[188:191], v[204:207], v[122:125]
	v_mfma_f32_16x16x32_bf16 v[114:117], v[196:199], v[204:207], v[114:117]
	v_mfma_f32_16x16x32_bf16 v[106:109], v[188:191], v[212:215], v[106:109]
	v_mfma_f32_16x16x32_bf16 v[98:101], v[196:199], v[212:215], v[98:101]
	v_mfma_f32_16x16x32_bf16 v[90:93], v[188:191], v[220:223], v[90:93]
	v_mfma_f32_16x16x32_bf16 v[82:85], v[196:199], v[220:223], v[82:85]
	v_mfma_f32_16x16x32_bf16 v[74:77], v[188:191], v[228:231], v[74:77]
	v_mfma_f32_16x16x32_bf16 v[66:69], v[196:199], v[228:231], v[66:69]
	s_barrier
	s_setprio 0
	v_lshl_add_u64 v[160:161], v[160:161], 0, s[84:85]
	s_add_i32 m0, s21, 0x18000
	ds_read_b128 v[200:203], v163 offset:49152
	ds_read_b128 v[204:207], v163 offset:50176
	ds_read_b128 v[208:211], v163 offset:51200
	ds_read_b128 v[212:215], v163 offset:52224
	ds_read_b128 v[216:219], v163 offset:53248
	ds_read_b128 v[220:223], v163 offset:54272
	ds_read_b128 v[224:227], v163 offset:55296
	ds_read_b128 v[228:231], v163 offset:56320
	global_load_lds_dwordx4 v[160:161], off
	s_add_i32 m0, s21, 0x1a000
	s_add_u32 s12, s16, 0x44080
	v_lshl_add_u64 v[160:161], v[180:181], 0, s[84:85]
	s_addc_u32 s13, s17, 0
	global_load_lds_dwordx4 v[160:161], off
	s_add_i32 m0, s21, 0x1c000
	v_lshl_add_u64 v[160:161], s[12:13], 0, v[134:135]
	global_load_lds_dwordx4 v[160:161], off
	s_add_i32 m0, s21, 0x1e000
	v_lshl_add_u64 v[160:161], s[12:13], 0, v[130:131]
	global_load_lds_dwordx4 v[160:161], off
	s_mov_b32 m0, s27
	v_lshl_add_u64 v[160:161], v[232:233], 0, s[84:85]
	global_load_lds_dwordx4 v[160:161], off
	s_mov_b32 m0, s28
	v_lshl_add_u64 v[160:161], v[234:235], 0, s[84:85]
	global_load_lds_dwordx4 v[160:161], off
	s_waitcnt vmcnt(8)
	s_waitcnt lgkmcnt(0)
	s_setprio 1
	s_barrier
	v_mfma_f32_16x16x32_bf16 v[62:65], v[164:167], v[200:203], v[62:65]
	v_mfma_f32_16x16x32_bf16 v[54:57], v[172:175], v[200:203], v[54:57]
	v_mfma_f32_16x16x32_bf16 v[46:49], v[164:167], v[208:211], v[46:49]
	v_mfma_f32_16x16x32_bf16 v[38:41], v[172:175], v[208:211], v[38:41]
	v_mfma_f32_16x16x32_bf16 v[30:33], v[164:167], v[216:219], v[30:33]
	v_mfma_f32_16x16x32_bf16 v[22:25], v[172:175], v[216:219], v[22:25]
	v_mfma_f32_16x16x32_bf16 v[14:17], v[164:167], v[224:227], v[14:17]
	v_mfma_f32_16x16x32_bf16 v[6:9], v[172:175], v[224:227], v[6:9]
	v_mfma_f32_16x16x32_bf16 v[62:65], v[168:171], v[204:207], v[62:65]
	v_mfma_f32_16x16x32_bf16 v[54:57], v[176:179], v[204:207], v[54:57]
	v_mfma_f32_16x16x32_bf16 v[46:49], v[168:171], v[212:215], v[46:49]
	v_mfma_f32_16x16x32_bf16 v[38:41], v[176:179], v[212:215], v[38:41]
	v_mfma_f32_16x16x32_bf16 v[30:33], v[168:171], v[220:223], v[30:33]
	v_mfma_f32_16x16x32_bf16 v[22:25], v[176:179], v[220:223], v[22:25]
	v_mfma_f32_16x16x32_bf16 v[14:17], v[168:171], v[228:231], v[14:17]
	v_mfma_f32_16x16x32_bf16 v[6:9], v[176:179], v[228:231], v[6:9]
	v_mfma_f32_16x16x32_bf16 v[58:61], v[184:187], v[200:203], v[58:61]
	v_mfma_f32_16x16x32_bf16 v[50:53], v[192:195], v[200:203], v[50:53]
	v_mfma_f32_16x16x32_bf16 v[42:45], v[184:187], v[208:211], v[42:45]
	v_mfma_f32_16x16x32_bf16 v[34:37], v[192:195], v[208:211], v[34:37]
	v_mfma_f32_16x16x32_bf16 v[26:29], v[184:187], v[216:219], v[26:29]
	v_mfma_f32_16x16x32_bf16 v[18:21], v[192:195], v[216:219], v[18:21]
	v_mfma_f32_16x16x32_bf16 v[10:13], v[184:187], v[224:227], v[10:13]
	v_mfma_f32_16x16x32_bf16 v[2:5], v[192:195], v[224:227], v[2:5]
	v_mfma_f32_16x16x32_bf16 v[58:61], v[188:191], v[204:207], v[58:61]
	v_mfma_f32_16x16x32_bf16 v[50:53], v[196:199], v[204:207], v[50:53]
	v_mfma_f32_16x16x32_bf16 v[42:45], v[188:191], v[212:215], v[42:45]
	v_mfma_f32_16x16x32_bf16 v[34:37], v[196:199], v[212:215], v[34:37]
	v_mfma_f32_16x16x32_bf16 v[26:29], v[188:191], v[220:223], v[26:29]
	v_mfma_f32_16x16x32_bf16 v[18:21], v[196:199], v[220:223], v[18:21]
	v_mfma_f32_16x16x32_bf16 v[10:13], v[188:191], v[228:231], v[10:13]
	v_mfma_f32_16x16x32_bf16 v[2:5], v[196:199], v[228:231], v[2:5]
	s_barrier
	s_setprio 0
	s_add_i32 s38, s38, 2
	s_add_u32 s36, s36, 0x100
	s_addc_u32 s37, s37, 0
	s_cmp_gt_u32 s38, 13
	s_mov_b64 s[12:13], s[14:15]
	s_cbranch_scc0 .LBB0_1050
	s_and_b64 vcc, exec, s[8:9]
	s_cbranch_vccz .LBB0_1053
	s_barrier

; #define PG8_STAGE(bufoff, gbase, voff) do { _Pragma("unroll") for (int _i = 0; _i < 2; ++_i) \
;         __builtin_amdgcn_global_load_lds((const unsigned*)((const char*)(gbase) + (voff)[_i]), (LAS unsigned*)(lds + (bufoff) + ldsw + _i * 8192), 16, 0, 0); } while (0)
; #define PG8_LDA(dst, b, h) do { _Pragma("unroll") for (int m = 0; m < 4; ++m) _Pragma("unroll") for (int k = 0; k < 2; ++k) dst[m][k] = *(const LAS bf16x8*)(lds + PG8_SA(b, h) + aoff + m * 2048 + k * 1024); } while (0)
; #define PG8_LDB(dst, b, h) do { _Pragma("unroll") for (int n = 0; n < 2; ++n) _Pragma("unroll") for (int k = 0; k < 2; ++k) dst[n][k] = *(const LAS bf16x8*)(lds + PG8_SB(b, h) + boff + n * 2048 + k * 1024); } while (0)
; #define PG8_MMA(ai, bj, At, Bt) do { __builtin_amdgcn_s_setprio(1); _Pragma("unroll") for (int m = 0; m < 4; ++m) _Pragma("unroll") for (int n = 0; n < 2; ++n) _Pragma("unroll") for (int k = 0; k < 2; ++k) \
;         acc[ai][bj][m][n] = __builtin_amdgcn_mfma_f32_16x16x32_bf16(Bt[n][k], At[m][k], acc[ai][bj][m][n], 0, 0, 0); __builtin_amdgcn_s_setprio(0); } while (0)
; #define PG8_WAIT_V(n) asm volatile("s_waitcnt vmcnt(" #n ")" ::: "memory")
; #define PG8_WAIT_L(n) asm volatile("s_waitcnt lgkmcnt(" #n ")" ::: "memory")
; #define PG8_BAR __builtin_amdgcn_s_barrier()
; #define PG8_SCHED __builtin_amdgcn_sched_barrier(0)
; template <class Epi, bool ALIGN_EPI = PG8_ALIGN, bool SP2 = PG8_SP2>
; __device__ __forceinline__ void gemm_phase(LAS uchar* lds, const Gemm g, const StaticOrder& S, const Epi& E) {
;     ...
;             const bool last = (t == nt - 2);
;             const char* a1 = cA + (size_t)(t + 1) * kstep;
;             const char* a2 = last ? nA : cA + (size_t)(t + 2) * kstep; const char* b2 = last ? nB : cB + (size_t)(t + 2) * kstep;
;             const char* a3 = a2 + kstep; const char* b3 = b2 + kstep;
;             if constexpr (SP2) {
;             PG8_LDB(B0, 0, 0); PG8_LDB(B1, 0, 1); PG8_SCHED; PG8_LDA(At, 0, 0); PG8_STAGE(PG8_SA(1, 1), a1 + hstepA, voffA);
;             PG8_WAIT_V(8); PG8_WAIT_L(0); PG8_BAR; PG8_MMA(0, 0, At, B0); PG8_MMA(0, 1, At, B1); PG8_BAR; PG8_SCHED;
;             PG8_LDA(At, 0, 1); PG8_STAGE(PG8_SB(0, 0), b2, voffB); PG8_STAGE(PG8_SB(0, 1), b2 + hstepB, voffB); PG8_STAGE(PG8_SA(0, 0), a2, voffA);
.LBB0_1142:
	s_add_u32 s38, s16, 0x100
	s_addc_u32 s39, s17, 0
	s_mov_b32 s40, -2
	s_add_u32 s16, s14, 0x100
	s_addc_u32 s17, s15, 0
	s_cmp_eq_u32 s40, 40
	s_cselect_b32 s21, s5, s17
	s_cselect_b32 s20, s4, s16
	v_add_u32_e32 v144, 0x10000, v139
	s_cselect_b32 s19, s13, s39
	s_cselect_b32 s18, s12, s38
	ds_read_b128 v[160:163], v144
	ds_read_b128 v[166:169], v144 offset:1024
	ds_read_b128 v[170:173], v144 offset:2048
	ds_read_b128 v[174:177], v144 offset:3072
	v_add_u32_e32 v144, 0x14000, v139
	ds_read_b128 v[178:181], v144
	ds_read_b128 v[184:187], v144 offset:1024
	ds_read_b128 v[188:191], v144 offset:2048
	ds_read_b128 v[192:195], v144 offset:3072
	v_lshl_add_u64 v[228:229], s[14:15], 0, v[156:157]
	s_add_i32 m0, s25, 0xc000
	ds_read_b128 v[196:199], v165
	ds_read_b128 v[200:203], v165 offset:1024
	ds_read_b128 v[204:207], v165 offset:2048
	ds_read_b128 v[208:211], v165 offset:3072
	ds_read_b128 v[212:215], v165 offset:4096
	ds_read_b128 v[216:219], v165 offset:5120
	ds_read_b128 v[220:223], v165 offset:6144
	ds_read_b128 v[224:227], v165 offset:7168
	global_load_lds_dwordx4 v[228:229], off
	s_add_i32 m0, s25, 0xe000
	v_lshl_add_u64 v[228:229], s[14:15], 0, v[158:159]
	global_load_lds_dwordx4 v[228:229], off
	s_waitcnt vmcnt(8)
	s_waitcnt lgkmcnt(0)
	s_setprio 1
	s_barrier
	v_mfma_f32_16x16x32_bf16 v[126:129], v[160:163], v[196:199], 0
	v_mfma_f32_16x16x32_bf16 v[122:125], v[170:173], v[196:199], 0
	v_mfma_f32_16x16x32_bf16 v[118:121], v[160:163], v[204:207], 0
	v_mfma_f32_16x16x32_bf16 v[110:113], v[170:173], v[204:207], 0
	v_mfma_f32_16x16x32_bf16 v[102:105], v[160:163], v[212:215], 0
	v_mfma_f32_16x16x32_bf16 v[94:97], v[170:173], v[212:215], 0
	v_mfma_f32_16x16x32_bf16 v[86:89], v[160:163], v[220:223], 0
	v_mfma_f32_16x16x32_bf16 v[78:81], v[170:173], v[220:223], 0
	v_mfma_f32_16x16x32_bf16 v[126:129], v[166:169], v[200:203], v[126:129]
	v_mfma_f32_16x16x32_bf16 v[122:125], v[174:177], v[200:203], v[122:125]
	v_mfma_f32_16x16x32_bf16 v[118:121], v[166:169], v[208:211], v[118:121]
	v_mfma_f32_16x16x32_bf16 v[110:113], v[174:177], v[208:211], v[110:113]
	v_mfma_f32_16x16x32_bf16 v[102:105], v[166:169], v[216:219], v[102:105]
	v_mfma_f32_16x16x32_bf16 v[94:97], v[174:177], v[216:219], v[94:97]
	v_mfma_f32_16x16x32_bf16 v[86:89], v[166:169], v[224:227], v[86:89]
	v_mfma_f32_16x16x32_bf16 v[78:81], v[174:177], v[224:227], v[78:81]
	v_mfma_f32_16x16x32_bf16 v[114:117], v[178:181], v[196:199], 0
	v_mfma_f32_16x16x32_bf16 v[106:109], v[188:191], v[196:199], 0
	v_mfma_f32_16x16x32_bf16 v[98:101], v[178:181], v[204:207], 0
	v_mfma_f32_16x16x32_bf16 v[90:93], v[188:191], v[204:207], 0
	v_mfma_f32_16x16x32_bf16 v[82:85], v[178:181], v[212:215], 0
	v_mfma_f32_16x16x32_bf16 v[74:77], v[188:191], v[212:215], 0
	v_mfma_f32_16x16x32_bf16 v[70:73], v[178:181], v[220:223], 0
	v_mfma_f32_16x16x32_bf16 v[66:69], v[188:191], v[220:223], 0
	v_mfma_f32_16x16x32_bf16 v[114:117], v[184:187], v[200:203], v[114:117]
	v_mfma_f32_16x16x32_bf16 v[106:109], v[192:195], v[200:203], v[106:109]
	v_mfma_f32_16x16x32_bf16 v[98:101], v[184:187], v[208:211], v[98:101]
	v_mfma_f32_16x16x32_bf16 v[90:93], v[192:195], v[208:211], v[90:93]
	v_mfma_f32_16x16x32_bf16 v[82:85], v[184:187], v[216:219], v[82:85]
	v_mfma_f32_16x16x32_bf16 v[74:77], v[192:195], v[216:219], v[74:77]
	v_mfma_f32_16x16x32_bf16 v[70:73], v[184:187], v[224:227], v[70:73]
	v_mfma_f32_16x16x32_bf16 v[66:69], v[192:195], v[224:227], v[66:69]
	s_barrier
	s_setprio 0
	v_lshl_add_u64 v[228:229], s[18:19], 0, v[132:133]
	s_add_i32 m0, s24, 0x10000
	ds_read_b128 v[196:199], v165 offset:16384
	ds_read_b128 v[200:203], v165 offset:17408
	ds_read_b128 v[204:207], v165 offset:18432
	ds_read_b128 v[208:211], v165 offset:19456
	ds_read_b128 v[212:215], v165 offset:20480
	ds_read_b128 v[216:219], v165 offset:21504
	ds_read_b128 v[220:223], v165 offset:22528
	ds_read_b128 v[224:227], v165 offset:23552
	global_load_lds_dwordx4 v[228:229], off
	s_add_i32 m0, s24, 0x12000
	s_add_u32 s14, s18, 0xb0000
	v_lshl_add_u64 v[230:231], s[18:19], 0, v[154:155]
	s_addc_u32 s15, s19, 0
	global_load_lds_dwordx4 v[230:231], off
	s_add_i32 m0, s24, 0x14000
	v_lshl_add_u64 v[232:233], s[14:15], 0, v[132:133]
	global_load_lds_dwordx4 v[232:233], off
	s_add_i32 m0, s24, 0x16000
	v_lshl_add_u64 v[232:233], s[14:15], 0, v[154:155]
	global_load_lds_dwordx4 v[232:233], off
	s_mov_b32 m0, s25
	v_lshl_add_u64 v[232:233], s[20:21], 0, v[130:131]
	global_load_lds_dwordx4 v[232:233], off
	s_mov_b32 m0, s26
	v_lshl_add_u64 v[234:235], s[20:21], 0, v[134:135]
	global_load_lds_dwordx4 v[234:235], off
	s_waitcnt vmcnt(8)
	s_waitcnt lgkmcnt(0)
	s_setprio 1
	s_barrier
; #define PG8_STAGE(bufoff, gbase, voff) do { _Pragma("unroll") for (int _i = 0; _i < 2; ++_i) \
;         __builtin_amdgcn_global_load_lds((const unsigned*)((const char*)(gbase) + (voff)[_i]), (LAS unsigned*)(lds + (bufoff) + ldsw + _i * 8192), 16, 0, 0); } while (0)
; #define PG8_LDA(dst, b, h) do { _Pragma("unroll") for (int m = 0; m < 4; ++m) _Pragma("unroll") for (int k = 0; k < 2; ++k) dst[m][k] = *(const LAS bf16x8*)(lds + PG8_SA(b, h) + aoff + m * 2048 + k * 1024); } while (0)
; #define PG8_LDB(dst, b, h) do { _Pragma("unroll") for (int n = 0; n < 2; ++n) _Pragma("unroll") for (int k = 0; k < 2; ++k) dst[n][k] = *(const LAS bf16x8*)(lds + PG8_SB(b, h) + boff + n * 2048 + k * 1024); } while (0)
; #define PG8_MMA(ai, bj, At, Bt) do { __builtin_amdgcn_s_setprio(1); _Pragma("unroll") for (int m = 0; m < 4; ++m) _Pragma("unroll") for (int n = 0; n < 2; ++n) _Pragma("unroll") for (int k = 0; k < 2; ++k) \
;         acc[ai][bj][m][n] = __builtin_amdgcn_mfma_f32_16x16x32_bf16(Bt[n][k], At[m][k], acc[ai][bj][m][n], 0, 0, 0); __builtin_amdgcn_s_setprio(0); } while (0)
; #define PG8_WAIT_V(n) asm volatile("s_waitcnt vmcnt(" #n ")" ::: "memory")
; #define PG8_WAIT_L(n) asm volatile("s_waitcnt lgkmcnt(" #n ")" ::: "memory")
; #define PG8_BAR __builtin_amdgcn_s_barrier()
; #define PG8_SCHED __builtin_amdgcn_sched_barrier(0)
; template <class Epi, bool ALIGN_EPI = PG8_ALIGN, bool SP2 = PG8_SP2>
; __device__ __forceinline__ void gemm_phase(LAS uchar* lds, const Gemm g, const StaticOrder& S, const Epi& E) {
;     ...
;             PG8_WAIT_V(8); PG8_WAIT_L(0); PG8_BAR; PG8_MMA(1, 0, At, B0); PG8_MMA(1, 1, At, B1); PG8_BAR; PG8_SCHED;
;             PG8_LDB(B0, 1, 0); PG8_LDB(B1, 1, 1); PG8_SCHED; PG8_LDA(At, 1, 0); PG8_STAGE(PG8_SA(0, 1), a2 + hstepA, voffA);
;             PG8_WAIT_V(8); PG8_WAIT_L(0); PG8_BAR; PG8_MMA(0, 0, At, B0); PG8_MMA(0, 1, At, B1); PG8_BAR; PG8_SCHED;
	v_mfma_f32_16x16x32_bf16 v[62:65], v[160:163], v[196:199], 0
	v_mfma_f32_16x16x32_bf16 v[58:61], v[170:173], v[196:199], 0
	v_mfma_f32_16x16x32_bf16 v[54:57], v[160:163], v[204:207], 0
	v_mfma_f32_16x16x32_bf16 v[46:49], v[170:173], v[204:207], 0
	v_mfma_f32_16x16x32_bf16 v[38:41], v[160:163], v[212:215], 0
	v_mfma_f32_16x16x32_bf16 v[30:33], v[170:173], v[212:215], 0
	v_mfma_f32_16x16x32_bf16 v[22:25], v[160:163], v[220:223], 0
	v_mfma_f32_16x16x32_bf16 v[14:17], v[170:173], v[220:223], 0
	v_mfma_f32_16x16x32_bf16 v[62:65], v[166:169], v[200:203], v[62:65]
	v_mfma_f32_16x16x32_bf16 v[58:61], v[174:177], v[200:203], v[58:61]
	v_mfma_f32_16x16x32_bf16 v[54:57], v[166:169], v[208:211], v[54:57]
	v_mfma_f32_16x16x32_bf16 v[46:49], v[174:177], v[208:211], v[46:49]
	v_mfma_f32_16x16x32_bf16 v[38:41], v[166:169], v[216:219], v[38:41]
	v_mfma_f32_16x16x32_bf16 v[30:33], v[174:177], v[216:219], v[30:33]
	v_mfma_f32_16x16x32_bf16 v[22:25], v[166:169], v[224:227], v[22:25]
	v_mfma_f32_16x16x32_bf16 v[14:17], v[174:177], v[224:227], v[14:17]
	v_mfma_f32_16x16x32_bf16 v[50:53], v[178:181], v[196:199], 0
	v_mfma_f32_16x16x32_bf16 v[42:45], v[188:191], v[196:199], 0
	v_mfma_f32_16x16x32_bf16 v[34:37], v[178:181], v[204:207], 0
	v_mfma_f32_16x16x32_bf16 v[26:29], v[188:191], v[204:207], 0
	v_mfma_f32_16x16x32_bf16 v[18:21], v[178:181], v[212:215], 0
	v_mfma_f32_16x16x32_bf16 v[10:13], v[188:191], v[212:215], 0
	v_mfma_f32_16x16x32_bf16 v[6:9], v[178:181], v[220:223], 0
	v_mfma_f32_16x16x32_bf16 v[2:5], v[188:191], v[220:223], 0
	v_mfma_f32_16x16x32_bf16 v[50:53], v[184:187], v[200:203], v[50:53]
	v_mfma_f32_16x16x32_bf16 v[42:45], v[192:195], v[200:203], v[42:45]
	v_mfma_f32_16x16x32_bf16 v[34:37], v[184:187], v[208:211], v[34:37]
	v_mfma_f32_16x16x32_bf16 v[26:29], v[192:195], v[208:211], v[26:29]
	v_mfma_f32_16x16x32_bf16 v[18:21], v[184:187], v[216:219], v[18:21]
	v_mfma_f32_16x16x32_bf16 v[10:13], v[192:195], v[216:219], v[10:13]
	v_mfma_f32_16x16x32_bf16 v[6:9], v[184:187], v[224:227], v[6:9]
	v_mfma_f32_16x16x32_bf16 v[2:5], v[192:195], v[224:227], v[2:5]
	s_barrier
	s_setprio 0
	v_add_u32_e32 v144, 0x18000, v139
	ds_read_b128 v[160:163], v144
	ds_read_b128 v[166:169], v144 offset:1024
	ds_read_b128 v[170:173], v144 offset:2048
	ds_read_b128 v[174:177], v144 offset:3072
	v_add_u32_e32 v144, 0x1c000, v139
	ds_read_b128 v[178:181], v144
	ds_read_b128 v[184:187], v144 offset:1024
	ds_read_b128 v[188:191], v144 offset:2048
	ds_read_b128 v[192:195], v144 offset:3072
	s_add_u32 s14, s20, 0xb0000
	s_addc_u32 s15, s21, 0
	s_mov_b32 m0, s27
	v_lshl_add_u64 v[236:237], s[14:15], 0, v[130:131]
	ds_read_b128 v[196:199], v165 offset:32768
	ds_read_b128 v[200:203], v165 offset:33792
	ds_read_b128 v[204:207], v165 offset:34816
	ds_read_b128 v[208:211], v165 offset:35840
	ds_read_b128 v[212:215], v165 offset:36864
	ds_read_b128 v[216:219], v165 offset:37888
	ds_read_b128 v[220:223], v165 offset:38912
	ds_read_b128 v[224:227], v165 offset:39936
	global_load_lds_dwordx4 v[236:237], off
	s_mov_b32 m0, s28
	v_lshl_add_u64 v[236:237], s[14:15], 0, v[134:135]
	global_load_lds_dwordx4 v[236:237], off
	s_waitcnt vmcnt(8)
	s_waitcnt lgkmcnt(0)
	s_setprio 1
	s_barrier
	v_mfma_f32_16x16x32_bf16 v[126:129], v[160:163], v[196:199], v[126:129]
	v_mfma_f32_16x16x32_bf16 v[122:125], v[170:173], v[196:199], v[122:125]
	v_mfma_f32_16x16x32_bf16 v[118:121], v[160:163], v[204:207], v[118:121]
	v_mfma_f32_16x16x32_bf16 v[110:113], v[170:173], v[204:207], v[110:113]
	v_mfma_f32_16x16x32_bf16 v[102:105], v[160:163], v[212:215], v[102:105]
	v_mfma_f32_16x16x32_bf16 v[94:97], v[170:173], v[212:215], v[94:97]
	v_mfma_f32_16x16x32_bf16 v[86:89], v[160:163], v[220:223], v[86:89]
	v_mfma_f32_16x16x32_bf16 v[78:81], v[170:173], v[220:223], v[78:81]
	v_mfma_f32_16x16x32_bf16 v[126:129], v[166:169], v[200:203], v[126:129]
	v_mfma_f32_16x16x32_bf16 v[122:125], v[174:177], v[200:203], v[122:125]
	v_mfma_f32_16x16x32_bf16 v[118:121], v[166:169], v[208:211], v[118:121]
	v_mfma_f32_16x16x32_bf16 v[110:113], v[174:177], v[208:211], v[110:113]
	v_mfma_f32_16x16x32_bf16 v[102:105], v[166:169], v[216:219], v[102:105]
	v_mfma_f32_16x16x32_bf16 v[94:97], v[174:177], v[216:219], v[94:97]
	v_mfma_f32_16x16x32_bf16 v[86:89], v[166:169], v[224:227], v[86:89]
	v_mfma_f32_16x16x32_bf16 v[78:81], v[174:177], v[224:227], v[78:81]
	v_mfma_f32_16x16x32_bf16 v[114:117], v[178:181], v[196:199], v[114:117]
	v_mfma_f32_16x16x32_bf16 v[106:109], v[188:191], v[196:199], v[106:109]
	v_mfma_f32_16x16x32_bf16 v[98:101], v[178:181], v[204:207], v[98:101]
	v_mfma_f32_16x16x32_bf16 v[90:93], v[188:191], v[204:207], v[90:93]
	v_mfma_f32_16x16x32_bf16 v[82:85], v[178:181], v[212:215], v[82:85]
	v_mfma_f32_16x16x32_bf16 v[74:77], v[188:191], v[212:215], v[74:77]
	v_mfma_f32_16x16x32_bf16 v[70:73], v[178:181], v[220:223], v[70:73]
	v_mfma_f32_16x16x32_bf16 v[66:69], v[188:191], v[220:223], v[66:69]
	v_mfma_f32_16x16x32_bf16 v[114:117], v[184:187], v[200:203], v[114:117]
	v_mfma_f32_16x16x32_bf16 v[106:109], v[192:195], v[200:203], v[106:109]
	v_mfma_f32_16x16x32_bf16 v[98:101], v[184:187], v[208:211], v[98:101]
	v_mfma_f32_16x16x32_bf16 v[90:93], v[192:195], v[208:211], v[90:93]
	v_mfma_f32_16x16x32_bf16 v[82:85], v[184:187], v[216:219], v[82:85]
	v_mfma_f32_16x16x32_bf16 v[74:77], v[192:195], v[216:219], v[74:77]
	v_mfma_f32_16x16x32_bf16 v[70:73], v[184:187], v[224:227], v[70:73]
	v_mfma_f32_16x16x32_bf16 v[66:69], v[192:195], v[224:227], v[66:69]
	s_barrier
; #define PG8_STAGE(bufoff, gbase, voff) do { _Pragma("unroll") for (int _i = 0; _i < 2; ++_i) \
;         __builtin_amdgcn_global_load_lds((const unsigned*)((const char*)(gbase) + (voff)[_i]), (LAS unsigned*)(lds + (bufoff) + ldsw + _i * 8192), 16, 0, 0); } while (0)
; #define PG8_LDA(dst, b, h) do { _Pragma("unroll") for (int m = 0; m < 4; ++m) _Pragma("unroll") for (int k = 0; k < 2; ++k) dst[m][k] = *(const LAS bf16x8*)(lds + PG8_SA(b, h) + aoff + m * 2048 + k * 1024); } while (0)
; #define PG8_LDB(dst, b, h) do { _Pragma("unroll") for (int n = 0; n < 2; ++n) _Pragma("unroll") for (int k = 0; k < 2; ++k) dst[n][k] = *(const LAS bf16x8*)(lds + PG8_SB(b, h) + boff + n * 2048 + k * 1024); } while (0)
; #define PG8_WAIT_V(n) asm volatile("s_waitcnt vmcnt(" #n ")" ::: "memory")
; #define PG8_BAR __builtin_amdgcn_s_barrier()
; template <class Epi, bool ALIGN_EPI = PG8_ALIGN, bool SP2 = PG8_SP2>
; __device__ __forceinline__ void gemm_phase(LAS uchar* lds, const Gemm g, const StaticOrder& S, const Epi& E) {
;     ...
;             const bool last = (t == nt - 2);
;             const char* a1 = cA + (size_t)(t + 1) * kstep;
;             const char* a2 = last ? nA : cA + (size_t)(t + 2) * kstep; const char* b2 = last ? nB : cB + (size_t)(t + 2) * kstep;
;             const char* a3 = a2 + kstep; const char* b3 = b2 + kstep;
;             if constexpr (SP2) {
;             PG8_LDB(B0, 0, 0); PG8_LDB(B1, 0, 1); PG8_SCHED; PG8_LDA(At, 0, 0); PG8_STAGE(PG8_SA(1, 1), a1 + hstepA, voffA);
;             PG8_WAIT_V(8); PG8_WAIT_L(0); PG8_BAR; PG8_MMA(0, 0, At, B0); PG8_MMA(0, 1, At, B1); PG8_BAR; PG8_SCHED;
;             PG8_LDA(At, 0, 1); PG8_STAGE(PG8_SB(0, 0), b2, voffB); PG8_STAGE(PG8_SB(0, 1), b2 + hstepB, voffB); PG8_STAGE(PG8_SA(0, 0), a2, voffA);
;             PG8_WAIT_V(8); PG8_WAIT_L(0); PG8_BAR; PG8_MMA(1, 0, At, B0); PG8_MMA(1, 1, At, B1); PG8_BAR; PG8_SCHED;
;             PG8_LDB(B0, 1, 0); PG8_LDB(B1, 1, 1); PG8_SCHED; PG8_LDA(At, 1, 0); PG8_STAGE(PG8_SA(0, 1), a2 + hstepA, voffA);
;             PG8_WAIT_V(8); PG8_WAIT_L(0); PG8_BAR; PG8_MMA(0, 0, At, B0); PG8_MMA(0, 1, At, B1); PG8_BAR; PG8_SCHED;
;             PG8_LDA(At, 1, 1); PG8_STAGE(PG8_SB(1, 0), b3, voffB); PG8_STAGE(PG8_SB(1, 1), b3 + hstepB, voffB); PG8_STAGE(PG8_SA(1, 0), a3, voffA);
;             PG8_WAIT_V(8); PG8_WAIT_L(0); PG8_BAR; PG8_MMA(1, 0, At, B0); PG8_MMA(1, 1, At, B1); PG8_BAR; PG8_SCHED;
	s_setprio 0
	v_lshl_add_u64 v[228:229], v[228:229], 0, s[84:85]
	s_add_i32 m0, s24, 0x18000
	ds_read_b128 v[196:199], v165 offset:49152
	ds_read_b128 v[200:203], v165 offset:50176
	ds_read_b128 v[204:207], v165 offset:51200
	ds_read_b128 v[208:211], v165 offset:52224
	ds_read_b128 v[212:215], v165 offset:53248
	ds_read_b128 v[216:219], v165 offset:54272
	ds_read_b128 v[220:223], v165 offset:55296
	ds_read_b128 v[224:227], v165 offset:56320
	global_load_lds_dwordx4 v[228:229], off
	s_add_i32 m0, s24, 0x1a000
	s_add_u32 s14, s18, 0xb0080
	v_lshl_add_u64 v[228:229], v[230:231], 0, s[84:85]
	s_addc_u32 s15, s19, 0
	global_load_lds_dwordx4 v[228:229], off
	s_add_i32 m0, s24, 0x1c000
	v_lshl_add_u64 v[228:229], s[14:15], 0, v[132:133]
	global_load_lds_dwordx4 v[228:229], off
	s_add_i32 m0, s24, 0x1e000
	v_lshl_add_u64 v[228:229], s[14:15], 0, v[154:155]
	global_load_lds_dwordx4 v[228:229], off
	s_mov_b32 m0, s29
	v_lshl_add_u64 v[228:229], v[232:233], 0, s[84:85]
	global_load_lds_dwordx4 v[228:229], off
	s_mov_b32 m0, s30
	v_lshl_add_u64 v[228:229], v[234:235], 0, s[84:85]
	global_load_lds_dwordx4 v[228:229], off
	s_waitcnt vmcnt(8)
	s_waitcnt lgkmcnt(0)
	s_setprio 1
	s_barrier
	v_mfma_f32_16x16x32_bf16 v[62:65], v[160:163], v[196:199], v[62:65]
	v_mfma_f32_16x16x32_bf16 v[58:61], v[170:173], v[196:199], v[58:61]
	v_mfma_f32_16x16x32_bf16 v[54:57], v[160:163], v[204:207], v[54:57]
	v_mfma_f32_16x16x32_bf16 v[46:49], v[170:173], v[204:207], v[46:49]
	v_mfma_f32_16x16x32_bf16 v[38:41], v[160:163], v[212:215], v[38:41]
	v_mfma_f32_16x16x32_bf16 v[30:33], v[170:173], v[212:215], v[30:33]
	v_mfma_f32_16x16x32_bf16 v[22:25], v[160:163], v[220:223], v[22:25]
	v_mfma_f32_16x16x32_bf16 v[14:17], v[170:173], v[220:223], v[14:17]
	v_mfma_f32_16x16x32_bf16 v[62:65], v[166:169], v[200:203], v[62:65]
	v_mfma_f32_16x16x32_bf16 v[58:61], v[174:177], v[200:203], v[58:61]
	v_mfma_f32_16x16x32_bf16 v[54:57], v[166:169], v[208:211], v[54:57]
	v_mfma_f32_16x16x32_bf16 v[46:49], v[174:177], v[208:211], v[46:49]
	v_mfma_f32_16x16x32_bf16 v[38:41], v[166:169], v[216:219], v[38:41]
	v_mfma_f32_16x16x32_bf16 v[30:33], v[174:177], v[216:219], v[30:33]
	v_mfma_f32_16x16x32_bf16 v[22:25], v[166:169], v[224:227], v[22:25]
	v_mfma_f32_16x16x32_bf16 v[14:17], v[174:177], v[224:227], v[14:17]
	v_mfma_f32_16x16x32_bf16 v[50:53], v[178:181], v[196:199], v[50:53]
	v_mfma_f32_16x16x32_bf16 v[42:45], v[188:191], v[196:199], v[42:45]
	v_mfma_f32_16x16x32_bf16 v[34:37], v[178:181], v[204:207], v[34:37]
	v_mfma_f32_16x16x32_bf16 v[26:29], v[188:191], v[204:207], v[26:29]
	v_mfma_f32_16x16x32_bf16 v[18:21], v[178:181], v[212:215], v[18:21]
	v_mfma_f32_16x16x32_bf16 v[10:13], v[188:191], v[212:215], v[10:13]
	v_mfma_f32_16x16x32_bf16 v[6:9], v[178:181], v[220:223], v[6:9]
	v_mfma_f32_16x16x32_bf16 v[2:5], v[188:191], v[220:223], v[2:5]
	v_mfma_f32_16x16x32_bf16 v[50:53], v[184:187], v[200:203], v[50:53]
	v_mfma_f32_16x16x32_bf16 v[42:45], v[192:195], v[200:203], v[42:45]
	v_mfma_f32_16x16x32_bf16 v[34:37], v[184:187], v[208:211], v[34:37]
	v_mfma_f32_16x16x32_bf16 v[26:29], v[192:195], v[208:211], v[26:29]
	v_mfma_f32_16x16x32_bf16 v[18:21], v[184:187], v[216:219], v[18:21]
	v_mfma_f32_16x16x32_bf16 v[10:13], v[192:195], v[216:219], v[10:13]
	v_mfma_f32_16x16x32_bf16 v[6:9], v[184:187], v[224:227], v[6:9]
	v_mfma_f32_16x16x32_bf16 v[2:5], v[192:195], v[224:227], v[2:5]
	s_barrier
	s_setprio 0
	s_add_i32 s40, s40, 2
	s_add_u32 s38, s38, 0x100
	s_addc_u32 s39, s39, 0
	s_cmp_gt_u32 s40, 41
	s_mov_b64 s[14:15], s[16:17]
.LBB0_1143:
	s_add_u32 s16, s14, 0x100
	s_addc_u32 s17, s15, 0
	s_cmp_eq_u32 s40, 40
	s_cselect_b32 s21, s5, s17
	s_cselect_b32 s20, s4, s16
	v_add_u32_e32 v144, 0x10000, v139
	s_cselect_b32 s19, s13, s39
	s_cselect_b32 s18, s12, s38
	ds_read_b128 v[160:163], v144
	ds_read_b128 v[166:169], v144 offset:1024
	ds_read_b128 v[170:173], v144 offset:2048
	ds_read_b128 v[174:177], v144 offset:3072
	v_add_u32_e32 v144, 0x14000, v139
	ds_read_b128 v[178:181], v144
	ds_read_b128 v[184:187], v144 offset:1024
	ds_read_b128 v[188:191], v144 offset:2048
	ds_read_b128 v[192:195], v144 offset:3072
	v_lshl_add_u64 v[228:229], s[14:15], 0, v[156:157]
	s_add_i32 m0, s25, 0xc000
	ds_read_b128 v[196:199], v165
	ds_read_b128 v[200:203], v165 offset:1024
	ds_read_b128 v[204:207], v165 offset:2048
	ds_read_b128 v[208:211], v165 offset:3072
	ds_read_b128 v[212:215], v165 offset:4096
	ds_read_b128 v[216:219], v165 offset:5120
	ds_read_b128 v[220:223], v165 offset:6144
	ds_read_b128 v[224:227], v165 offset:7168
	global_load_lds_dwordx4 v[228:229], off
	s_add_i32 m0, s25, 0xe000
	v_lshl_add_u64 v[228:229], s[14:15], 0, v[158:159]
	global_load_lds_dwordx4 v[228:229], off
	s_waitcnt vmcnt(8)
	s_waitcnt lgkmcnt(0)
	s_setprio 1
	s_barrier
; #define PG8_STAGE(bufoff, gbase, voff) do { _Pragma("unroll") for (int _i = 0; _i < 2; ++_i) \
;         __builtin_amdgcn_global_load_lds((const unsigned*)((const char*)(gbase) + (voff)[_i]), (LAS unsigned*)(lds + (bufoff) + ldsw + _i * 8192), 16, 0, 0); } while (0)
; #define PG8_LDA(dst, b, h) do { _Pragma("unroll") for (int m = 0; m < 4; ++m) _Pragma("unroll") for (int k = 0; k < 2; ++k) dst[m][k] = *(const LAS bf16x8*)(lds + PG8_SA(b, h) + aoff + m * 2048 + k * 1024); } while (0)
; #define PG8_MMA(ai, bj, At, Bt) do { __builtin_amdgcn_s_setprio(1); _Pragma("unroll") for (int m = 0; m < 4; ++m) _Pragma("unroll") for (int n = 0; n < 2; ++n) _Pragma("unroll") for (int k = 0; k < 2; ++k) \
;         acc[ai][bj][m][n] = __builtin_amdgcn_mfma_f32_16x16x32_bf16(Bt[n][k], At[m][k], acc[ai][bj][m][n], 0, 0, 0); __builtin_amdgcn_s_setprio(0); } while (0)
; #define PG8_WAIT_V(n) asm volatile("s_waitcnt vmcnt(" #n ")" ::: "memory")
; #define PG8_WAIT_L(n) asm volatile("s_waitcnt lgkmcnt(" #n ")" ::: "memory")
; #define PG8_BAR __builtin_amdgcn_s_barrier()
; #define PG8_SCHED __builtin_amdgcn_sched_barrier(0)
; template <class Epi, bool ALIGN_EPI = PG8_ALIGN, bool SP2 = PG8_SP2>
; __device__ __forceinline__ void gemm_phase(LAS uchar* lds, const Gemm g, const StaticOrder& S, const Epi& E) {
;     ...
;             PG8_WAIT_V(8); PG8_WAIT_L(0); PG8_BAR; PG8_MMA(0, 0, At, B0); PG8_MMA(0, 1, At, B1); PG8_BAR; PG8_SCHED;
;             PG8_LDA(At, 0, 1); PG8_STAGE(PG8_SB(0, 0), b2, voffB); PG8_STAGE(PG8_SB(0, 1), b2 + hstepB, voffB); PG8_STAGE(PG8_SA(0, 0), a2, voffA);
;             PG8_WAIT_V(8); PG8_WAIT_L(0); PG8_BAR; PG8_MMA(1, 0, At, B0); PG8_MMA(1, 1, At, B1); PG8_BAR; PG8_SCHED;
	v_mfma_f32_16x16x32_bf16 v[126:129], v[160:163], v[196:199], v[126:129]
	v_mfma_f32_16x16x32_bf16 v[122:125], v[170:173], v[196:199], v[122:125]
	v_mfma_f32_16x16x32_bf16 v[118:121], v[160:163], v[204:207], v[118:121]
	v_mfma_f32_16x16x32_bf16 v[110:113], v[170:173], v[204:207], v[110:113]
	v_mfma_f32_16x16x32_bf16 v[102:105], v[160:163], v[212:215], v[102:105]
	v_mfma_f32_16x16x32_bf16 v[94:97], v[170:173], v[212:215], v[94:97]
	v_mfma_f32_16x16x32_bf16 v[86:89], v[160:163], v[220:223], v[86:89]
	v_mfma_f32_16x16x32_bf16 v[78:81], v[170:173], v[220:223], v[78:81]
	v_mfma_f32_16x16x32_bf16 v[126:129], v[166:169], v[200:203], v[126:129]
	v_mfma_f32_16x16x32_bf16 v[122:125], v[174:177], v[200:203], v[122:125]
	v_mfma_f32_16x16x32_bf16 v[118:121], v[166:169], v[208:211], v[118:121]
	v_mfma_f32_16x16x32_bf16 v[110:113], v[174:177], v[208:211], v[110:113]
	v_mfma_f32_16x16x32_bf16 v[102:105], v[166:169], v[216:219], v[102:105]
	v_mfma_f32_16x16x32_bf16 v[94:97], v[174:177], v[216:219], v[94:97]
	v_mfma_f32_16x16x32_bf16 v[86:89], v[166:169], v[224:227], v[86:89]
	v_mfma_f32_16x16x32_bf16 v[78:81], v[174:177], v[224:227], v[78:81]
	v_mfma_f32_16x16x32_bf16 v[114:117], v[178:181], v[196:199], v[114:117]
	v_mfma_f32_16x16x32_bf16 v[106:109], v[188:191], v[196:199], v[106:109]
	v_mfma_f32_16x16x32_bf16 v[98:101], v[178:181], v[204:207], v[98:101]
	v_mfma_f32_16x16x32_bf16 v[90:93], v[188:191], v[204:207], v[90:93]
	v_mfma_f32_16x16x32_bf16 v[82:85], v[178:181], v[212:215], v[82:85]
	v_mfma_f32_16x16x32_bf16 v[74:77], v[188:191], v[212:215], v[74:77]
	v_mfma_f32_16x16x32_bf16 v[70:73], v[178:181], v[220:223], v[70:73]
	v_mfma_f32_16x16x32_bf16 v[66:69], v[188:191], v[220:223], v[66:69]
	v_mfma_f32_16x16x32_bf16 v[114:117], v[184:187], v[200:203], v[114:117]
	v_mfma_f32_16x16x32_bf16 v[106:109], v[192:195], v[200:203], v[106:109]
	v_mfma_f32_16x16x32_bf16 v[98:101], v[184:187], v[208:211], v[98:101]
	v_mfma_f32_16x16x32_bf16 v[90:93], v[192:195], v[208:211], v[90:93]
	v_mfma_f32_16x16x32_bf16 v[82:85], v[184:187], v[216:219], v[82:85]
	v_mfma_f32_16x16x32_bf16 v[74:77], v[192:195], v[216:219], v[74:77]
	v_mfma_f32_16x16x32_bf16 v[70:73], v[184:187], v[224:227], v[70:73]
	v_mfma_f32_16x16x32_bf16 v[66:69], v[192:195], v[224:227], v[66:69]
	s_barrier
	s_setprio 0
	v_lshl_add_u64 v[228:229], s[18:19], 0, v[132:133]
	s_add_i32 m0, s24, 0x10000
	ds_read_b128 v[196:199], v165 offset:16384
	ds_read_b128 v[200:203], v165 offset:17408
	ds_read_b128 v[204:207], v165 offset:18432
	ds_read_b128 v[208:211], v165 offset:19456
	ds_read_b128 v[212:215], v165 offset:20480
	ds_read_b128 v[216:219], v165 offset:21504
	ds_read_b128 v[220:223], v165 offset:22528
	ds_read_b128 v[224:227], v165 offset:23552
	global_load_lds_dwordx4 v[228:229], off
	s_add_i32 m0, s24, 0x12000
	s_add_u32 s14, s18, 0xb0000
	v_lshl_add_u64 v[230:231], s[18:19], 0, v[154:155]
	s_addc_u32 s15, s19, 0
	global_load_lds_dwordx4 v[230:231], off
	s_add_i32 m0, s24, 0x14000
	v_lshl_add_u64 v[232:233], s[14:15], 0, v[132:133]
	global_load_lds_dwordx4 v[232:233], off
	s_add_i32 m0, s24, 0x16000
	v_lshl_add_u64 v[232:233], s[14:15], 0, v[154:155]
	global_load_lds_dwordx4 v[232:233], off
	s_mov_b32 m0, s25
	v_lshl_add_u64 v[232:233], s[20:21], 0, v[130:131]
	global_load_lds_dwordx4 v[232:233], off
	s_mov_b32 m0, s26
	v_lshl_add_u64 v[234:235], s[20:21], 0, v[134:135]
	global_load_lds_dwordx4 v[234:235], off
	s_waitcnt vmcnt(8)
	s_waitcnt lgkmcnt(0)
	s_setprio 1
	s_barrier
	v_mfma_f32_16x16x32_bf16 v[62:65], v[160:163], v[196:199], v[62:65]
	v_mfma_f32_16x16x32_bf16 v[58:61], v[170:173], v[196:199], v[58:61]
	v_mfma_f32_16x16x32_bf16 v[54:57], v[160:163], v[204:207], v[54:57]
	v_mfma_f32_16x16x32_bf16 v[46:49], v[170:173], v[204:207], v[46:49]
	v_mfma_f32_16x16x32_bf16 v[38:41], v[160:163], v[212:215], v[38:41]
	v_mfma_f32_16x16x32_bf16 v[30:33], v[170:173], v[212:215], v[30:33]
	v_mfma_f32_16x16x32_bf16 v[22:25], v[160:163], v[220:223], v[22:25]
	v_mfma_f32_16x16x32_bf16 v[14:17], v[170:173], v[220:223], v[14:17]
	v_mfma_f32_16x16x32_bf16 v[62:65], v[166:169], v[200:203], v[62:65]
	v_mfma_f32_16x16x32_bf16 v[58:61], v[174:177], v[200:203], v[58:61]
	v_mfma_f32_16x16x32_bf16 v[54:57], v[166:169], v[208:211], v[54:57]
	v_mfma_f32_16x16x32_bf16 v[46:49], v[174:177], v[208:211], v[46:49]
	v_mfma_f32_16x16x32_bf16 v[38:41], v[166:169], v[216:219], v[38:41]
	v_mfma_f32_16x16x32_bf16 v[30:33], v[174:177], v[216:219], v[30:33]
	v_mfma_f32_16x16x32_bf16 v[22:25], v[166:169], v[224:227], v[22:25]
	v_mfma_f32_16x16x32_bf16 v[14:17], v[174:177], v[224:227], v[14:17]
	v_mfma_f32_16x16x32_bf16 v[50:53], v[178:181], v[196:199], v[50:53]
	v_mfma_f32_16x16x32_bf16 v[42:45], v[188:191], v[196:199], v[42:45]
	v_mfma_f32_16x16x32_bf16 v[34:37], v[178:181], v[204:207], v[34:37]
	v_mfma_f32_16x16x32_bf16 v[26:29], v[188:191], v[204:207], v[26:29]
	v_mfma_f32_16x16x32_bf16 v[18:21], v[178:181], v[212:215], v[18:21]
	v_mfma_f32_16x16x32_bf16 v[10:13], v[188:191], v[212:215], v[10:13]
	v_mfma_f32_16x16x32_bf16 v[6:9], v[178:181], v[220:223], v[6:9]
	v_mfma_f32_16x16x32_bf16 v[2:5], v[188:191], v[220:223], v[2:5]
	v_mfma_f32_16x16x32_bf16 v[50:53], v[184:187], v[200:203], v[50:53]
	v_mfma_f32_16x16x32_bf16 v[42:45], v[192:195], v[200:203], v[42:45]
	v_mfma_f32_16x16x32_bf16 v[34:37], v[184:187], v[208:211], v[34:37]
	v_mfma_f32_16x16x32_bf16 v[26:29], v[192:195], v[208:211], v[26:29]
	v_mfma_f32_16x16x32_bf16 v[18:21], v[184:187], v[216:219], v[18:21]
	v_mfma_f32_16x16x32_bf16 v[10:13], v[192:195], v[216:219], v[10:13]
	v_mfma_f32_16x16x32_bf16 v[6:9], v[184:187], v[224:227], v[6:9]
	v_mfma_f32_16x16x32_bf16 v[2:5], v[192:195], v[224:227], v[2:5]
	s_barrier
; #define PG8_STAGE(bufoff, gbase, voff) do { _Pragma("unroll") for (int _i = 0; _i < 2; ++_i) \
;         __builtin_amdgcn_global_load_lds((const unsigned*)((const char*)(gbase) + (voff)[_i]), (LAS unsigned*)(lds + (bufoff) + ldsw + _i * 8192), 16, 0, 0); } while (0)
; #define PG8_LDA(dst, b, h) do { _Pragma("unroll") for (int m = 0; m < 4; ++m) _Pragma("unroll") for (int k = 0; k < 2; ++k) dst[m][k] = *(const LAS bf16x8*)(lds + PG8_SA(b, h) + aoff + m * 2048 + k * 1024); } while (0)
; #define PG8_LDB(dst, b, h) do { _Pragma("unroll") for (int n = 0; n < 2; ++n) _Pragma("unroll") for (int k = 0; k < 2; ++k) dst[n][k] = *(const LAS bf16x8*)(lds + PG8_SB(b, h) + boff + n * 2048 + k * 1024); } while (0)
; #define PG8_MMA(ai, bj, At, Bt) do { __builtin_amdgcn_s_setprio(1); _Pragma("unroll") for (int m = 0; m < 4; ++m) _Pragma("unroll") for (int n = 0; n < 2; ++n) _Pragma("unroll") for (int k = 0; k < 2; ++k) \
;         acc[ai][bj][m][n] = __builtin_amdgcn_mfma_f32_16x16x32_bf16(Bt[n][k], At[m][k], acc[ai][bj][m][n], 0, 0, 0); __builtin_amdgcn_s_setprio(0); } while (0)
; #define PG8_WAIT_V(n) asm volatile("s_waitcnt vmcnt(" #n ")" ::: "memory")
; #define PG8_WAIT_L(n) asm volatile("s_waitcnt lgkmcnt(" #n ")" ::: "memory")
; #define PG8_BAR __builtin_amdgcn_s_barrier()
; #define PG8_SCHED __builtin_amdgcn_sched_barrier(0)
; template <class Epi, bool ALIGN_EPI = PG8_ALIGN, bool SP2 = PG8_SP2>
; __device__ __forceinline__ void gemm_phase(LAS uchar* lds, const Gemm g, const StaticOrder& S, const Epi& E) {
;     ...
;             PG8_LDB(B0, 1, 0); PG8_LDB(B1, 1, 1); PG8_SCHED; PG8_LDA(At, 1, 0); PG8_STAGE(PG8_SA(0, 1), a2 + hstepA, voffA);
;             PG8_WAIT_V(8); PG8_WAIT_L(0); PG8_BAR; PG8_MMA(0, 0, At, B0); PG8_MMA(0, 1, At, B1); PG8_BAR; PG8_SCHED;
;             PG8_LDA(At, 1, 1); PG8_STAGE(PG8_SB(1, 0), b3, voffB); PG8_STAGE(PG8_SB(1, 1), b3 + hstepB, voffB); PG8_STAGE(PG8_SA(1, 0), a3, voffA);
;             PG8_WAIT_V(8); PG8_WAIT_L(0); PG8_BAR; PG8_MMA(1, 0, At, B0); PG8_MMA(1, 1, At, B1); PG8_BAR; PG8_SCHED;
	s_setprio 0
	v_add_u32_e32 v144, 0x18000, v139
	ds_read_b128 v[160:163], v144
	ds_read_b128 v[166:169], v144 offset:1024
	ds_read_b128 v[170:173], v144 offset:2048
	ds_read_b128 v[174:177], v144 offset:3072
	v_add_u32_e32 v144, 0x1c000, v139
	ds_read_b128 v[178:181], v144
	ds_read_b128 v[184:187], v144 offset:1024
	ds_read_b128 v[188:191], v144 offset:2048
	ds_read_b128 v[192:195], v144 offset:3072
	s_add_u32 s14, s20, 0xb0000
	s_addc_u32 s15, s21, 0
	s_mov_b32 m0, s27
	v_lshl_add_u64 v[236:237], s[14:15], 0, v[130:131]
	ds_read_b128 v[196:199], v165 offset:32768
	ds_read_b128 v[200:203], v165 offset:33792
	ds_read_b128 v[204:207], v165 offset:34816
	ds_read_b128 v[208:211], v165 offset:35840
	ds_read_b128 v[212:215], v165 offset:36864
	ds_read_b128 v[216:219], v165 offset:37888
	ds_read_b128 v[220:223], v165 offset:38912
	ds_read_b128 v[224:227], v165 offset:39936
	global_load_lds_dwordx4 v[236:237], off
	s_mov_b32 m0, s28
	v_lshl_add_u64 v[236:237], s[14:15], 0, v[134:135]
	global_load_lds_dwordx4 v[236:237], off
	s_waitcnt vmcnt(8)
	s_waitcnt lgkmcnt(0)
	s_setprio 1
	s_barrier
	v_mfma_f32_16x16x32_bf16 v[126:129], v[160:163], v[196:199], v[126:129]
	v_mfma_f32_16x16x32_bf16 v[122:125], v[170:173], v[196:199], v[122:125]
	v_mfma_f32_16x16x32_bf16 v[118:121], v[160:163], v[204:207], v[118:121]
	v_mfma_f32_16x16x32_bf16 v[110:113], v[170:173], v[204:207], v[110:113]
	v_mfma_f32_16x16x32_bf16 v[102:105], v[160:163], v[212:215], v[102:105]
	v_mfma_f32_16x16x32_bf16 v[94:97], v[170:173], v[212:215], v[94:97]
	v_mfma_f32_16x16x32_bf16 v[86:89], v[160:163], v[220:223], v[86:89]
	v_mfma_f32_16x16x32_bf16 v[78:81], v[170:173], v[220:223], v[78:81]
	v_mfma_f32_16x16x32_bf16 v[126:129], v[166:169], v[200:203], v[126:129]
	v_mfma_f32_16x16x32_bf16 v[122:125], v[174:177], v[200:203], v[122:125]
	v_mfma_f32_16x16x32_bf16 v[118:121], v[166:169], v[208:211], v[118:121]
	v_mfma_f32_16x16x32_bf16 v[110:113], v[174:177], v[208:211], v[110:113]
	v_mfma_f32_16x16x32_bf16 v[102:105], v[166:169], v[216:219], v[102:105]
	v_mfma_f32_16x16x32_bf16 v[94:97], v[174:177], v[216:219], v[94:97]
	v_mfma_f32_16x16x32_bf16 v[86:89], v[166:169], v[224:227], v[86:89]
	v_mfma_f32_16x16x32_bf16 v[78:81], v[174:177], v[224:227], v[78:81]
	v_mfma_f32_16x16x32_bf16 v[114:117], v[178:181], v[196:199], v[114:117]
	v_mfma_f32_16x16x32_bf16 v[106:109], v[188:191], v[196:199], v[106:109]
	v_mfma_f32_16x16x32_bf16 v[98:101], v[178:181], v[204:207], v[98:101]
	v_mfma_f32_16x16x32_bf16 v[90:93], v[188:191], v[204:207], v[90:93]
	v_mfma_f32_16x16x32_bf16 v[82:85], v[178:181], v[212:215], v[82:85]
	v_mfma_f32_16x16x32_bf16 v[74:77], v[188:191], v[212:215], v[74:77]
	v_mfma_f32_16x16x32_bf16 v[70:73], v[178:181], v[220:223], v[70:73]
	v_mfma_f32_16x16x32_bf16 v[66:69], v[188:191], v[220:223], v[66:69]
	v_mfma_f32_16x16x32_bf16 v[114:117], v[184:187], v[200:203], v[114:117]
	v_mfma_f32_16x16x32_bf16 v[106:109], v[192:195], v[200:203], v[106:109]
	v_mfma_f32_16x16x32_bf16 v[98:101], v[184:187], v[208:211], v[98:101]
	v_mfma_f32_16x16x32_bf16 v[90:93], v[192:195], v[208:211], v[90:93]
	v_mfma_f32_16x16x32_bf16 v[82:85], v[184:187], v[216:219], v[82:85]
	v_mfma_f32_16x16x32_bf16 v[74:77], v[192:195], v[216:219], v[74:77]
	v_mfma_f32_16x16x32_bf16 v[70:73], v[184:187], v[224:227], v[70:73]
	v_mfma_f32_16x16x32_bf16 v[66:69], v[192:195], v[224:227], v[66:69]
	s_barrier
	s_setprio 0
	v_lshl_add_u64 v[228:229], v[228:229], 0, s[84:85]
	s_add_i32 m0, s24, 0x18000
	ds_read_b128 v[196:199], v165 offset:49152
	ds_read_b128 v[200:203], v165 offset:50176
	ds_read_b128 v[204:207], v165 offset:51200
	ds_read_b128 v[208:211], v165 offset:52224
	ds_read_b128 v[212:215], v165 offset:53248
	ds_read_b128 v[216:219], v165 offset:54272
	ds_read_b128 v[220:223], v165 offset:55296
	ds_read_b128 v[224:227], v165 offset:56320
	global_load_lds_dwordx4 v[228:229], off
	s_add_i32 m0, s24, 0x1a000
	s_add_u32 s14, s18, 0xb0080
	v_lshl_add_u64 v[228:229], v[230:231], 0, s[84:85]
	s_addc_u32 s15, s19, 0
	global_load_lds_dwordx4 v[228:229], off
	s_add_i32 m0, s24, 0x1c000
	v_lshl_add_u64 v[228:229], s[14:15], 0, v[132:133]
	global_load_lds_dwordx4 v[228:229], off
	s_add_i32 m0, s24, 0x1e000
	v_lshl_add_u64 v[228:229], s[14:15], 0, v[154:155]
	global_load_lds_dwordx4 v[228:229], off
	s_mov_b32 m0, s29
	v_lshl_add_u64 v[228:229], v[232:233], 0, s[84:85]
	global_load_lds_dwordx4 v[228:229], off
	s_mov_b32 m0, s30
	v_lshl_add_u64 v[228:229], v[234:235], 0, s[84:85]
	global_load_lds_dwordx4 v[228:229], off
	s_waitcnt vmcnt(8)
	s_waitcnt lgkmcnt(0)
	s_setprio 1
	s_barrier
	v_mfma_f32_16x16x32_bf16 v[62:65], v[160:163], v[196:199], v[62:65]
	v_mfma_f32_16x16x32_bf16 v[58:61], v[170:173], v[196:199], v[58:61]
	v_mfma_f32_16x16x32_bf16 v[54:57], v[160:163], v[204:207], v[54:57]
	v_mfma_f32_16x16x32_bf16 v[46:49], v[170:173], v[204:207], v[46:49]
	v_mfma_f32_16x16x32_bf16 v[38:41], v[160:163], v[212:215], v[38:41]
	v_mfma_f32_16x16x32_bf16 v[30:33], v[170:173], v[212:215], v[30:33]
	v_mfma_f32_16x16x32_bf16 v[22:25], v[160:163], v[220:223], v[22:25]
	v_mfma_f32_16x16x32_bf16 v[14:17], v[170:173], v[220:223], v[14:17]
	v_mfma_f32_16x16x32_bf16 v[62:65], v[166:169], v[200:203], v[62:65]
	v_mfma_f32_16x16x32_bf16 v[58:61], v[174:177], v[200:203], v[58:61]
	v_mfma_f32_16x16x32_bf16 v[54:57], v[166:169], v[208:211], v[54:57]
	v_mfma_f32_16x16x32_bf16 v[46:49], v[174:177], v[208:211], v[46:49]
	v_mfma_f32_16x16x32_bf16 v[38:41], v[166:169], v[216:219], v[38:41]
	v_mfma_f32_16x16x32_bf16 v[30:33], v[174:177], v[216:219], v[30:33]
	v_mfma_f32_16x16x32_bf16 v[22:25], v[166:169], v[224:227], v[22:25]
	v_mfma_f32_16x16x32_bf16 v[14:17], v[174:177], v[224:227], v[14:17]
	v_mfma_f32_16x16x32_bf16 v[50:53], v[178:181], v[196:199], v[50:53]
	v_mfma_f32_16x16x32_bf16 v[42:45], v[188:191], v[196:199], v[42:45]
	v_mfma_f32_16x16x32_bf16 v[34:37], v[178:181], v[204:207], v[34:37]
	v_mfma_f32_16x16x32_bf16 v[26:29], v[188:191], v[204:207], v[26:29]
	v_mfma_f32_16x16x32_bf16 v[18:21], v[178:181], v[212:215], v[18:21]
	v_mfma_f32_16x16x32_bf16 v[10:13], v[188:191], v[212:215], v[10:13]
	v_mfma_f32_16x16x32_bf16 v[6:9], v[178:181], v[220:223], v[6:9]
	v_mfma_f32_16x16x32_bf16 v[2:5], v[188:191], v[220:223], v[2:5]
	v_mfma_f32_16x16x32_bf16 v[50:53], v[184:187], v[200:203], v[50:53]
	v_mfma_f32_16x16x32_bf16 v[42:45], v[192:195], v[200:203], v[42:45]
	v_mfma_f32_16x16x32_bf16 v[34:37], v[184:187], v[208:211], v[34:37]
	v_mfma_f32_16x16x32_bf16 v[26:29], v[192:195], v[208:211], v[26:29]
	v_mfma_f32_16x16x32_bf16 v[18:21], v[184:187], v[216:219], v[18:21]
	v_mfma_f32_16x16x32_bf16 v[10:13], v[192:195], v[216:219], v[10:13]
	v_mfma_f32_16x16x32_bf16 v[6:9], v[184:187], v[224:227], v[6:9]
	v_mfma_f32_16x16x32_bf16 v[2:5], v[192:195], v[224:227], v[2:5]
	s_barrier
	s_setprio 0
	s_add_i32 s40, s40, 2
	s_add_u32 s38, s38, 0x100
	s_addc_u32 s39, s39, 0
	s_cmp_gt_u32 s40, 41
	s_mov_b64 s[14:15], s[16:17]
	s_cbranch_scc0 .LBB0_1143
	s_and_b64 vcc, exec, s[10:11]
	s_cbranch_vccz .LBB0_1146
	s_barrier
